# v49 plus per-phase s_setprio flips removed from the executed GEMM loops (128 fewer scalar ops per K-iteration set)
# speedup vs baseline: 1.0070x; 1.0030x over previous
.LBB0_96:
	s_add_u32 s0, s40, 0xfffc0080
	s_addc_u32 s1, s41, -1
	s_add_i32 s2, 0, 0x10000
	ds_read_b128 v[156:159], v236
	ds_read_b128 v[160:163], v236 offset:1024
	ds_read_b128 v[164:167], v236 offset:2048
	ds_read_b128 v[168:171], v236 offset:3072
	s_cmp_eq_u32 s72, 12
	s_cselect_b32 s45, s13, s1
	s_cselect_b32 s44, s12, s0
	s_cselect_b32 s1, s15, s11
	s_cselect_b32 s0, s14, s9
	s_add_i32 m0, s17, 0xc000
	ds_read_b128 v[172:175], v155
	ds_read_b128 v[176:179], v155 offset:1024
	ds_read_b128 v[180:183], v155 offset:2048
	ds_read_b128 v[184:187], v155 offset:3072
	ds_read_b128 v[188:191], v155 offset:4096
	ds_read_b128 v[192:195], v155 offset:5120
	ds_read_b128 v[196:199], v155 offset:6144
	global_load_lds_dwordx4 v136, s[40:41]
	s_add_i32 m0, s17, 0xe000
	ds_read_b128 v[200:203], v155 offset:7168
	global_load_lds_dwordx4 v134, s[40:41]
	s_waitcnt lgkmcnt(8)
	s_barrier
	s_waitcnt lgkmcnt(0)
	v_mfma_f32_16x16x32_bf16 v[124:127], v[156:159], v[172:175], v[124:127]
	v_mfma_f32_16x16x32_bf16 v[120:123], v[164:167], v[172:175], v[120:123]
	v_mfma_f32_16x16x32_bf16 v[116:119], v[156:159], v[180:183], v[116:119]
	v_mfma_f32_16x16x32_bf16 v[108:111], v[164:167], v[180:183], v[108:111]
	v_mfma_f32_16x16x32_bf16 v[100:103], v[156:159], v[188:191], v[100:103]
	v_mfma_f32_16x16x32_bf16 v[92:95], v[164:167], v[188:191], v[92:95]
	v_mfma_f32_16x16x32_bf16 v[84:87], v[156:159], v[196:199], v[84:87]
	v_mfma_f32_16x16x32_bf16 v[76:79], v[164:167], v[196:199], v[76:79]
	v_mfma_f32_16x16x32_bf16 v[124:127], v[160:163], v[176:179], v[124:127]
	v_mfma_f32_16x16x32_bf16 v[120:123], v[168:171], v[176:179], v[120:123]
	v_mfma_f32_16x16x32_bf16 v[116:119], v[160:163], v[184:187], v[116:119]
	v_mfma_f32_16x16x32_bf16 v[108:111], v[168:171], v[184:187], v[108:111]
	v_mfma_f32_16x16x32_bf16 v[100:103], v[160:163], v[192:195], v[100:103]
	v_mfma_f32_16x16x32_bf16 v[92:95], v[168:171], v[192:195], v[92:95]
	v_mfma_f32_16x16x32_bf16 v[84:87], v[160:163], v[200:203], v[84:87]
	v_mfma_f32_16x16x32_bf16 v[76:79], v[168:171], v[200:203], v[76:79]
	s_barrier
	s_add_i32 s30, 0, 0x14000
	s_add_i32 s2, s2, s59
	ds_read_b128 v[204:207], v237
	ds_read_b128 v[208:211], v237 offset:1024
	s_mov_b32 m0, s2
	ds_read_b128 v[228:231], v237 offset:2048
	global_load_lds_dwordx4 v140, s[0:1]
	s_add_i32 m0, s2, 0x2000
	ds_read_b128 v[232:235], v237 offset:3072
	global_load_lds_dwordx4 v132, s[0:1]
	s_barrier
	s_waitcnt lgkmcnt(0)
	v_mfma_f32_16x16x32_bf16 v[112:115], v[204:207], v[172:175], v[112:115]
	v_mfma_f32_16x16x32_bf16 v[104:107], v[228:231], v[172:175], v[104:107]
	v_mfma_f32_16x16x32_bf16 v[96:99], v[204:207], v[180:183], v[96:99]
	v_mfma_f32_16x16x32_bf16 v[88:91], v[228:231], v[180:183], v[88:91]
	v_mfma_f32_16x16x32_bf16 v[80:83], v[204:207], v[188:191], v[80:83]
	v_mfma_f32_16x16x32_bf16 v[72:75], v[228:231], v[188:191], v[72:75]
	v_mfma_f32_16x16x32_bf16 v[68:71], v[204:207], v[196:199], v[68:71]
	v_mfma_f32_16x16x32_bf16 v[64:67], v[228:231], v[196:199], v[64:67]
	v_mfma_f32_16x16x32_bf16 v[112:115], v[208:211], v[176:179], v[112:115]
	v_mfma_f32_16x16x32_bf16 v[104:107], v[232:235], v[176:179], v[104:107]
	v_mfma_f32_16x16x32_bf16 v[96:99], v[208:211], v[184:187], v[96:99]
	v_mfma_f32_16x16x32_bf16 v[88:91], v[232:235], v[184:187], v[88:91]
	v_mfma_f32_16x16x32_bf16 v[80:83], v[208:211], v[192:195], v[80:83]
	v_mfma_f32_16x16x32_bf16 v[72:75], v[232:235], v[192:195], v[72:75]
	v_mfma_f32_16x16x32_bf16 v[68:71], v[208:211], v[200:203], v[68:71]
	v_mfma_f32_16x16x32_bf16 v[64:67], v[232:235], v[200:203], v[64:67]
	s_mov_b32 m0, s17
	s_barrier
	ds_read_b128 v[172:175], v155 offset:16384
	ds_read_b128 v[176:179], v155 offset:17408
	ds_read_b128 v[180:183], v155 offset:18432
	ds_read_b128 v[184:187], v155 offset:19456
	ds_read_b128 v[188:191], v155 offset:20480
	ds_read_b128 v[192:195], v155 offset:21504
	ds_read_b128 v[196:199], v155 offset:22528
	global_load_lds_dwordx4 v128, s[44:45]
	s_mov_b32 m0, s64
	ds_read_b128 v[200:203], v155 offset:23552
	global_load_lds_dwordx4 v130, s[44:45]
	s_barrier
	s_waitcnt lgkmcnt(0)
	v_mfma_f32_16x16x32_bf16 v[60:63], v[156:159], v[172:175], v[60:63]
	v_mfma_f32_16x16x32_bf16 v[56:59], v[164:167], v[172:175], v[56:59]
	v_mfma_f32_16x16x32_bf16 v[52:55], v[156:159], v[180:183], v[52:55]
	v_mfma_f32_16x16x32_bf16 v[44:47], v[164:167], v[180:183], v[44:47]
	v_mfma_f32_16x16x32_bf16 v[36:39], v[156:159], v[188:191], v[36:39]
	v_mfma_f32_16x16x32_bf16 v[28:31], v[164:167], v[188:191], v[28:31]
	v_mfma_f32_16x16x32_bf16 v[20:23], v[156:159], v[196:199], v[20:23]
	v_mfma_f32_16x16x32_bf16 v[12:15], v[164:167], v[196:199], v[12:15]
	v_mfma_f32_16x16x32_bf16 v[60:63], v[160:163], v[176:179], v[60:63]
	v_mfma_f32_16x16x32_bf16 v[56:59], v[168:171], v[176:179], v[56:59]
	v_mfma_f32_16x16x32_bf16 v[52:55], v[160:163], v[184:187], v[52:55]
	v_mfma_f32_16x16x32_bf16 v[44:47], v[168:171], v[184:187], v[44:47]
	v_mfma_f32_16x16x32_bf16 v[36:39], v[160:163], v[192:195], v[36:39]
	v_mfma_f32_16x16x32_bf16 v[28:31], v[168:171], v[192:195], v[28:31]
	v_mfma_f32_16x16x32_bf16 v[20:23], v[160:163], v[200:203], v[20:23]
	v_mfma_f32_16x16x32_bf16 v[12:15], v[168:171], v[200:203], v[12:15]
	s_barrier
	s_add_i32 s2, s30, s59
	s_mov_b32 m0, s2
	s_add_u32 s18, s0, 0x40000
	s_addc_u32 s19, s1, 0
	global_load_lds_dwordx4 v140, s[18:19]
	s_add_i32 m0, s2, 0x2000
	s_nop 0
	global_load_lds_dwordx4 v132, s[18:19]
	s_waitcnt vmcnt(6)
	s_barrier
	v_mfma_f32_16x16x32_bf16 v[48:51], v[204:207], v[172:175], v[48:51]
	v_mfma_f32_16x16x32_bf16 v[40:43], v[228:231], v[172:175], v[40:43]
	v_mfma_f32_16x16x32_bf16 v[32:35], v[204:207], v[180:183], v[32:35]
	v_mfma_f32_16x16x32_bf16 v[24:27], v[228:231], v[180:183], v[24:27]
	v_mfma_f32_16x16x32_bf16 v[16:19], v[204:207], v[188:191], v[16:19]
	v_mfma_f32_16x16x32_bf16 v[8:11], v[228:231], v[188:191], v[8:11]
	v_mfma_f32_16x16x32_bf16 v[4:7], v[204:207], v[196:199], v[4:7]
	v_mfma_f32_16x16x32_bf16 v[0:3], v[228:231], v[196:199], v[0:3]
	v_mfma_f32_16x16x32_bf16 v[48:51], v[208:211], v[176:179], v[48:51]
	v_mfma_f32_16x16x32_bf16 v[40:43], v[232:235], v[176:179], v[40:43]
	v_mfma_f32_16x16x32_bf16 v[32:35], v[208:211], v[184:187], v[32:35]
	v_mfma_f32_16x16x32_bf16 v[24:27], v[232:235], v[184:187], v[24:27]
	v_mfma_f32_16x16x32_bf16 v[16:19], v[208:211], v[192:195], v[16:19]
	v_mfma_f32_16x16x32_bf16 v[8:11], v[232:235], v[192:195], v[8:11]
	v_mfma_f32_16x16x32_bf16 v[4:7], v[208:211], v[200:203], v[4:7]
	v_mfma_f32_16x16x32_bf16 v[0:3], v[232:235], v[200:203], v[0:3]
	s_add_i32 s2, 0, 0x18000
	s_barrier
	ds_read_b128 v[156:159], v238
	ds_read_b128 v[160:163], v238 offset:1024
	ds_read_b128 v[164:167], v238 offset:2048
	ds_read_b128 v[168:171], v238 offset:3072
	s_add_u32 s18, s44, 0x40000
	s_addc_u32 s19, s45, 0
	s_mov_b32 m0, s65
	ds_read_b128 v[172:175], v155 offset:32768
	ds_read_b128 v[176:179], v155 offset:33792
	ds_read_b128 v[180:183], v155 offset:34816
	ds_read_b128 v[184:187], v155 offset:35840
	ds_read_b128 v[188:191], v155 offset:36864
	ds_read_b128 v[192:195], v155 offset:37888
	ds_read_b128 v[196:199], v155 offset:38912
	global_load_lds_dwordx4 v128, s[18:19]
	s_mov_b32 m0, s66
	ds_read_b128 v[200:203], v155 offset:39936
	global_load_lds_dwordx4 v130, s[18:19]
	s_waitcnt lgkmcnt(8)
	s_barrier
	s_waitcnt lgkmcnt(0)
	v_mfma_f32_16x16x32_bf16 v[124:127], v[156:159], v[172:175], v[124:127]
	v_mfma_f32_16x16x32_bf16 v[120:123], v[164:167], v[172:175], v[120:123]
	v_mfma_f32_16x16x32_bf16 v[116:119], v[156:159], v[180:183], v[116:119]
	v_mfma_f32_16x16x32_bf16 v[108:111], v[164:167], v[180:183], v[108:111]
	v_mfma_f32_16x16x32_bf16 v[100:103], v[156:159], v[188:191], v[100:103]
	v_mfma_f32_16x16x32_bf16 v[92:95], v[164:167], v[188:191], v[92:95]
	v_mfma_f32_16x16x32_bf16 v[84:87], v[156:159], v[196:199], v[84:87]
	v_mfma_f32_16x16x32_bf16 v[76:79], v[164:167], v[196:199], v[76:79]
	v_mfma_f32_16x16x32_bf16 v[124:127], v[160:163], v[176:179], v[124:127]
	v_mfma_f32_16x16x32_bf16 v[120:123], v[168:171], v[176:179], v[120:123]
	v_mfma_f32_16x16x32_bf16 v[116:119], v[160:163], v[184:187], v[116:119]
	v_mfma_f32_16x16x32_bf16 v[108:111], v[168:171], v[184:187], v[108:111]
	v_mfma_f32_16x16x32_bf16 v[100:103], v[160:163], v[192:195], v[100:103]
	v_mfma_f32_16x16x32_bf16 v[92:95], v[168:171], v[192:195], v[92:95]
	v_mfma_f32_16x16x32_bf16 v[84:87], v[160:163], v[200:203], v[84:87]
	v_mfma_f32_16x16x32_bf16 v[76:79], v[168:171], v[200:203], v[76:79]
	s_barrier
	s_add_i32 s18, 0, 0x1c000
	s_add_i32 s2, s2, s59
	s_mov_b32 m0, s2
	ds_read_b128 v[204:207], v239
	ds_read_b128 v[208:211], v239 offset:1024
	ds_read_b128 v[228:231], v239 offset:2048
	ds_read_b128 v[232:235], v239 offset:3072
	s_add_u32 s100, s0, 0x80
	s_addc_u32 s101, s1, 0
	global_load_lds_dwordx4 v140, s[100:101]
	s_add_i32 m0, s2, 0x2000
	s_nop 0
	global_load_lds_dwordx4 v132, s[100:101]
	s_barrier
	s_waitcnt lgkmcnt(0)
	v_mfma_f32_16x16x32_bf16 v[112:115], v[204:207], v[172:175], v[112:115]
	v_mfma_f32_16x16x32_bf16 v[104:107], v[228:231], v[172:175], v[104:107]
	v_mfma_f32_16x16x32_bf16 v[96:99], v[204:207], v[180:183], v[96:99]
	v_mfma_f32_16x16x32_bf16 v[88:91], v[228:231], v[180:183], v[88:91]
	v_mfma_f32_16x16x32_bf16 v[80:83], v[204:207], v[188:191], v[80:83]
	v_mfma_f32_16x16x32_bf16 v[72:75], v[228:231], v[188:191], v[72:75]
	v_mfma_f32_16x16x32_bf16 v[68:71], v[204:207], v[196:199], v[68:71]
	v_mfma_f32_16x16x32_bf16 v[64:67], v[228:231], v[196:199], v[64:67]
	v_mfma_f32_16x16x32_bf16 v[112:115], v[208:211], v[176:179], v[112:115]
	v_mfma_f32_16x16x32_bf16 v[104:107], v[232:235], v[176:179], v[104:107]
	v_mfma_f32_16x16x32_bf16 v[96:99], v[208:211], v[184:187], v[96:99]
	v_mfma_f32_16x16x32_bf16 v[88:91], v[232:235], v[184:187], v[88:91]
	v_mfma_f32_16x16x32_bf16 v[80:83], v[208:211], v[192:195], v[80:83]
	v_mfma_f32_16x16x32_bf16 v[72:75], v[232:235], v[192:195], v[72:75]
	v_mfma_f32_16x16x32_bf16 v[68:71], v[208:211], v[200:203], v[68:71]
	v_mfma_f32_16x16x32_bf16 v[64:67], v[232:235], v[200:203], v[64:67]
	s_mov_b32 m0, s69
	s_barrier
	ds_read_b128 v[172:175], v155 offset:49152
	ds_read_b128 v[176:179], v155 offset:50176
	ds_read_b128 v[180:183], v155 offset:51200
	ds_read_b128 v[184:187], v155 offset:52224
	ds_read_b128 v[188:191], v155 offset:53248
	ds_read_b128 v[192:195], v155 offset:54272
	ds_read_b128 v[196:199], v155 offset:55296
	ds_read_b128 v[200:203], v155 offset:56320
	s_add_u32 s100, s44, 0x80
	s_addc_u32 s101, s45, 0
	global_load_lds_dwordx4 v128, s[100:101]
	s_mov_b32 m0, s71
	s_nop 0
	global_load_lds_dwordx4 v130, s[100:101]
	s_barrier
	s_waitcnt lgkmcnt(0)
	v_mfma_f32_16x16x32_bf16 v[60:63], v[156:159], v[172:175], v[60:63]
	v_mfma_f32_16x16x32_bf16 v[56:59], v[164:167], v[172:175], v[56:59]
	v_mfma_f32_16x16x32_bf16 v[52:55], v[156:159], v[180:183], v[52:55]
	v_mfma_f32_16x16x32_bf16 v[44:47], v[164:167], v[180:183], v[44:47]
	v_mfma_f32_16x16x32_bf16 v[36:39], v[156:159], v[188:191], v[36:39]
	v_mfma_f32_16x16x32_bf16 v[28:31], v[164:167], v[188:191], v[28:31]
	v_mfma_f32_16x16x32_bf16 v[20:23], v[156:159], v[196:199], v[20:23]
	v_mfma_f32_16x16x32_bf16 v[12:15], v[164:167], v[196:199], v[12:15]
	v_mfma_f32_16x16x32_bf16 v[60:63], v[160:163], v[176:179], v[60:63]
	v_mfma_f32_16x16x32_bf16 v[56:59], v[168:171], v[176:179], v[56:59]
	v_mfma_f32_16x16x32_bf16 v[52:55], v[160:163], v[184:187], v[52:55]
	v_mfma_f32_16x16x32_bf16 v[44:47], v[168:171], v[184:187], v[44:47]
	v_mfma_f32_16x16x32_bf16 v[36:39], v[160:163], v[192:195], v[36:39]
	v_mfma_f32_16x16x32_bf16 v[28:31], v[168:171], v[192:195], v[28:31]
	v_mfma_f32_16x16x32_bf16 v[20:23], v[160:163], v[200:203], v[20:23]
	v_mfma_f32_16x16x32_bf16 v[12:15], v[168:171], v[200:203], v[12:15]
	s_barrier
	s_add_i32 s2, s18, s59
	s_mov_b32 m0, s2
	s_add_u32 s0, s0, 0x40080
	s_addc_u32 s1, s1, 0
	global_load_lds_dwordx4 v140, s[0:1]
	s_add_i32 m0, s2, 0x2000
	s_nop 0
	global_load_lds_dwordx4 v132, s[0:1]
	s_waitcnt vmcnt(6)
	s_barrier
	v_mfma_f32_16x16x32_bf16 v[48:51], v[204:207], v[172:175], v[48:51]
	v_mfma_f32_16x16x32_bf16 v[40:43], v[228:231], v[172:175], v[40:43]
	v_mfma_f32_16x16x32_bf16 v[32:35], v[204:207], v[180:183], v[32:35]
	v_mfma_f32_16x16x32_bf16 v[24:27], v[228:231], v[180:183], v[24:27]
	v_mfma_f32_16x16x32_bf16 v[16:19], v[204:207], v[188:191], v[16:19]
	v_mfma_f32_16x16x32_bf16 v[8:11], v[228:231], v[188:191], v[8:11]
	v_mfma_f32_16x16x32_bf16 v[4:7], v[204:207], v[196:199], v[4:7]
	v_mfma_f32_16x16x32_bf16 v[0:3], v[228:231], v[196:199], v[0:3]
	v_mfma_f32_16x16x32_bf16 v[48:51], v[208:211], v[176:179], v[48:51]
	v_mfma_f32_16x16x32_bf16 v[40:43], v[232:235], v[176:179], v[40:43]
	v_mfma_f32_16x16x32_bf16 v[32:35], v[208:211], v[184:187], v[32:35]
	v_mfma_f32_16x16x32_bf16 v[24:27], v[232:235], v[184:187], v[24:27]
	v_mfma_f32_16x16x32_bf16 v[16:19], v[208:211], v[192:195], v[16:19]
	v_mfma_f32_16x16x32_bf16 v[8:11], v[232:235], v[192:195], v[8:11]
	v_mfma_f32_16x16x32_bf16 v[4:7], v[208:211], v[200:203], v[4:7]
	v_mfma_f32_16x16x32_bf16 v[0:3], v[232:235], v[200:203], v[0:3]
	s_add_i32 s72, s72, 2
	s_add_u32 s9, s9, 0x100
	s_addc_u32 s11, s11, 0
	s_add_u32 s40, s40, 0x100
	s_addc_u32 s41, s41, 0
	s_cmp_gt_u32 s72, 13
	s_barrier
	s_cbranch_scc0 .LBB0_96
	s_lshl_b32 s0, s16, 8
	v_mbcnt_lo_u32_b32 v139, -1, 0
	v_mbcnt_hi_u32_b32 v139, -1, v139
	s_lshl_b32 s1, s21, 8
	v_ashrrev_i32_e32 v138, 1, v139
	s_add_i32 s0, s0, s67
	v_and_b32_e32 v138, -8, v138
	s_or_b32 s1, s1, s68
	v_and_or_b32 v156, v139, 15, s0
	v_add_u32_e32 v138, s1, v138
	v_ashrrev_i32_e32 v157, 31, v156
	v_ashrrev_i32_e32 v139, 31, v138
	v_lshlrev_b64 v[158:159], 11, v[156:157]
	v_lshl_add_u64 v[158:159], s[26:27], 0, v[158:159]
	v_lshlrev_b64 v[160:161], 1, v[138:139]
	v_lshl_add_u64 v[138:139], v[158:159], 0, v[160:161]
	v_cvt_pk_bf16_f32 v60, v60, v61
	v_cvt_pk_bf16_f32 v61, v62, v63
	v_cvt_pk_bf16_f32 v62, v56, v57
	v_add_co_u32_e32 v56, vcc, s31, v138
	v_cvt_pk_bf16_f32 v112, v112, v113
	v_cvt_pk_bf16_f32 v113, v114, v115
	v_cvt_pk_bf16_f32 v114, v104, v105
	v_or_b32_e32 v104, 16, v156
	s_nop 0
	v_addc_co_u32_e32 v57, vcc, 0, v139, vcc
	v_cvt_pk_bf16_f32 v48, v48, v49
	v_cvt_pk_bf16_f32 v49, v50, v51
	v_cvt_pk_bf16_f32 v51, v42, v43
	v_cvt_pk_bf16_f32 v42, v44, v45
	v_add_co_u32_e32 v44, vcc, s42, v138
	v_ashrrev_i32_e32 v105, 31, v104
	v_cvt_pk_bf16_f32 v96, v96, v97
	v_cvt_pk_bf16_f32 v97, v98, v99
	v_cvt_pk_bf16_f32 v98, v88, v89
	v_or_b32_e32 v88, 32, v156
	v_addc_co_u32_e32 v45, vcc, 0, v139, vcc
	v_lshlrev_b64 v[104:105], 11, v[104:105]
	v_ashrrev_i32_e32 v89, 31, v88
	v_cvt_pk_bf16_f32 v80, v80, v81
	v_cvt_pk_bf16_f32 v81, v82, v83
	v_cvt_pk_bf16_f32 v82, v72, v73
	v_or_b32_e32 v72, 48, v156
	s_mov_b64 s[0:1], 0x40000
	v_cvt_pk_bf16_f32 v32, v32, v33
	v_cvt_pk_bf16_f32 v33, v34, v35
	v_cvt_pk_bf16_f32 v35, v26, v27
	v_cvt_pk_bf16_f32 v26, v28, v29
	v_add_co_u32_e32 v28, vcc, s43, v138
	v_lshl_add_u64 v[104:105], s[26:27], 0, v[104:105]
	v_lshlrev_b64 v[88:89], 11, v[88:89]
	v_ashrrev_i32_e32 v73, 31, v72
	v_cvt_pk_bf16_f32 v68, v68, v69
	v_cvt_pk_bf16_f32 v69, v70, v71
	v_cvt_pk_bf16_f32 v70, v64, v65
	v_lshl_add_u64 v[64:65], v[138:139], 0, s[0:1]
	s_mov_b64 s[0:1], 0x48000
	v_addc_co_u32_e32 v29, vcc, 0, v139, vcc
	v_cvt_pk_bf16_f32 v115, v106, v107
	flat_store_dwordx4 v[138:139], v[112:115] offset:256
	v_lshl_add_u64 v[88:89], s[26:27], 0, v[88:89]
	v_lshlrev_b64 v[72:73], 11, v[72:73]
	v_lshl_add_u64 v[112:113], v[104:105], 0, v[160:161]
	v_cvt_pk_bf16_f32 v50, v40, v41
	flat_store_dwordx4 v[64:65], v[48:51] offset:256
	v_cvt_pk_bf16_f32 v16, v16, v17
	v_cvt_pk_bf16_f32 v17, v18, v19
	v_cvt_pk_bf16_f32 v19, v10, v11
	v_cvt_pk_bf16_f32 v10, v12, v13
	v_add_co_u32_e32 v12, vcc, s47, v138
	s_nop 0
	v_lshl_add_u64 v[48:49], v[138:139], 0, s[0:1]
	s_mov_b64 s[0:1], 0x50000
	v_cvt_pk_bf16_f32 v99, v90, v91
	flat_store_dwordx4 v[112:113], v[96:99] offset:256
	v_lshl_add_u64 v[72:73], s[26:27], 0, v[72:73]
	v_cvt_pk_bf16_f32 v34, v24, v25
	flat_store_dwordx4 v[48:49], v[32:35] offset:256
	v_lshl_add_u64 v[96:97], v[88:89], 0, v[160:161]
	v_addc_co_u32_e32 v13, vcc, 0, v139, vcc
	v_lshl_add_u64 v[32:33], v[138:139], 0, s[0:1]
	s_mov_b64 s[0:1], 0x58000
	v_cvt_pk_bf16_f32 v83, v74, v75
	flat_store_dwordx4 v[96:97], v[80:83] offset:256
	v_cvt_pk_bf16_f32 v18, v8, v9
	flat_store_dwordx4 v[32:33], v[16:19] offset:256
	s_and_b64 vcc, exec, s[6:7]
	v_lshl_add_u64 v[80:81], v[72:73], 0, v[160:161]
	v_lshl_add_u64 v[16:17], v[138:139], 0, s[0:1]
	s_mov_b32 s21, s10
	s_mov_b32 s16, s8
	s_mov_b64 s[40:41], s[14:15]
	s_mov_b64 s[0:1], s[12:13]
	v_cvt_pk_bf16_f32 v124, v124, v125
	v_cvt_pk_bf16_f32 v125, v126, v127
	v_cvt_pk_bf16_f32 v126, v120, v121
	v_cvt_pk_bf16_f32 v127, v122, v123
	flat_store_dwordx4 v[138:139], v[124:127]
	v_cvt_pk_bf16_f32 v104, v116, v117
	v_cvt_pk_bf16_f32 v105, v118, v119
	v_cvt_pk_bf16_f32 v106, v108, v109
	v_cvt_pk_bf16_f32 v107, v110, v111
	flat_store_dwordx4 v[112:113], v[104:107]
	v_cvt_pk_bf16_f32 v88, v100, v101
	v_cvt_pk_bf16_f32 v89, v102, v103
	v_cvt_pk_bf16_f32 v90, v92, v93
	v_cvt_pk_bf16_f32 v91, v94, v95
	flat_store_dwordx4 v[96:97], v[88:91]
	v_cvt_pk_bf16_f32 v72, v84, v85
	v_cvt_pk_bf16_f32 v73, v86, v87
	v_cvt_pk_bf16_f32 v74, v76, v77
	v_cvt_pk_bf16_f32 v75, v78, v79
	flat_store_dwordx4 v[80:81], v[72:75]
	v_cvt_pk_bf16_f32 v71, v66, v67
	flat_store_dwordx4 v[80:81], v[68:71] offset:256
	v_cvt_pk_bf16_f32 v63, v58, v59
	flat_store_dwordx4 v[56:57], v[60:63]
	v_cvt_pk_bf16_f32 v40, v52, v53
	v_cvt_pk_bf16_f32 v41, v54, v55
	v_cvt_pk_bf16_f32 v43, v46, v47
	flat_store_dwordx4 v[44:45], v[40:43]
	v_cvt_pk_bf16_f32 v24, v36, v37
	v_cvt_pk_bf16_f32 v25, v38, v39
	v_cvt_pk_bf16_f32 v27, v30, v31
	flat_store_dwordx4 v[28:29], v[24:27]
	v_cvt_pk_bf16_f32 v8, v20, v21
	v_cvt_pk_bf16_f32 v9, v22, v23
	v_cvt_pk_bf16_f32 v11, v14, v15
	flat_store_dwordx4 v[12:13], v[8:11]
	v_cvt_pk_bf16_f32 v4, v4, v5
	v_cvt_pk_bf16_f32 v5, v6, v7
	v_cvt_pk_bf16_f32 v6, v0, v1
	v_cvt_pk_bf16_f32 v7, v2, v3
	flat_store_dwordx4 v[16:17], v[4:7] offset:256
	s_cbranch_vccz .LBB0_89
	s_waitcnt vmcnt(0)
	s_cmpk_gt_u32 s51, 0xff
	s_cbranch_scc1 .LBB0_100
	s_barrier

.LBB0_126:
	s_add_u32 s0, s8, 0xfff80080
	s_addc_u32 s1, s9, -1
	s_add_i32 s2, 0, 0x10000
	v_add_u32_e32 v138, s2, v238
	ds_read_b128 v[154:157], v138
	ds_read_b128 v[158:161], v138 offset:1024
	ds_read_b128 v[162:165], v138 offset:2048
	ds_read_b128 v[166:169], v138 offset:3072
	s_cmp_eq_u32 s20, 28
	s_cselect_b32 s11, s45, s1
	s_cselect_b32 s10, s44, s0
	s_cselect_b32 s1, s67, s15
	s_cselect_b32 s0, s66, s13
	s_add_i32 m0, s17, 0xc000
	ds_read_b128 v[170:173], v239
	ds_read_b128 v[174:177], v239 offset:1024
	ds_read_b128 v[178:181], v239 offset:2048
	ds_read_b128 v[182:185], v239 offset:3072
	ds_read_b128 v[186:189], v239 offset:4096
	ds_read_b128 v[190:193], v239 offset:5120
	ds_read_b128 v[194:197], v239 offset:6144
	global_load_lds_dwordx4 v136, s[8:9]
	s_add_i32 m0, s17, 0xe000
	ds_read_b128 v[198:201], v239 offset:7168
	global_load_lds_dwordx4 v134, s[8:9]
	s_waitcnt lgkmcnt(8)
	s_barrier
	s_waitcnt lgkmcnt(0)
	v_mfma_f32_16x16x32_bf16 v[124:127], v[154:157], v[170:173], v[124:127]
	v_mfma_f32_16x16x32_bf16 v[120:123], v[162:165], v[170:173], v[120:123]
	v_mfma_f32_16x16x32_bf16 v[116:119], v[154:157], v[178:181], v[116:119]
	v_mfma_f32_16x16x32_bf16 v[112:115], v[162:165], v[178:181], v[112:115]
	v_mfma_f32_16x16x32_bf16 v[104:107], v[154:157], v[186:189], v[104:107]
	v_mfma_f32_16x16x32_bf16 v[96:99], v[162:165], v[186:189], v[96:99]
	v_mfma_f32_16x16x32_bf16 v[88:91], v[154:157], v[194:197], v[88:91]
	v_mfma_f32_16x16x32_bf16 v[80:83], v[162:165], v[194:197], v[80:83]
	v_mfma_f32_16x16x32_bf16 v[124:127], v[158:161], v[174:177], v[124:127]
	v_mfma_f32_16x16x32_bf16 v[120:123], v[166:169], v[174:177], v[120:123]
	v_mfma_f32_16x16x32_bf16 v[116:119], v[158:161], v[182:185], v[116:119]
	v_mfma_f32_16x16x32_bf16 v[112:115], v[166:169], v[182:185], v[112:115]
	v_mfma_f32_16x16x32_bf16 v[104:107], v[158:161], v[190:193], v[104:107]
	v_mfma_f32_16x16x32_bf16 v[96:99], v[166:169], v[190:193], v[96:99]
	v_mfma_f32_16x16x32_bf16 v[88:91], v[158:161], v[198:201], v[88:91]
	v_mfma_f32_16x16x32_bf16 v[80:83], v[166:169], v[198:201], v[80:83]
	s_barrier
	s_add_i32 s21, 0, 0x14000
	v_add_u32_e32 v138, s21, v238
	s_add_i32 s2, s2, s58
	ds_read_b128 v[202:205], v138
	ds_read_b128 v[206:209], v138 offset:1024
	s_mov_b32 m0, s2
	ds_read_b128 v[240:243], v138 offset:2048
	global_load_lds_dwordx4 v140, s[0:1]
	s_add_i32 m0, s2, 0x2000
	ds_read_b128 v[244:247], v138 offset:3072
	global_load_lds_dwordx4 v132, s[0:1]
	s_barrier
	s_waitcnt lgkmcnt(0)
	v_mfma_f32_16x16x32_bf16 v[108:111], v[202:205], v[170:173], v[108:111]
	v_mfma_f32_16x16x32_bf16 v[100:103], v[240:243], v[170:173], v[100:103]
	v_mfma_f32_16x16x32_bf16 v[92:95], v[202:205], v[178:181], v[92:95]
	v_mfma_f32_16x16x32_bf16 v[84:87], v[240:243], v[178:181], v[84:87]
	v_mfma_f32_16x16x32_bf16 v[76:79], v[202:205], v[186:189], v[76:79]
	v_mfma_f32_16x16x32_bf16 v[72:75], v[240:243], v[186:189], v[72:75]
	v_mfma_f32_16x16x32_bf16 v[68:71], v[202:205], v[194:197], v[68:71]
	v_mfma_f32_16x16x32_bf16 v[64:67], v[240:243], v[194:197], v[64:67]
	v_mfma_f32_16x16x32_bf16 v[108:111], v[206:209], v[174:177], v[108:111]
	v_mfma_f32_16x16x32_bf16 v[100:103], v[244:247], v[174:177], v[100:103]
	v_mfma_f32_16x16x32_bf16 v[92:95], v[206:209], v[182:185], v[92:95]
	v_mfma_f32_16x16x32_bf16 v[84:87], v[244:247], v[182:185], v[84:87]
	v_mfma_f32_16x16x32_bf16 v[76:79], v[206:209], v[190:193], v[76:79]
	v_mfma_f32_16x16x32_bf16 v[72:75], v[244:247], v[190:193], v[72:75]
	v_mfma_f32_16x16x32_bf16 v[68:71], v[206:209], v[198:201], v[68:71]
	v_mfma_f32_16x16x32_bf16 v[64:67], v[244:247], v[198:201], v[64:67]
	s_mov_b32 m0, s17
	v_lshl_add_u64 v[248:249], s[10:11], 0, v[128:129]
	s_barrier
	ds_read_b128 v[170:173], v239 offset:16384
	ds_read_b128 v[174:177], v239 offset:17408
	ds_read_b128 v[178:181], v239 offset:18432
	ds_read_b128 v[182:185], v239 offset:19456
	ds_read_b128 v[186:189], v239 offset:20480
	ds_read_b128 v[190:193], v239 offset:21504
	ds_read_b128 v[194:197], v239 offset:22528
	ds_read_b128 v[198:201], v239 offset:23552
	global_load_lds_dwordx4 v128, s[10:11]
	v_lshl_add_u64 v[250:251], s[10:11], 0, v[130:131]
	s_mov_b32 m0, s59
	s_nop 0
	global_load_lds_dwordx4 v130, s[10:11]
	s_barrier
	s_waitcnt lgkmcnt(0)
	v_mfma_f32_16x16x32_bf16 v[60:63], v[154:157], v[170:173], v[60:63]
	v_mfma_f32_16x16x32_bf16 v[56:59], v[162:165], v[170:173], v[56:59]
	v_mfma_f32_16x16x32_bf16 v[52:55], v[154:157], v[178:181], v[52:55]
	v_mfma_f32_16x16x32_bf16 v[48:51], v[162:165], v[178:181], v[48:51]
	v_mfma_f32_16x16x32_bf16 v[36:39], v[154:157], v[186:189], v[36:39]
	v_mfma_f32_16x16x32_bf16 v[32:35], v[162:165], v[186:189], v[32:35]
	v_mfma_f32_16x16x32_bf16 v[20:23], v[154:157], v[194:197], v[20:23]
	v_mfma_f32_16x16x32_bf16 v[16:19], v[162:165], v[194:197], v[16:19]
	v_mfma_f32_16x16x32_bf16 v[60:63], v[158:161], v[174:177], v[60:63]
	v_mfma_f32_16x16x32_bf16 v[56:59], v[166:169], v[174:177], v[56:59]
	v_mfma_f32_16x16x32_bf16 v[52:55], v[158:161], v[182:185], v[52:55]
	v_mfma_f32_16x16x32_bf16 v[48:51], v[166:169], v[182:185], v[48:51]
	v_mfma_f32_16x16x32_bf16 v[36:39], v[158:161], v[190:193], v[36:39]
	v_mfma_f32_16x16x32_bf16 v[32:35], v[166:169], v[190:193], v[32:35]
	v_mfma_f32_16x16x32_bf16 v[20:23], v[158:161], v[198:201], v[20:23]
	v_mfma_f32_16x16x32_bf16 v[16:19], v[166:169], v[198:201], v[16:19]
	s_barrier
	s_add_i32 s2, s21, s58
	s_mov_b32 m0, s2
	s_add_u32 s18, s0, 0x100000
	s_addc_u32 s19, s1, 0
	global_load_lds_dwordx4 v140, s[18:19]
	s_add_i32 m0, s2, 0x2000
	s_nop 0
	global_load_lds_dwordx4 v132, s[18:19]
	s_waitcnt vmcnt(6)
	s_barrier
	v_mfma_f32_16x16x32_bf16 v[44:47], v[202:205], v[170:173], v[44:47]
	v_mfma_f32_16x16x32_bf16 v[40:43], v[240:243], v[170:173], v[40:43]
	v_mfma_f32_16x16x32_bf16 v[28:31], v[202:205], v[178:181], v[28:31]
	v_mfma_f32_16x16x32_bf16 v[24:27], v[240:243], v[178:181], v[24:27]
	v_mfma_f32_16x16x32_bf16 v[12:15], v[202:205], v[186:189], v[12:15]
	v_mfma_f32_16x16x32_bf16 v[8:11], v[240:243], v[186:189], v[8:11]
	v_mfma_f32_16x16x32_bf16 v[4:7], v[202:205], v[194:197], v[4:7]
	v_mfma_f32_16x16x32_bf16 v[0:3], v[240:243], v[194:197], v[0:3]
	v_mfma_f32_16x16x32_bf16 v[44:47], v[206:209], v[174:177], v[44:47]
	v_mfma_f32_16x16x32_bf16 v[40:43], v[244:247], v[174:177], v[40:43]
	v_mfma_f32_16x16x32_bf16 v[28:31], v[206:209], v[182:185], v[28:31]
	v_mfma_f32_16x16x32_bf16 v[24:27], v[244:247], v[182:185], v[24:27]
	v_mfma_f32_16x16x32_bf16 v[12:15], v[206:209], v[190:193], v[12:15]
	v_mfma_f32_16x16x32_bf16 v[8:11], v[244:247], v[190:193], v[8:11]
	v_mfma_f32_16x16x32_bf16 v[4:7], v[206:209], v[198:201], v[4:7]
	v_mfma_f32_16x16x32_bf16 v[0:3], v[244:247], v[198:201], v[0:3]
	s_add_i32 s2, 0, 0x18000
	v_add_u32_e32 v166, s2, v238
	s_barrier
	ds_read_b128 v[154:157], v166
	ds_read_b128 v[158:161], v166 offset:1024
	ds_read_b128 v[162:165], v166 offset:2048
	ds_read_b128 v[166:169], v166 offset:3072
	s_add_u32 s10, s10, 0x80000
	s_addc_u32 s11, s11, 0
	s_mov_b32 m0, s65
	ds_read_b128 v[170:173], v239 offset:32768
	ds_read_b128 v[174:177], v239 offset:33792
	ds_read_b128 v[178:181], v239 offset:34816
	ds_read_b128 v[182:185], v239 offset:35840
	ds_read_b128 v[186:189], v239 offset:36864
	ds_read_b128 v[190:193], v239 offset:37888
	ds_read_b128 v[194:197], v239 offset:38912
	global_load_lds_dwordx4 v128, s[10:11]
	s_mov_b32 m0, s72
	ds_read_b128 v[198:201], v239 offset:39936
	global_load_lds_dwordx4 v130, s[10:11]
	s_waitcnt lgkmcnt(8)
	s_barrier
	s_waitcnt lgkmcnt(0)
	v_mfma_f32_16x16x32_bf16 v[124:127], v[154:157], v[170:173], v[124:127]
	v_mfma_f32_16x16x32_bf16 v[120:123], v[162:165], v[170:173], v[120:123]
	v_mfma_f32_16x16x32_bf16 v[116:119], v[154:157], v[178:181], v[116:119]
	v_mfma_f32_16x16x32_bf16 v[112:115], v[162:165], v[178:181], v[112:115]
	v_mfma_f32_16x16x32_bf16 v[104:107], v[154:157], v[186:189], v[104:107]
	v_mfma_f32_16x16x32_bf16 v[96:99], v[162:165], v[186:189], v[96:99]
	v_mfma_f32_16x16x32_bf16 v[88:91], v[154:157], v[194:197], v[88:91]
	v_mfma_f32_16x16x32_bf16 v[80:83], v[162:165], v[194:197], v[80:83]
	v_mfma_f32_16x16x32_bf16 v[124:127], v[158:161], v[174:177], v[124:127]
	v_mfma_f32_16x16x32_bf16 v[120:123], v[166:169], v[174:177], v[120:123]
	v_mfma_f32_16x16x32_bf16 v[116:119], v[158:161], v[182:185], v[116:119]
	v_mfma_f32_16x16x32_bf16 v[112:115], v[166:169], v[182:185], v[112:115]
	v_mfma_f32_16x16x32_bf16 v[104:107], v[158:161], v[190:193], v[104:107]
	v_mfma_f32_16x16x32_bf16 v[96:99], v[166:169], v[190:193], v[96:99]
	v_mfma_f32_16x16x32_bf16 v[88:91], v[158:161], v[198:201], v[88:91]
	v_mfma_f32_16x16x32_bf16 v[80:83], v[166:169], v[198:201], v[80:83]
	s_barrier
	s_add_i32 s10, 0, 0x1c000
	s_add_i32 s2, s2, s58
	v_add_u32_e32 v244, s10, v238
	s_mov_b32 m0, s2
	ds_read_b128 v[202:205], v244
	ds_read_b128 v[206:209], v244 offset:1024
	ds_read_b128 v[240:243], v244 offset:2048
	ds_read_b128 v[244:247], v244 offset:3072
	s_add_u32 s100, s0, 0x80
	s_addc_u32 s101, s1, 0
	global_load_lds_dwordx4 v140, s[100:101]
	s_add_i32 m0, s2, 0x2000
	s_nop 0
	global_load_lds_dwordx4 v132, s[100:101]
	s_barrier
	s_waitcnt lgkmcnt(0)
	v_mfma_f32_16x16x32_bf16 v[108:111], v[202:205], v[170:173], v[108:111]
	v_mfma_f32_16x16x32_bf16 v[100:103], v[240:243], v[170:173], v[100:103]
	v_mfma_f32_16x16x32_bf16 v[92:95], v[202:205], v[178:181], v[92:95]
	v_mfma_f32_16x16x32_bf16 v[84:87], v[240:243], v[178:181], v[84:87]
	v_mfma_f32_16x16x32_bf16 v[76:79], v[202:205], v[186:189], v[76:79]
	v_mfma_f32_16x16x32_bf16 v[72:75], v[240:243], v[186:189], v[72:75]
	v_mfma_f32_16x16x32_bf16 v[68:71], v[202:205], v[194:197], v[68:71]
	v_mfma_f32_16x16x32_bf16 v[64:67], v[240:243], v[194:197], v[64:67]
	v_mfma_f32_16x16x32_bf16 v[108:111], v[206:209], v[174:177], v[108:111]
	v_mfma_f32_16x16x32_bf16 v[100:103], v[244:247], v[174:177], v[100:103]
	v_mfma_f32_16x16x32_bf16 v[92:95], v[206:209], v[182:185], v[92:95]
	v_mfma_f32_16x16x32_bf16 v[84:87], v[244:247], v[182:185], v[84:87]
	v_mfma_f32_16x16x32_bf16 v[76:79], v[206:209], v[190:193], v[76:79]
	v_mfma_f32_16x16x32_bf16 v[72:75], v[244:247], v[190:193], v[72:75]
	v_mfma_f32_16x16x32_bf16 v[68:71], v[206:209], v[198:201], v[68:71]
	v_mfma_f32_16x16x32_bf16 v[64:67], v[244:247], v[198:201], v[64:67]
	s_mov_b32 m0, s75
	v_lshl_add_u64 v[138:139], v[248:249], 0, s[82:83]
	s_barrier
	ds_read_b128 v[170:173], v239 offset:49152
	ds_read_b128 v[174:177], v239 offset:50176
	ds_read_b128 v[178:181], v239 offset:51200
	ds_read_b128 v[182:185], v239 offset:52224
	ds_read_b128 v[186:189], v239 offset:53248
	ds_read_b128 v[190:193], v239 offset:54272
	ds_read_b128 v[194:197], v239 offset:55296
	ds_read_b128 v[198:201], v239 offset:56320
	global_load_lds_dwordx4 v[138:139], off
	v_lshl_add_u64 v[138:139], v[250:251], 0, s[82:83]
	s_mov_b32 m0, s77
	s_nop 0
	global_load_lds_dwordx4 v[138:139], off
	s_barrier
	s_waitcnt lgkmcnt(0)
	v_mfma_f32_16x16x32_bf16 v[60:63], v[154:157], v[170:173], v[60:63]
	v_mfma_f32_16x16x32_bf16 v[56:59], v[162:165], v[170:173], v[56:59]
	v_mfma_f32_16x16x32_bf16 v[52:55], v[154:157], v[178:181], v[52:55]
	v_mfma_f32_16x16x32_bf16 v[48:51], v[162:165], v[178:181], v[48:51]
	v_mfma_f32_16x16x32_bf16 v[36:39], v[154:157], v[186:189], v[36:39]
	v_mfma_f32_16x16x32_bf16 v[32:35], v[162:165], v[186:189], v[32:35]
	v_mfma_f32_16x16x32_bf16 v[20:23], v[154:157], v[194:197], v[20:23]
	v_mfma_f32_16x16x32_bf16 v[16:19], v[162:165], v[194:197], v[16:19]
	v_mfma_f32_16x16x32_bf16 v[60:63], v[158:161], v[174:177], v[60:63]
	v_mfma_f32_16x16x32_bf16 v[56:59], v[166:169], v[174:177], v[56:59]
	v_mfma_f32_16x16x32_bf16 v[52:55], v[158:161], v[182:185], v[52:55]
	v_mfma_f32_16x16x32_bf16 v[48:51], v[166:169], v[182:185], v[48:51]
	v_mfma_f32_16x16x32_bf16 v[36:39], v[158:161], v[190:193], v[36:39]
	v_mfma_f32_16x16x32_bf16 v[32:35], v[166:169], v[190:193], v[32:35]
	v_mfma_f32_16x16x32_bf16 v[20:23], v[158:161], v[198:201], v[20:23]
	v_mfma_f32_16x16x32_bf16 v[16:19], v[166:169], v[198:201], v[16:19]
	s_barrier
	s_add_i32 s2, s10, s58
	s_mov_b32 m0, s2
	s_add_u32 s0, s0, 0x100080
	s_addc_u32 s1, s1, 0
	global_load_lds_dwordx4 v140, s[0:1]
	s_add_i32 m0, s2, 0x2000
	s_nop 0
	global_load_lds_dwordx4 v132, s[0:1]
	s_waitcnt vmcnt(6)
	s_barrier
	v_mfma_f32_16x16x32_bf16 v[44:47], v[202:205], v[170:173], v[44:47]
	v_mfma_f32_16x16x32_bf16 v[40:43], v[240:243], v[170:173], v[40:43]
	v_mfma_f32_16x16x32_bf16 v[28:31], v[202:205], v[178:181], v[28:31]
	v_mfma_f32_16x16x32_bf16 v[24:27], v[240:243], v[178:181], v[24:27]
	v_mfma_f32_16x16x32_bf16 v[12:15], v[202:205], v[186:189], v[12:15]
	v_mfma_f32_16x16x32_bf16 v[8:11], v[240:243], v[186:189], v[8:11]
	v_mfma_f32_16x16x32_bf16 v[4:7], v[202:205], v[194:197], v[4:7]
	v_mfma_f32_16x16x32_bf16 v[0:3], v[240:243], v[194:197], v[0:3]
	v_mfma_f32_16x16x32_bf16 v[44:47], v[206:209], v[174:177], v[44:47]
	v_mfma_f32_16x16x32_bf16 v[40:43], v[244:247], v[174:177], v[40:43]
	v_mfma_f32_16x16x32_bf16 v[28:31], v[206:209], v[182:185], v[28:31]
	v_mfma_f32_16x16x32_bf16 v[24:27], v[244:247], v[182:185], v[24:27]
	v_mfma_f32_16x16x32_bf16 v[12:15], v[206:209], v[190:193], v[12:15]
	v_mfma_f32_16x16x32_bf16 v[8:11], v[244:247], v[190:193], v[8:11]
	v_mfma_f32_16x16x32_bf16 v[4:7], v[206:209], v[198:201], v[4:7]
	v_mfma_f32_16x16x32_bf16 v[0:3], v[244:247], v[198:201], v[0:3]
	s_add_i32 s20, s20, 2
	s_add_u32 s13, s13, 0x100
	s_addc_u32 s15, s15, 0
	s_add_u32 s8, s8, 0x100
	s_addc_u32 s9, s9, 0
	s_cmp_gt_u32 s20, 29
	s_barrier
	s_cbranch_scc0 .LBB0_126
	v_mbcnt_lo_u32_b32 v154, -1, 0
	v_mbcnt_hi_u32_b32 v154, -1, v154
	s_lshl_b32 s0, s16, 8
	v_ashrrev_i32_e32 v138, 2, v154
	s_or_b32 s0, s0, s74
	v_and_b32_e32 v138, -4, v138
	s_lshl_b32 s13, s64, 8
	v_add_u32_e32 v138, s0, v138
	v_and_b32_e32 v240, 15, v154
	s_cmp_gt_i32 s71, 7
	s_mov_b64 s[0:1], -1
	v_ashrrev_i32_e32 v139, 31, v138
	s_cbranch_scc0 .LBB0_145
	s_add_i32 s0, s71, -8
	s_lshl_b32 s52, s0, 10
	s_lshl_b32 s15, s0, 12
	s_lshl_b32 s16, s0, 11
	s_addk_i32 s15, 0x1000
	s_lshl_b64 s[0:1], s[52:53], 2
	v_or_b32_e32 v155, s73, v240
	s_add_u32 s0, s49, s0
	v_add_u32_e32 v206, s13, v155
	s_addc_u32 s1, s76, s1
	v_lshlrev_b64 v[198:199], 2, v[138:139]
	v_add_u32_e32 v156, s16, v206
	v_lshl_add_u64 v[160:161], s[0:1], 0, v[198:199]
	v_ashrrev_i32_e32 v157, 31, v156
	flat_load_dwordx4 v[162:165], v[160:161]
	v_lshlrev_b64 v[158:159], 12, v[156:157]
	v_lshl_add_u64 v[158:159], s[26:27], 0, v[158:159]
	v_lshl_add_u64 v[158:159], v[158:159], 0, v[198:199]
	flat_load_dwordx4 v[166:169], v[158:159] nt
	s_mov_b32 s0, 0x3c800000
	v_and_b32_e32 v155, 1, v154
	v_add_u32_e32 v156, s16, v156
	v_cmp_eq_u32_e64 s[8:9], 0, v155
	v_ashrrev_i32_e32 v157, 31, v156
	v_lshlrev_b64 v[156:157], 11, v[156:157]
	v_sub_u32_e32 v154, s15, v206
	v_lshl_add_u64 v[156:157], s[24:25], 0, v[156:157]
	v_cmp_ne_u32_e32 vcc, 0, v206
	v_lshl_add_u64 v[156:157], v[138:139], 1, v[156:157]
	s_waitcnt vmcnt(0) lgkmcnt(0)
	v_or_b32_e32 v236, 16, v206
	v_add_u32_e32 v236, s16, v236
	v_ashrrev_i32_e32 v237, 31, v236
	v_lshlrev_b64 v[236:237], 12, v[236:237]
	v_lshl_add_u64 v[236:237], s[26:27], 0, v[236:237]
	v_lshl_add_u64 v[236:237], v[236:237], 0, v[198:199]
	global_load_dwordx4 v[232:235], v[236:237], off nt
	v_or_b32_e32 v236, 32, v206
	v_add_u32_e32 v236, s16, v236
	v_ashrrev_i32_e32 v237, 31, v236
	v_lshlrev_b64 v[236:237], 12, v[236:237]
	v_lshl_add_u64 v[236:237], s[26:27], 0, v[236:237]
	v_lshl_add_u64 v[236:237], v[236:237], 0, v[198:199]
	global_load_dwordx4 v[246:249], v[236:237], off nt
	v_pk_mul_f32 v[164:165], v[164:165], s[0:1] op_sel_hi:[1,0]
	v_pk_mul_f32 v[162:163], v[162:163], s[0:1] op_sel_hi:[1,0]
	v_xor_b32_e32 v170, 0x80000000, v164
	v_xor_b32_e32 v171, 0x80000000, v165
	v_xor_b32_e32 v172, 0x80000000, v162
	v_xor_b32_e32 v173, 0x80000000, v163
	v_cndmask_b32_e64 v201, v171, v165, s[8:9]
	v_cndmask_b32_e64 v200, v170, v164, s[8:9]
	v_cndmask_b32_e64 v205, v173, v163, s[8:9]
	v_cndmask_b32_e64 v204, v172, v162, s[8:9]
	v_pk_add_f32 v[162:163], v[168:169], v[200:201]
	v_pk_add_f32 v[164:165], v[166:167], v[204:205]
	v_sub_f32_e32 v155, v162, v126
	v_sub_f32_e32 v167, v163, v127
	v_sub_f32_e32 v166, v164, v124
	v_cvt_pk_bf16_f32 v167, v155, v167
	v_ashrrev_i32_e32 v155, 31, v154
	v_sub_f32_e32 v168, v165, v125
	v_cvt_pk_bf16_f32 v166, v166, v168
	global_store_dwordx2 v[156:157], v[166:167], off
	s_and_saveexec_b64 s[0:1], vcc
	s_cbranch_execz .LBB0_130
	v_pk_add_f32 v[162:163], v[126:127], v[162:163]
	v_pk_add_f32 v[164:165], v[124:125], v[164:165]
	s_nop 0
	v_cvt_pk_bf16_f32 v164, v164, v165
	v_cvt_pk_bf16_f32 v165, v162, v163
	v_lshlrev_b64 v[162:163], 11, v[154:155]
	v_lshl_add_u64 v[162:163], s[24:25], 0, v[162:163]
	v_lshl_add_u64 v[162:163], v[138:139], 1, v[162:163]
	global_store_dwordx2 v[162:163], v[164:165], off

.LBB0_203:
	s_add_u32 s2, s44, s13
	s_addc_u32 s15, s45, 0
	s_add_u32 s17, s2, 0x100
	s_addc_u32 s21, s15, 0
	s_and_b64 s[18:19], s[0:1], exec
	s_cselect_b32 s81, s9, s21
	s_cselect_b32 s80, s8, s17
	s_add_u32 s13, s64, s13
	s_addc_u32 s17, s65, 0
	s_add_u32 s13, s13, 0x100
	s_addc_u32 s17, s17, 0
	s_add_i32 s21, 0, 0x10000
	s_and_b64 s[0:1], s[0:1], exec
	s_cselect_b32 s89, s11, s17
	s_cselect_b32 s88, s10, s13
	s_add_u32 s96, s2, 0x10080
	s_addc_u32 s97, s15, 0
	s_add_i32 s43, s21, s52
	s_add_i32 m0, s41, 0xc000
	s_add_i32 s47, s41, 0xe000
	s_add_i32 s42, 0, 0x14000
	s_add_i32 s31, s43, 0x2000
	s_add_u32 s76, s88, 0x40000
	v_add_u32_e32 v138, s21, v136
	s_addc_u32 s77, s89, 0
	s_add_i32 s19, s42, s52
	ds_read_b128 v[154:157], v138
	ds_read_b128 v[158:161], v138 offset:1024
	ds_read_b128 v[162:165], v138 offset:2048
	ds_read_b128 v[166:169], v138 offset:3072
	s_add_i32 s18, s19, 0x2000
	s_add_i32 s17, 0, 0x18000
	s_add_u32 s68, s80, 0x10000
	s_addc_u32 s69, s81, 0
	s_add_i32 s15, s17, s52
	s_add_i32 s13, 0, 0x1c000
	s_add_i32 s2, s15, 0x2000
	s_add_u32 s0, s88, 0x40080
	s_addc_u32 s1, s89, 0
	s_add_i32 s30, s13, s52
	s_add_i32 s21, s30, 0x2000
	ds_read_b128 v[170:173], v137
	ds_read_b128 v[174:177], v137 offset:1024
	ds_read_b128 v[178:181], v137 offset:2048
	ds_read_b128 v[182:185], v137 offset:3072
	ds_read_b128 v[186:189], v137 offset:4096
	ds_read_b128 v[190:193], v137 offset:5120
	ds_read_b128 v[194:197], v137 offset:6144
	global_load_lds_dwordx4 v128, s[96:97]
	s_mov_b32 m0, s47
	ds_read_b128 v[198:201], v137 offset:7168
	global_load_lds_dwordx4 v132, s[96:97]
	s_waitcnt lgkmcnt(8)
	s_barrier
	s_waitcnt lgkmcnt(0)
	v_mfma_f32_16x16x32_bf16 v[124:127], v[154:157], v[170:173], v[124:127]
	v_mfma_f32_16x16x32_bf16 v[120:123], v[162:165], v[170:173], v[120:123]
	v_mfma_f32_16x16x32_bf16 v[112:115], v[154:157], v[178:181], v[112:115]
	v_mfma_f32_16x16x32_bf16 v[104:107], v[162:165], v[178:181], v[104:107]
	v_mfma_f32_16x16x32_bf16 v[96:99], v[154:157], v[186:189], v[96:99]
	v_mfma_f32_16x16x32_bf16 v[88:91], v[162:165], v[186:189], v[88:91]
	v_mfma_f32_16x16x32_bf16 v[80:83], v[154:157], v[194:197], v[80:83]
	v_mfma_f32_16x16x32_bf16 v[72:75], v[162:165], v[194:197], v[72:75]
	v_mfma_f32_16x16x32_bf16 v[124:127], v[158:161], v[174:177], v[124:127]
	v_mfma_f32_16x16x32_bf16 v[120:123], v[166:169], v[174:177], v[120:123]
	v_mfma_f32_16x16x32_bf16 v[112:115], v[158:161], v[182:185], v[112:115]
	v_mfma_f32_16x16x32_bf16 v[104:107], v[166:169], v[182:185], v[104:107]
	v_mfma_f32_16x16x32_bf16 v[96:99], v[158:161], v[190:193], v[96:99]
	v_mfma_f32_16x16x32_bf16 v[88:91], v[166:169], v[190:193], v[88:91]
	v_mfma_f32_16x16x32_bf16 v[80:83], v[158:161], v[198:201], v[80:83]
	v_mfma_f32_16x16x32_bf16 v[72:75], v[166:169], v[198:201], v[72:75]
	s_barrier
	v_add_u32_e32 v138, s42, v136
	s_mov_b32 m0, s43
	ds_read_b128 v[202:205], v138
	ds_read_b128 v[206:209], v138 offset:1024
	ds_read_b128 v[228:231], v138 offset:2048
	global_load_lds_dwordx4 v130, s[88:89]
	s_mov_b32 m0, s31
	ds_read_b128 v[232:235], v138 offset:3072
	global_load_lds_dwordx4 v134, s[88:89]
	s_barrier
	s_waitcnt lgkmcnt(0)
	v_mfma_f32_16x16x32_bf16 v[116:119], v[202:205], v[170:173], v[116:119]
	v_mfma_f32_16x16x32_bf16 v[108:111], v[228:231], v[170:173], v[108:111]
	v_mfma_f32_16x16x32_bf16 v[100:103], v[202:205], v[178:181], v[100:103]
	v_mfma_f32_16x16x32_bf16 v[92:95], v[228:231], v[178:181], v[92:95]
	v_mfma_f32_16x16x32_bf16 v[84:87], v[202:205], v[186:189], v[84:87]
	v_mfma_f32_16x16x32_bf16 v[76:79], v[228:231], v[186:189], v[76:79]
	v_mfma_f32_16x16x32_bf16 v[68:71], v[202:205], v[194:197], v[68:71]
	v_mfma_f32_16x16x32_bf16 v[64:67], v[228:231], v[194:197], v[64:67]
	v_mfma_f32_16x16x32_bf16 v[116:119], v[206:209], v[174:177], v[116:119]
	v_mfma_f32_16x16x32_bf16 v[108:111], v[232:235], v[174:177], v[108:111]
	v_mfma_f32_16x16x32_bf16 v[100:103], v[206:209], v[182:185], v[100:103]
	v_mfma_f32_16x16x32_bf16 v[92:95], v[232:235], v[182:185], v[92:95]
	v_mfma_f32_16x16x32_bf16 v[84:87], v[206:209], v[190:193], v[84:87]
	v_mfma_f32_16x16x32_bf16 v[76:79], v[232:235], v[190:193], v[76:79]
	v_mfma_f32_16x16x32_bf16 v[68:71], v[206:209], v[198:201], v[68:71]
	v_mfma_f32_16x16x32_bf16 v[64:67], v[232:235], v[198:201], v[64:67]
	s_mov_b32 m0, s41
	s_barrier
	ds_read_b128 v[170:173], v137 offset:16384
	ds_read_b128 v[174:177], v137 offset:17408
	ds_read_b128 v[178:181], v137 offset:18432
	ds_read_b128 v[182:185], v137 offset:19456
	ds_read_b128 v[186:189], v137 offset:20480
	ds_read_b128 v[190:193], v137 offset:21504
	ds_read_b128 v[194:197], v137 offset:22528
	global_load_lds_dwordx4 v128, s[80:81]
	s_mov_b32 m0, s57
	ds_read_b128 v[198:201], v137 offset:23552
	global_load_lds_dwordx4 v132, s[80:81]
	s_barrier
	s_waitcnt lgkmcnt(0)
	v_mfma_f32_16x16x32_bf16 v[60:63], v[154:157], v[170:173], v[60:63]
	v_mfma_f32_16x16x32_bf16 v[56:59], v[162:165], v[170:173], v[56:59]
	v_mfma_f32_16x16x32_bf16 v[48:51], v[154:157], v[178:181], v[48:51]
	v_mfma_f32_16x16x32_bf16 v[40:43], v[162:165], v[178:181], v[40:43]
	v_mfma_f32_16x16x32_bf16 v[32:35], v[154:157], v[186:189], v[32:35]
	v_mfma_f32_16x16x32_bf16 v[24:27], v[162:165], v[186:189], v[24:27]
	v_mfma_f32_16x16x32_bf16 v[16:19], v[154:157], v[194:197], v[16:19]
	v_mfma_f32_16x16x32_bf16 v[8:11], v[162:165], v[194:197], v[8:11]
	v_mfma_f32_16x16x32_bf16 v[60:63], v[158:161], v[174:177], v[60:63]
	v_mfma_f32_16x16x32_bf16 v[56:59], v[166:169], v[174:177], v[56:59]
	v_mfma_f32_16x16x32_bf16 v[48:51], v[158:161], v[182:185], v[48:51]
	v_mfma_f32_16x16x32_bf16 v[40:43], v[166:169], v[182:185], v[40:43]
	v_mfma_f32_16x16x32_bf16 v[32:35], v[158:161], v[190:193], v[32:35]
	v_mfma_f32_16x16x32_bf16 v[24:27], v[166:169], v[190:193], v[24:27]
	v_mfma_f32_16x16x32_bf16 v[16:19], v[158:161], v[198:201], v[16:19]
	v_mfma_f32_16x16x32_bf16 v[8:11], v[166:169], v[198:201], v[8:11]
	s_barrier
	s_mov_b32 m0, s19
	s_nop 0
	global_load_lds_dwordx4 v130, s[76:77]
	s_mov_b32 m0, s18
	s_nop 0
	global_load_lds_dwordx4 v134, s[76:77]
	s_waitcnt vmcnt(6)
	s_barrier
	v_mfma_f32_16x16x32_bf16 v[52:55], v[202:205], v[170:173], v[52:55]
	v_mfma_f32_16x16x32_bf16 v[44:47], v[228:231], v[170:173], v[44:47]
	v_mfma_f32_16x16x32_bf16 v[36:39], v[202:205], v[178:181], v[36:39]
	v_mfma_f32_16x16x32_bf16 v[28:31], v[228:231], v[178:181], v[28:31]
	v_mfma_f32_16x16x32_bf16 v[20:23], v[202:205], v[186:189], v[20:23]
	v_mfma_f32_16x16x32_bf16 v[12:15], v[228:231], v[186:189], v[12:15]
	v_mfma_f32_16x16x32_bf16 v[4:7], v[202:205], v[194:197], v[4:7]
	v_mfma_f32_16x16x32_bf16 v[0:3], v[228:231], v[194:197], v[0:3]
	v_mfma_f32_16x16x32_bf16 v[52:55], v[206:209], v[174:177], v[52:55]
	v_mfma_f32_16x16x32_bf16 v[44:47], v[232:235], v[174:177], v[44:47]
	v_mfma_f32_16x16x32_bf16 v[36:39], v[206:209], v[182:185], v[36:39]
	v_mfma_f32_16x16x32_bf16 v[28:31], v[232:235], v[182:185], v[28:31]
	v_mfma_f32_16x16x32_bf16 v[20:23], v[206:209], v[190:193], v[20:23]
	v_mfma_f32_16x16x32_bf16 v[12:15], v[232:235], v[190:193], v[12:15]
	v_mfma_f32_16x16x32_bf16 v[4:7], v[206:209], v[198:201], v[4:7]
	v_mfma_f32_16x16x32_bf16 v[0:3], v[232:235], v[198:201], v[0:3]
	v_add_u32_e32 v140, s17, v136
	s_barrier
	ds_read_b128 v[154:157], v140
	ds_read_b128 v[158:161], v140 offset:1024
	ds_read_b128 v[162:165], v140 offset:2048
	ds_read_b128 v[166:169], v140 offset:3072
	s_mov_b32 m0, s58
	ds_read_b128 v[170:173], v137 offset:32768
	ds_read_b128 v[174:177], v137 offset:33792
	ds_read_b128 v[178:181], v137 offset:34816
	ds_read_b128 v[182:185], v137 offset:35840
	ds_read_b128 v[186:189], v137 offset:36864
	ds_read_b128 v[190:193], v137 offset:37888
	ds_read_b128 v[194:197], v137 offset:38912
	global_load_lds_dwordx4 v128, s[68:69]
	s_mov_b32 m0, s59
	ds_read_b128 v[198:201], v137 offset:39936
	global_load_lds_dwordx4 v132, s[68:69]
	s_waitcnt lgkmcnt(8)
	s_barrier
	s_waitcnt lgkmcnt(0)
	v_mfma_f32_16x16x32_bf16 v[124:127], v[154:157], v[170:173], v[124:127]
	v_mfma_f32_16x16x32_bf16 v[120:123], v[162:165], v[170:173], v[120:123]
	v_mfma_f32_16x16x32_bf16 v[112:115], v[154:157], v[178:181], v[112:115]
	v_mfma_f32_16x16x32_bf16 v[104:107], v[162:165], v[178:181], v[104:107]
	v_mfma_f32_16x16x32_bf16 v[96:99], v[154:157], v[186:189], v[96:99]
	v_mfma_f32_16x16x32_bf16 v[88:91], v[162:165], v[186:189], v[88:91]
	v_mfma_f32_16x16x32_bf16 v[80:83], v[154:157], v[194:197], v[80:83]
	v_mfma_f32_16x16x32_bf16 v[72:75], v[162:165], v[194:197], v[72:75]
	v_mfma_f32_16x16x32_bf16 v[124:127], v[158:161], v[174:177], v[124:127]
	v_mfma_f32_16x16x32_bf16 v[120:123], v[166:169], v[174:177], v[120:123]
	v_mfma_f32_16x16x32_bf16 v[112:115], v[158:161], v[182:185], v[112:115]
	v_mfma_f32_16x16x32_bf16 v[104:107], v[166:169], v[182:185], v[104:107]
	v_mfma_f32_16x16x32_bf16 v[96:99], v[158:161], v[190:193], v[96:99]
	v_mfma_f32_16x16x32_bf16 v[88:91], v[166:169], v[190:193], v[88:91]
	v_mfma_f32_16x16x32_bf16 v[80:83], v[158:161], v[198:201], v[80:83]
	v_mfma_f32_16x16x32_bf16 v[72:75], v[166:169], v[198:201], v[72:75]
	s_barrier
	s_mov_b32 m0, s15
	v_add_u32_e32 v140, s13, v136
	ds_read_b128 v[202:205], v140
	ds_read_b128 v[206:209], v140 offset:1024
	ds_read_b128 v[228:231], v140 offset:2048
	ds_read_b128 v[232:235], v140 offset:3072
	s_add_u32 s100, s88, 0x80
	s_addc_u32 s101, s89, 0
	global_load_lds_dwordx4 v130, s[100:101]
	s_mov_b32 m0, s2
	s_nop 0
	global_load_lds_dwordx4 v134, s[100:101]
	s_barrier
	s_waitcnt lgkmcnt(0)
	v_mfma_f32_16x16x32_bf16 v[116:119], v[202:205], v[170:173], v[116:119]
	v_mfma_f32_16x16x32_bf16 v[108:111], v[228:231], v[170:173], v[108:111]
	v_mfma_f32_16x16x32_bf16 v[100:103], v[202:205], v[178:181], v[100:103]
	v_mfma_f32_16x16x32_bf16 v[92:95], v[228:231], v[178:181], v[92:95]
	v_mfma_f32_16x16x32_bf16 v[84:87], v[202:205], v[186:189], v[84:87]
	v_mfma_f32_16x16x32_bf16 v[76:79], v[228:231], v[186:189], v[76:79]
	v_mfma_f32_16x16x32_bf16 v[68:71], v[202:205], v[194:197], v[68:71]
	v_mfma_f32_16x16x32_bf16 v[64:67], v[228:231], v[194:197], v[64:67]
	v_mfma_f32_16x16x32_bf16 v[116:119], v[206:209], v[174:177], v[116:119]
	v_mfma_f32_16x16x32_bf16 v[108:111], v[232:235], v[174:177], v[108:111]
	v_mfma_f32_16x16x32_bf16 v[100:103], v[206:209], v[182:185], v[100:103]
	v_mfma_f32_16x16x32_bf16 v[92:95], v[232:235], v[182:185], v[92:95]
	v_mfma_f32_16x16x32_bf16 v[84:87], v[206:209], v[190:193], v[84:87]
	v_mfma_f32_16x16x32_bf16 v[76:79], v[232:235], v[190:193], v[76:79]
	v_mfma_f32_16x16x32_bf16 v[68:71], v[206:209], v[198:201], v[68:71]
	v_mfma_f32_16x16x32_bf16 v[64:67], v[232:235], v[198:201], v[64:67]
	s_mov_b32 m0, s73
	s_barrier
	ds_read_b128 v[170:173], v137 offset:49152
	ds_read_b128 v[174:177], v137 offset:50176
	ds_read_b128 v[178:181], v137 offset:51200
	ds_read_b128 v[182:185], v137 offset:52224
	ds_read_b128 v[186:189], v137 offset:53248
	ds_read_b128 v[190:193], v137 offset:54272
	ds_read_b128 v[194:197], v137 offset:55296
	ds_read_b128 v[198:201], v137 offset:56320
	s_add_u32 s100, s80, 0x80
	s_addc_u32 s101, s81, 0
	global_load_lds_dwordx4 v128, s[100:101]
	s_mov_b32 m0, s74
	s_nop 0
	global_load_lds_dwordx4 v132, s[100:101]
	s_barrier
	s_waitcnt lgkmcnt(0)
	v_mfma_f32_16x16x32_bf16 v[60:63], v[154:157], v[170:173], v[60:63]
	v_mfma_f32_16x16x32_bf16 v[56:59], v[162:165], v[170:173], v[56:59]
	v_mfma_f32_16x16x32_bf16 v[48:51], v[154:157], v[178:181], v[48:51]
	v_mfma_f32_16x16x32_bf16 v[40:43], v[162:165], v[178:181], v[40:43]
	v_mfma_f32_16x16x32_bf16 v[32:35], v[154:157], v[186:189], v[32:35]
	v_mfma_f32_16x16x32_bf16 v[24:27], v[162:165], v[186:189], v[24:27]
	v_mfma_f32_16x16x32_bf16 v[16:19], v[154:157], v[194:197], v[16:19]
	v_mfma_f32_16x16x32_bf16 v[8:11], v[162:165], v[194:197], v[8:11]
	v_mfma_f32_16x16x32_bf16 v[60:63], v[158:161], v[174:177], v[60:63]
	v_mfma_f32_16x16x32_bf16 v[56:59], v[166:169], v[174:177], v[56:59]
	v_mfma_f32_16x16x32_bf16 v[48:51], v[158:161], v[182:185], v[48:51]
	v_mfma_f32_16x16x32_bf16 v[40:43], v[166:169], v[182:185], v[40:43]
	v_mfma_f32_16x16x32_bf16 v[32:35], v[158:161], v[190:193], v[32:35]
	v_mfma_f32_16x16x32_bf16 v[24:27], v[166:169], v[190:193], v[24:27]
	v_mfma_f32_16x16x32_bf16 v[16:19], v[158:161], v[198:201], v[16:19]
	v_mfma_f32_16x16x32_bf16 v[8:11], v[166:169], v[198:201], v[8:11]
	s_barrier
	s_mov_b32 m0, s30
	s_nop 0
	global_load_lds_dwordx4 v130, s[0:1]
	s_mov_b32 m0, s21
	s_nop 0
	global_load_lds_dwordx4 v134, s[0:1]
	s_waitcnt vmcnt(6)
	s_barrier
	v_mfma_f32_16x16x32_bf16 v[52:55], v[202:205], v[170:173], v[52:55]
	v_mfma_f32_16x16x32_bf16 v[44:47], v[228:231], v[170:173], v[44:47]
	v_mfma_f32_16x16x32_bf16 v[36:39], v[202:205], v[178:181], v[36:39]
	v_mfma_f32_16x16x32_bf16 v[28:31], v[228:231], v[178:181], v[28:31]
	v_mfma_f32_16x16x32_bf16 v[20:23], v[202:205], v[186:189], v[20:23]
	v_mfma_f32_16x16x32_bf16 v[12:15], v[228:231], v[186:189], v[12:15]
	v_mfma_f32_16x16x32_bf16 v[4:7], v[202:205], v[194:197], v[4:7]
	v_mfma_f32_16x16x32_bf16 v[0:3], v[228:231], v[194:197], v[0:3]
	v_mfma_f32_16x16x32_bf16 v[52:55], v[206:209], v[174:177], v[52:55]
	v_mfma_f32_16x16x32_bf16 v[44:47], v[232:235], v[174:177], v[44:47]
	v_mfma_f32_16x16x32_bf16 v[36:39], v[206:209], v[182:185], v[36:39]
	v_mfma_f32_16x16x32_bf16 v[28:31], v[232:235], v[182:185], v[28:31]
	v_mfma_f32_16x16x32_bf16 v[20:23], v[206:209], v[190:193], v[20:23]
	v_mfma_f32_16x16x32_bf16 v[12:15], v[232:235], v[190:193], v[12:15]
	v_mfma_f32_16x16x32_bf16 v[4:7], v[206:209], v[198:201], v[4:7]
	v_mfma_f32_16x16x32_bf16 v[0:3], v[232:235], v[198:201], v[0:3]
	s_movk_i32 s13, 0x100
	s_andn2_b64 vcc, exec, s[66:67]
	s_mov_b64 s[0:1], -1
	s_mov_b64 s[66:67], 0
	s_barrier
	s_cbranch_vccz .LBB0_203
	v_mbcnt_lo_u32_b32 v138, -1, 0
	v_mbcnt_hi_u32_b32 v138, -1, v138
	s_lshl_b32 s0, s40, 8
	v_ashrrev_i32_e32 v139, 1, v138
	s_or_b32 s0, s0, s72
	v_and_b32_e32 v139, -8, v139
	v_add_u32_e32 v139, s0, v139
	s_lshl_b32 s1, s20, 8
	v_and_or_b32 v138, v138, 15, s71
	s_and_b32 s1, s1, 0x300
	v_cvt_pk_bf16_f32 v124, v124, v125
	v_cvt_pk_bf16_f32 v125, v126, v127
	v_cvt_pk_bf16_f32 v126, v120, v121
	v_ashrrev_i32_e32 v120, 1, v139
	v_add_u32_e32 v138, s1, v138
	v_cvt_pk_bf16_f32 v127, v122, v123
	v_and_b32_e32 v122, 0xfffffc00, v120
	v_add_u32_e32 v120, v122, v138
	s_ashr_i32 s0, s20, 2
	v_ashrrev_i32_e32 v121, 31, v120
	s_ashr_i32 s1, s0, 31
	v_lshlrev_b64 v[120:121], 13, v[120:121]
	s_lshl_b64 s[0:1], s[0:1], 12
	v_and_b32_e32 v140, 0x7f8, v139
	v_lshl_add_u64 v[120:121], s[38:39], 0, v[120:121]
	v_lshl_add_u64 v[120:121], v[120:121], 0, s[0:1]
	v_lshlrev_b32_e32 v140, 1, v140
	v_lshl_add_u64 v[120:121], v[120:121], 0, v[140:141]
	flat_store_dwordx4 v[120:121], v[124:127]
	v_add_u32_e32 v120, 0x80, v139
	v_cvt_pk_bf16_f32 v116, v116, v117
	v_cvt_pk_bf16_f32 v117, v118, v119
	v_cvt_pk_bf16_f32 v118, v108, v109
	v_ashrrev_i32_e32 v108, 1, v120
	v_and_b32_e32 v121, 0x7f8, v120
	v_and_b32_e32 v120, 0xfffffc00, v108
	v_add_u32_e32 v108, v120, v138
	v_ashrrev_i32_e32 v109, 31, v108
	v_lshlrev_b64 v[108:109], 13, v[108:109]
	v_lshl_add_u64 v[108:109], s[38:39], 0, v[108:109]
	v_cvt_pk_bf16_f32 v119, v110, v111
	v_lshl_add_u64 v[110:111], v[108:109], 0, s[0:1]
	v_lshlrev_b32_e32 v108, 1, v121
	v_mov_b32_e32 v109, v141
	v_lshl_add_u64 v[110:111], v[110:111], 0, v[108:109]
	flat_store_dwordx4 v[110:111], v[116:119]
	v_cvt_pk_bf16_f32 v110, v112, v113
	v_cvt_pk_bf16_f32 v112, v104, v105
	v_cvt_pk_bf16_f32 v100, v100, v101
	v_cvt_pk_bf16_f32 v101, v102, v103
	v_cvt_pk_bf16_f32 v102, v92, v93
	s_nop 1
	v_or_b32_e32 v116, 16, v138
	v_add_u32_e32 v104, v122, v116
	v_add_u32_e32 v92, v120, v116
	v_ashrrev_i32_e32 v105, 31, v104
	v_ashrrev_i32_e32 v93, 31, v92
	v_lshlrev_b64 v[104:105], 13, v[104:105]
	v_lshlrev_b64 v[92:93], 13, v[92:93]
	v_lshl_add_u64 v[104:105], s[38:39], 0, v[104:105]
	v_lshl_add_u64 v[92:93], s[38:39], 0, v[92:93]
	v_lshl_add_u64 v[104:105], v[104:105], 0, s[0:1]
	v_lshl_add_u64 v[92:93], v[92:93], 0, s[0:1]
	v_lshl_add_u64 v[104:105], v[104:105], 0, v[140:141]
	v_lshl_add_u64 v[92:93], v[92:93], 0, v[108:109]
	v_cvt_pk_bf16_f32 v111, v114, v115
	v_cvt_pk_bf16_f32 v113, v106, v107
	flat_store_dwordx4 v[104:105], v[110:113]
	v_cvt_pk_bf16_f32 v103, v94, v95
	flat_store_dwordx4 v[92:93], v[100:103]
	v_cvt_pk_bf16_f32 v94, v88, v89
	v_cvt_pk_bf16_f32 v84, v84, v85
	v_cvt_pk_bf16_f32 v85, v86, v87
	v_cvt_pk_bf16_f32 v86, v76, v77
	v_cvt_pk_bf16_f32 v92, v96, v97
	s_nop 1
	v_or_b32_e32 v100, 32, v138
	v_add_u32_e32 v88, v122, v100
	v_add_u32_e32 v76, v120, v100
	v_ashrrev_i32_e32 v89, 31, v88
	v_ashrrev_i32_e32 v77, 31, v76
	v_lshlrev_b64 v[88:89], 13, v[88:89]
	v_lshlrev_b64 v[76:77], 13, v[76:77]
	v_lshl_add_u64 v[88:89], s[38:39], 0, v[88:89]
	v_lshl_add_u64 v[76:77], s[38:39], 0, v[76:77]
	v_lshl_add_u64 v[88:89], v[88:89], 0, s[0:1]
	v_lshl_add_u64 v[76:77], v[76:77], 0, s[0:1]
	v_lshl_add_u64 v[88:89], v[88:89], 0, v[140:141]
	v_lshl_add_u64 v[76:77], v[76:77], 0, v[108:109]
	v_cvt_pk_bf16_f32 v93, v98, v99
	v_cvt_pk_bf16_f32 v95, v90, v91
	flat_store_dwordx4 v[88:89], v[92:95]
	v_cvt_pk_bf16_f32 v87, v78, v79
	flat_store_dwordx4 v[76:77], v[84:87]
	v_cvt_pk_bf16_f32 v78, v72, v73
	v_cvt_pk_bf16_f32 v68, v68, v69
	v_cvt_pk_bf16_f32 v69, v70, v71
	v_cvt_pk_bf16_f32 v70, v64, v65
	v_cvt_pk_bf16_f32 v76, v80, v81
	s_nop 1
	v_or_b32_e32 v84, 48, v138
	v_add_u32_e32 v72, v122, v84
	v_add_u32_e32 v64, v120, v84
	v_ashrrev_i32_e32 v73, 31, v72
	v_ashrrev_i32_e32 v65, 31, v64
	v_lshlrev_b64 v[72:73], 13, v[72:73]
	v_lshlrev_b64 v[64:65], 13, v[64:65]
	v_lshl_add_u64 v[72:73], s[38:39], 0, v[72:73]
	v_lshl_add_u64 v[64:65], s[38:39], 0, v[64:65]
	v_lshl_add_u64 v[72:73], v[72:73], 0, s[0:1]
	v_lshl_add_u64 v[64:65], v[64:65], 0, s[0:1]
	v_lshl_add_u64 v[72:73], v[72:73], 0, v[140:141]
	v_lshl_add_u64 v[64:65], v[64:65], 0, v[108:109]
	v_cvt_pk_bf16_f32 v77, v82, v83
	v_cvt_pk_bf16_f32 v79, v74, v75
	flat_store_dwordx4 v[72:73], v[76:79]
	v_cvt_pk_bf16_f32 v71, v66, v67
	flat_store_dwordx4 v[64:65], v[68:71]
	v_add_u32_e32 v64, 0x80, v138
	v_cvt_pk_bf16_f32 v60, v60, v61
	v_cvt_pk_bf16_f32 v61, v62, v63
	v_cvt_pk_bf16_f32 v62, v56, v57
	v_add_u32_e32 v56, v122, v64
	v_cvt_pk_bf16_f32 v52, v52, v53
	v_cvt_pk_bf16_f32 v53, v54, v55
	v_cvt_pk_bf16_f32 v54, v44, v45
	v_add_u32_e32 v44, v120, v64
	v_ashrrev_i32_e32 v57, 31, v56
	v_ashrrev_i32_e32 v45, 31, v44
	v_lshlrev_b64 v[56:57], 13, v[56:57]
	v_lshlrev_b64 v[44:45], 13, v[44:45]
	v_lshl_add_u64 v[56:57], s[38:39], 0, v[56:57]
	v_lshl_add_u64 v[44:45], s[38:39], 0, v[44:45]
	v_lshl_add_u64 v[56:57], v[56:57], 0, s[0:1]
	v_lshl_add_u64 v[44:45], v[44:45], 0, s[0:1]
	v_lshl_add_u64 v[56:57], v[56:57], 0, v[140:141]
	v_lshl_add_u64 v[44:45], v[44:45], 0, v[108:109]
	v_cvt_pk_bf16_f32 v63, v58, v59
	flat_store_dwordx4 v[56:57], v[60:63]
	v_cvt_pk_bf16_f32 v55, v46, v47
	flat_store_dwordx4 v[44:45], v[52:55]
	v_cvt_pk_bf16_f32 v46, v40, v41
	v_cvt_pk_bf16_f32 v36, v36, v37
	v_cvt_pk_bf16_f32 v37, v38, v39
	v_cvt_pk_bf16_f32 v38, v28, v29
	v_cvt_pk_bf16_f32 v44, v48, v49
	s_nop 1
	v_add_u32_e32 v52, 0x90, v138
	v_add_u32_e32 v40, v122, v52
	v_add_u32_e32 v28, v120, v52
	v_ashrrev_i32_e32 v41, 31, v40
	v_ashrrev_i32_e32 v29, 31, v28
	v_lshlrev_b64 v[40:41], 13, v[40:41]
	v_lshlrev_b64 v[28:29], 13, v[28:29]
	v_lshl_add_u64 v[40:41], s[38:39], 0, v[40:41]
	v_lshl_add_u64 v[28:29], s[38:39], 0, v[28:29]
	v_lshl_add_u64 v[40:41], v[40:41], 0, s[0:1]
	v_lshl_add_u64 v[28:29], v[28:29], 0, s[0:1]
	v_lshl_add_u64 v[40:41], v[40:41], 0, v[140:141]
	v_lshl_add_u64 v[28:29], v[28:29], 0, v[108:109]
	v_cvt_pk_bf16_f32 v45, v50, v51
	v_cvt_pk_bf16_f32 v47, v42, v43
	flat_store_dwordx4 v[40:41], v[44:47]
	v_cvt_pk_bf16_f32 v39, v30, v31
	flat_store_dwordx4 v[28:29], v[36:39]
	v_cvt_pk_bf16_f32 v30, v24, v25
	v_cvt_pk_bf16_f32 v20, v20, v21
	v_cvt_pk_bf16_f32 v21, v22, v23
	v_cvt_pk_bf16_f32 v22, v12, v13
	v_cvt_pk_bf16_f32 v28, v32, v33
	s_nop 1
	v_add_u32_e32 v36, 0xa0, v138
	v_add_u32_e32 v24, v122, v36
	v_add_u32_e32 v12, v120, v36
	v_ashrrev_i32_e32 v25, 31, v24
	v_ashrrev_i32_e32 v13, 31, v12
	v_lshlrev_b64 v[24:25], 13, v[24:25]
	v_lshlrev_b64 v[12:13], 13, v[12:13]
	v_lshl_add_u64 v[24:25], s[38:39], 0, v[24:25]
	v_lshl_add_u64 v[12:13], s[38:39], 0, v[12:13]
	v_lshl_add_u64 v[24:25], v[24:25], 0, s[0:1]
	v_lshl_add_u64 v[12:13], v[12:13], 0, s[0:1]
	v_lshl_add_u64 v[24:25], v[24:25], 0, v[140:141]
	v_lshl_add_u64 v[12:13], v[12:13], 0, v[108:109]
	v_cvt_pk_bf16_f32 v29, v34, v35
	v_cvt_pk_bf16_f32 v31, v26, v27
	flat_store_dwordx4 v[24:25], v[28:31]
	v_cvt_pk_bf16_f32 v23, v14, v15
	flat_store_dwordx4 v[12:13], v[20:23]
	v_cvt_pk_bf16_f32 v14, v8, v9
	v_cvt_pk_bf16_f32 v4, v4, v5
	v_cvt_pk_bf16_f32 v5, v6, v7
	v_cvt_pk_bf16_f32 v6, v0, v1
	s_and_b64 vcc, exec, s[6:7]
	s_nop 0
	v_add_u32_e32 v20, 0xb0, v138
	v_add_u32_e32 v8, v122, v20
	v_add_u32_e32 v0, v120, v20
	v_ashrrev_i32_e32 v9, 31, v8
	v_ashrrev_i32_e32 v1, 31, v0
	v_lshlrev_b64 v[8:9], 13, v[8:9]
	v_lshlrev_b64 v[0:1], 13, v[0:1]
	v_lshl_add_u64 v[8:9], s[38:39], 0, v[8:9]
	v_lshl_add_u64 v[0:1], s[38:39], 0, v[0:1]
	v_lshl_add_u64 v[8:9], v[8:9], 0, s[0:1]
	v_lshl_add_u64 v[0:1], v[0:1], 0, s[0:1]
	v_lshl_add_u64 v[8:9], v[8:9], 0, v[140:141]
	v_lshl_add_u64 v[0:1], v[0:1], 0, v[108:109]
	s_mov_b32 s20, s12
	s_mov_b32 s40, s14
	s_mov_b64 s[64:65], s[10:11]
	s_mov_b64 s[44:45], s[8:9]
	v_readlane_b32 s89, v252, 11
	s_mov_b32 s81, 0x10000
	s_mov_b32 s88, 0x8000
	v_readlane_b32 s77, v252, 31
	v_cvt_pk_bf16_f32 v12, v16, v17
	v_cvt_pk_bf16_f32 v13, v18, v19
	v_cvt_pk_bf16_f32 v15, v10, v11
	flat_store_dwordx4 v[8:9], v[12:15]
	v_cvt_pk_bf16_f32 v7, v2, v3
	flat_store_dwordx4 v[0:1], v[4:7]
	s_cbranch_vccz .LBB0_192
	s_waitcnt vmcnt(0)
	s_cmpk_gt_u32 s49, 0xff
	s_cbranch_scc1 .LBB0_207
	s_barrier

.LBB0_275:
	s_add_u32 s0, s12, 0x100
	s_addc_u32 s1, s13, 0
	s_add_i32 s2, 0, 0x10000
	ds_read_b128 v[156:159], v236
	ds_read_b128 v[160:163], v236 offset:1024
	ds_read_b128 v[164:167], v236 offset:2048
	ds_read_b128 v[168:171], v236 offset:3072
	s_cmp_eq_u32 s65, 40
	s_cselect_b32 s15, s5, s1
	s_cselect_b32 s14, s4, s0
	s_cselect_b32 s11, s9, s64
	s_cselect_b32 s10, s8, s59
	s_add_i32 m0, s40, 0xc000
	ds_read_b128 v[172:175], v155
	ds_read_b128 v[176:179], v155 offset:1024
	ds_read_b128 v[180:183], v155 offset:2048
	ds_read_b128 v[184:187], v155 offset:3072
	ds_read_b128 v[188:191], v155 offset:4096
	ds_read_b128 v[192:195], v155 offset:5120
	ds_read_b128 v[196:199], v155 offset:6144
	global_load_lds_dwordx4 v136, s[12:13]
	s_add_i32 m0, s40, 0xe000
	ds_read_b128 v[200:203], v155 offset:7168
	global_load_lds_dwordx4 v134, s[12:13]
	s_waitcnt lgkmcnt(8)
	s_barrier
	s_waitcnt lgkmcnt(0)
	v_mfma_f32_16x16x32_bf16 v[124:127], v[156:159], v[172:175], v[124:127]
	v_mfma_f32_16x16x32_bf16 v[120:123], v[164:167], v[172:175], v[120:123]
	v_mfma_f32_16x16x32_bf16 v[116:119], v[156:159], v[180:183], v[116:119]
	v_mfma_f32_16x16x32_bf16 v[108:111], v[164:167], v[180:183], v[108:111]
	v_mfma_f32_16x16x32_bf16 v[100:103], v[156:159], v[188:191], v[100:103]
	v_mfma_f32_16x16x32_bf16 v[92:95], v[164:167], v[188:191], v[92:95]
	v_mfma_f32_16x16x32_bf16 v[84:87], v[156:159], v[196:199], v[84:87]
	v_mfma_f32_16x16x32_bf16 v[76:79], v[164:167], v[196:199], v[76:79]
	v_mfma_f32_16x16x32_bf16 v[124:127], v[160:163], v[176:179], v[124:127]
	v_mfma_f32_16x16x32_bf16 v[120:123], v[168:171], v[176:179], v[120:123]
	v_mfma_f32_16x16x32_bf16 v[116:119], v[160:163], v[184:187], v[116:119]
	v_mfma_f32_16x16x32_bf16 v[108:111], v[168:171], v[184:187], v[108:111]
	v_mfma_f32_16x16x32_bf16 v[100:103], v[160:163], v[192:195], v[100:103]
	v_mfma_f32_16x16x32_bf16 v[92:95], v[168:171], v[192:195], v[92:95]
	v_mfma_f32_16x16x32_bf16 v[84:87], v[160:163], v[200:203], v[84:87]
	v_mfma_f32_16x16x32_bf16 v[76:79], v[168:171], v[200:203], v[76:79]
	s_barrier
	s_add_i32 s18, 0, 0x14000
	s_add_i32 s2, s2, s39
	ds_read_b128 v[204:207], v237
	ds_read_b128 v[208:211], v237 offset:1024
	s_mov_b32 m0, s2
	ds_read_b128 v[228:231], v237 offset:2048
	global_load_lds_dwordx4 v140, s[10:11]
	s_add_i32 m0, s2, 0x2000
	ds_read_b128 v[232:235], v237 offset:3072
	global_load_lds_dwordx4 v132, s[10:11]
	s_barrier
	s_waitcnt lgkmcnt(0)
	v_mfma_f32_16x16x32_bf16 v[112:115], v[204:207], v[172:175], v[112:115]
	v_mfma_f32_16x16x32_bf16 v[104:107], v[228:231], v[172:175], v[104:107]
	v_mfma_f32_16x16x32_bf16 v[96:99], v[204:207], v[180:183], v[96:99]
	v_mfma_f32_16x16x32_bf16 v[88:91], v[228:231], v[180:183], v[88:91]
	v_mfma_f32_16x16x32_bf16 v[80:83], v[204:207], v[188:191], v[80:83]
	v_mfma_f32_16x16x32_bf16 v[72:75], v[228:231], v[188:191], v[72:75]
	v_mfma_f32_16x16x32_bf16 v[68:71], v[204:207], v[196:199], v[68:71]
	v_mfma_f32_16x16x32_bf16 v[64:67], v[228:231], v[196:199], v[64:67]
	v_mfma_f32_16x16x32_bf16 v[112:115], v[208:211], v[176:179], v[112:115]
	v_mfma_f32_16x16x32_bf16 v[104:107], v[232:235], v[176:179], v[104:107]
	v_mfma_f32_16x16x32_bf16 v[96:99], v[208:211], v[184:187], v[96:99]
	v_mfma_f32_16x16x32_bf16 v[88:91], v[232:235], v[184:187], v[88:91]
	v_mfma_f32_16x16x32_bf16 v[80:83], v[208:211], v[192:195], v[80:83]
	v_mfma_f32_16x16x32_bf16 v[72:75], v[232:235], v[192:195], v[72:75]
	v_mfma_f32_16x16x32_bf16 v[68:71], v[208:211], v[200:203], v[68:71]
	v_mfma_f32_16x16x32_bf16 v[64:67], v[232:235], v[200:203], v[64:67]
	s_mov_b32 m0, s40
	s_barrier
	ds_read_b128 v[172:175], v155 offset:16384
	ds_read_b128 v[176:179], v155 offset:17408
	ds_read_b128 v[180:183], v155 offset:18432
	ds_read_b128 v[184:187], v155 offset:19456
	ds_read_b128 v[188:191], v155 offset:20480
	ds_read_b128 v[192:195], v155 offset:21504
	ds_read_b128 v[196:199], v155 offset:22528
	global_load_lds_dwordx4 v128, s[14:15]
	s_mov_b32 m0, s41
	ds_read_b128 v[200:203], v155 offset:23552
	global_load_lds_dwordx4 v130, s[14:15]
	s_barrier
	s_waitcnt lgkmcnt(0)
	v_mfma_f32_16x16x32_bf16 v[60:63], v[156:159], v[172:175], v[60:63]
	v_mfma_f32_16x16x32_bf16 v[56:59], v[164:167], v[172:175], v[56:59]
	v_mfma_f32_16x16x32_bf16 v[52:55], v[156:159], v[180:183], v[52:55]
	v_mfma_f32_16x16x32_bf16 v[44:47], v[164:167], v[180:183], v[44:47]
	v_mfma_f32_16x16x32_bf16 v[36:39], v[156:159], v[188:191], v[36:39]
	v_mfma_f32_16x16x32_bf16 v[28:31], v[164:167], v[188:191], v[28:31]
	v_mfma_f32_16x16x32_bf16 v[20:23], v[156:159], v[196:199], v[20:23]
	v_mfma_f32_16x16x32_bf16 v[12:15], v[164:167], v[196:199], v[12:15]
	v_mfma_f32_16x16x32_bf16 v[60:63], v[160:163], v[176:179], v[60:63]
	v_mfma_f32_16x16x32_bf16 v[56:59], v[168:171], v[176:179], v[56:59]
	v_mfma_f32_16x16x32_bf16 v[52:55], v[160:163], v[184:187], v[52:55]
	v_mfma_f32_16x16x32_bf16 v[44:47], v[168:171], v[184:187], v[44:47]
	v_mfma_f32_16x16x32_bf16 v[36:39], v[160:163], v[192:195], v[36:39]
	v_mfma_f32_16x16x32_bf16 v[28:31], v[168:171], v[192:195], v[28:31]
	v_mfma_f32_16x16x32_bf16 v[20:23], v[160:163], v[200:203], v[20:23]
	v_mfma_f32_16x16x32_bf16 v[12:15], v[168:171], v[200:203], v[12:15]
	s_barrier
	s_add_i32 s2, s18, s39
	s_mov_b32 m0, s2
	s_add_u32 s12, s10, 0xb0000
	s_addc_u32 s13, s11, 0
	global_load_lds_dwordx4 v140, s[12:13]
	s_add_i32 m0, s2, 0x2000
	s_nop 0
	global_load_lds_dwordx4 v132, s[12:13]
	s_waitcnt vmcnt(6)
	s_barrier
	v_mfma_f32_16x16x32_bf16 v[48:51], v[204:207], v[172:175], v[48:51]
	v_mfma_f32_16x16x32_bf16 v[40:43], v[228:231], v[172:175], v[40:43]
	v_mfma_f32_16x16x32_bf16 v[32:35], v[204:207], v[180:183], v[32:35]
	v_mfma_f32_16x16x32_bf16 v[24:27], v[228:231], v[180:183], v[24:27]
	v_mfma_f32_16x16x32_bf16 v[16:19], v[204:207], v[188:191], v[16:19]
	v_mfma_f32_16x16x32_bf16 v[8:11], v[228:231], v[188:191], v[8:11]
	v_mfma_f32_16x16x32_bf16 v[4:7], v[204:207], v[196:199], v[4:7]
	v_mfma_f32_16x16x32_bf16 v[0:3], v[228:231], v[196:199], v[0:3]
	v_mfma_f32_16x16x32_bf16 v[48:51], v[208:211], v[176:179], v[48:51]
	v_mfma_f32_16x16x32_bf16 v[40:43], v[232:235], v[176:179], v[40:43]
	v_mfma_f32_16x16x32_bf16 v[32:35], v[208:211], v[184:187], v[32:35]
	v_mfma_f32_16x16x32_bf16 v[24:27], v[232:235], v[184:187], v[24:27]
	v_mfma_f32_16x16x32_bf16 v[16:19], v[208:211], v[192:195], v[16:19]
	v_mfma_f32_16x16x32_bf16 v[8:11], v[232:235], v[192:195], v[8:11]
	v_mfma_f32_16x16x32_bf16 v[4:7], v[208:211], v[200:203], v[4:7]
	v_mfma_f32_16x16x32_bf16 v[0:3], v[232:235], v[200:203], v[0:3]
	s_add_i32 s2, 0, 0x18000
	s_barrier
	ds_read_b128 v[156:159], v238
	ds_read_b128 v[160:163], v238 offset:1024
	ds_read_b128 v[164:167], v238 offset:2048
	ds_read_b128 v[168:171], v238 offset:3072
	s_add_u32 s12, s14, 0xb0000
	s_addc_u32 s13, s15, 0
	s_mov_b32 m0, s44
	ds_read_b128 v[172:175], v155 offset:32768
	ds_read_b128 v[176:179], v155 offset:33792
	ds_read_b128 v[180:183], v155 offset:34816
	ds_read_b128 v[184:187], v155 offset:35840
	ds_read_b128 v[188:191], v155 offset:36864
	ds_read_b128 v[192:195], v155 offset:37888
	ds_read_b128 v[196:199], v155 offset:38912
	global_load_lds_dwordx4 v128, s[12:13]
	s_mov_b32 m0, s45
	ds_read_b128 v[200:203], v155 offset:39936
	global_load_lds_dwordx4 v130, s[12:13]
	s_waitcnt lgkmcnt(8)
	s_barrier
	s_waitcnt lgkmcnt(0)
	v_mfma_f32_16x16x32_bf16 v[124:127], v[156:159], v[172:175], v[124:127]
	v_mfma_f32_16x16x32_bf16 v[120:123], v[164:167], v[172:175], v[120:123]
	v_mfma_f32_16x16x32_bf16 v[116:119], v[156:159], v[180:183], v[116:119]
	v_mfma_f32_16x16x32_bf16 v[108:111], v[164:167], v[180:183], v[108:111]
	v_mfma_f32_16x16x32_bf16 v[100:103], v[156:159], v[188:191], v[100:103]
	v_mfma_f32_16x16x32_bf16 v[92:95], v[164:167], v[188:191], v[92:95]
	v_mfma_f32_16x16x32_bf16 v[84:87], v[156:159], v[196:199], v[84:87]
	v_mfma_f32_16x16x32_bf16 v[76:79], v[164:167], v[196:199], v[76:79]
	v_mfma_f32_16x16x32_bf16 v[124:127], v[160:163], v[176:179], v[124:127]
	v_mfma_f32_16x16x32_bf16 v[120:123], v[168:171], v[176:179], v[120:123]
	v_mfma_f32_16x16x32_bf16 v[116:119], v[160:163], v[184:187], v[116:119]
	v_mfma_f32_16x16x32_bf16 v[108:111], v[168:171], v[184:187], v[108:111]
	v_mfma_f32_16x16x32_bf16 v[100:103], v[160:163], v[192:195], v[100:103]
	v_mfma_f32_16x16x32_bf16 v[92:95], v[168:171], v[192:195], v[92:95]
	v_mfma_f32_16x16x32_bf16 v[84:87], v[160:163], v[200:203], v[84:87]
	v_mfma_f32_16x16x32_bf16 v[76:79], v[168:171], v[200:203], v[76:79]
	s_barrier
	s_add_i32 s12, 0, 0x1c000
	s_add_i32 s2, s2, s39
	s_mov_b32 m0, s2
	ds_read_b128 v[204:207], v239
	ds_read_b128 v[208:211], v239 offset:1024
	ds_read_b128 v[228:231], v239 offset:2048
	ds_read_b128 v[232:235], v239 offset:3072
	s_add_u32 s100, s10, 0x80
	s_addc_u32 s101, s11, 0
	global_load_lds_dwordx4 v140, s[100:101]
	s_add_i32 m0, s2, 0x2000
	s_nop 0
	global_load_lds_dwordx4 v132, s[100:101]
	s_barrier
	s_waitcnt lgkmcnt(0)
	v_mfma_f32_16x16x32_bf16 v[112:115], v[204:207], v[172:175], v[112:115]
	v_mfma_f32_16x16x32_bf16 v[104:107], v[228:231], v[172:175], v[104:107]
	v_mfma_f32_16x16x32_bf16 v[96:99], v[204:207], v[180:183], v[96:99]
	v_mfma_f32_16x16x32_bf16 v[88:91], v[228:231], v[180:183], v[88:91]
	v_mfma_f32_16x16x32_bf16 v[80:83], v[204:207], v[188:191], v[80:83]
	v_mfma_f32_16x16x32_bf16 v[72:75], v[228:231], v[188:191], v[72:75]
	v_mfma_f32_16x16x32_bf16 v[68:71], v[204:207], v[196:199], v[68:71]
	v_mfma_f32_16x16x32_bf16 v[64:67], v[228:231], v[196:199], v[64:67]
	v_mfma_f32_16x16x32_bf16 v[112:115], v[208:211], v[176:179], v[112:115]
	v_mfma_f32_16x16x32_bf16 v[104:107], v[232:235], v[176:179], v[104:107]
	v_mfma_f32_16x16x32_bf16 v[96:99], v[208:211], v[184:187], v[96:99]
	v_mfma_f32_16x16x32_bf16 v[88:91], v[232:235], v[184:187], v[88:91]
	v_mfma_f32_16x16x32_bf16 v[80:83], v[208:211], v[192:195], v[80:83]
	v_mfma_f32_16x16x32_bf16 v[72:75], v[232:235], v[192:195], v[72:75]
	v_mfma_f32_16x16x32_bf16 v[68:71], v[208:211], v[200:203], v[68:71]
	v_mfma_f32_16x16x32_bf16 v[64:67], v[232:235], v[200:203], v[64:67]
	s_mov_b32 m0, s49
	s_barrier
	ds_read_b128 v[172:175], v155 offset:49152
	ds_read_b128 v[176:179], v155 offset:50176
	ds_read_b128 v[180:183], v155 offset:51200
	ds_read_b128 v[184:187], v155 offset:52224
	ds_read_b128 v[188:191], v155 offset:53248
	ds_read_b128 v[192:195], v155 offset:54272
	ds_read_b128 v[196:199], v155 offset:55296
	ds_read_b128 v[200:203], v155 offset:56320
	s_add_u32 s100, s14, 0x80
	s_addc_u32 s101, s15, 0
	global_load_lds_dwordx4 v128, s[100:101]
	s_mov_b32 m0, s20
	s_nop 0
	global_load_lds_dwordx4 v130, s[100:101]
	s_barrier
	s_waitcnt lgkmcnt(0)
	v_mfma_f32_16x16x32_bf16 v[60:63], v[156:159], v[172:175], v[60:63]
	v_mfma_f32_16x16x32_bf16 v[56:59], v[164:167], v[172:175], v[56:59]
	v_mfma_f32_16x16x32_bf16 v[52:55], v[156:159], v[180:183], v[52:55]
	v_mfma_f32_16x16x32_bf16 v[44:47], v[164:167], v[180:183], v[44:47]
	v_mfma_f32_16x16x32_bf16 v[36:39], v[156:159], v[188:191], v[36:39]
	v_mfma_f32_16x16x32_bf16 v[28:31], v[164:167], v[188:191], v[28:31]
	v_mfma_f32_16x16x32_bf16 v[20:23], v[156:159], v[196:199], v[20:23]
	v_mfma_f32_16x16x32_bf16 v[12:15], v[164:167], v[196:199], v[12:15]
	v_mfma_f32_16x16x32_bf16 v[60:63], v[160:163], v[176:179], v[60:63]
	v_mfma_f32_16x16x32_bf16 v[56:59], v[168:171], v[176:179], v[56:59]
	v_mfma_f32_16x16x32_bf16 v[52:55], v[160:163], v[184:187], v[52:55]
	v_mfma_f32_16x16x32_bf16 v[44:47], v[168:171], v[184:187], v[44:47]
	v_mfma_f32_16x16x32_bf16 v[36:39], v[160:163], v[192:195], v[36:39]
	v_mfma_f32_16x16x32_bf16 v[28:31], v[168:171], v[192:195], v[28:31]
	v_mfma_f32_16x16x32_bf16 v[20:23], v[160:163], v[200:203], v[20:23]
	v_mfma_f32_16x16x32_bf16 v[12:15], v[168:171], v[200:203], v[12:15]
	s_barrier
	s_add_i32 s2, s12, s39
	s_mov_b32 m0, s2
	s_add_u32 s10, s10, 0xb0080
	s_addc_u32 s11, s11, 0
	global_load_lds_dwordx4 v140, s[10:11]
	s_add_i32 m0, s2, 0x2000
	s_nop 0
	global_load_lds_dwordx4 v132, s[10:11]
	s_waitcnt vmcnt(6)
	s_barrier
	v_mfma_f32_16x16x32_bf16 v[48:51], v[204:207], v[172:175], v[48:51]
	v_mfma_f32_16x16x32_bf16 v[40:43], v[228:231], v[172:175], v[40:43]
	v_mfma_f32_16x16x32_bf16 v[32:35], v[204:207], v[180:183], v[32:35]
	v_mfma_f32_16x16x32_bf16 v[24:27], v[228:231], v[180:183], v[24:27]
	v_mfma_f32_16x16x32_bf16 v[16:19], v[204:207], v[188:191], v[16:19]
	v_mfma_f32_16x16x32_bf16 v[8:11], v[228:231], v[188:191], v[8:11]
	v_mfma_f32_16x16x32_bf16 v[4:7], v[204:207], v[196:199], v[4:7]
	v_mfma_f32_16x16x32_bf16 v[0:3], v[228:231], v[196:199], v[0:3]
	v_mfma_f32_16x16x32_bf16 v[48:51], v[208:211], v[176:179], v[48:51]
	v_mfma_f32_16x16x32_bf16 v[40:43], v[232:235], v[176:179], v[40:43]
	v_mfma_f32_16x16x32_bf16 v[32:35], v[208:211], v[184:187], v[32:35]
	v_mfma_f32_16x16x32_bf16 v[24:27], v[232:235], v[184:187], v[24:27]
	v_mfma_f32_16x16x32_bf16 v[16:19], v[208:211], v[192:195], v[16:19]
	v_mfma_f32_16x16x32_bf16 v[8:11], v[232:235], v[192:195], v[8:11]
	v_mfma_f32_16x16x32_bf16 v[4:7], v[208:211], v[200:203], v[4:7]
	v_mfma_f32_16x16x32_bf16 v[0:3], v[232:235], v[200:203], v[0:3]
	s_add_i32 s65, s65, 2
	s_add_u32 s59, s59, 0x100
	s_addc_u32 s64, s64, 0
	s_cmp_gt_u32 s65, 41
	s_mov_b64 s[12:13], s[0:1]
	s_barrier
	s_cbranch_scc0 .LBB0_275
	s_lshl_b32 s0, s57, 8
	v_mbcnt_lo_u32_b32 v139, -1, 0
	v_mbcnt_hi_u32_b32 v139, -1, v139
	s_lshl_b32 s1, s58, 8
	v_ashrrev_i32_e32 v138, 1, v139
	s_add_i32 s0, s0, s46
	v_and_b32_e32 v138, -8, v138
	s_or_b32 s1, s1, s48
	v_and_or_b32 v156, v139, 15, s0
	v_add_u32_e32 v138, s1, v138
	v_ashrrev_i32_e32 v157, 31, v156
	v_ashrrev_i32_e32 v139, 31, v138
	v_lshlrev_b64 v[158:159], 11, v[156:157]
	v_lshl_add_u64 v[158:159], s[24:25], 0, v[158:159]
	v_lshlrev_b64 v[160:161], 1, v[138:139]
	v_lshl_add_u64 v[138:139], v[158:159], 0, v[160:161]
	v_cvt_pk_bf16_f32 v60, v60, v61
	v_cvt_pk_bf16_f32 v61, v62, v63
	v_cvt_pk_bf16_f32 v62, v56, v57
	v_add_co_u32_e32 v56, vcc, s19, v138
	v_cvt_pk_bf16_f32 v112, v112, v113
	v_cvt_pk_bf16_f32 v113, v114, v115
	v_cvt_pk_bf16_f32 v114, v104, v105
	v_or_b32_e32 v104, 16, v156
	s_nop 0
	v_addc_co_u32_e32 v57, vcc, 0, v139, vcc
	v_cvt_pk_bf16_f32 v48, v48, v49
	v_cvt_pk_bf16_f32 v49, v50, v51
	v_cvt_pk_bf16_f32 v51, v42, v43
	v_cvt_pk_bf16_f32 v42, v44, v45
	v_add_co_u32_e32 v44, vcc, s30, v138
	v_ashrrev_i32_e32 v105, 31, v104
	v_cvt_pk_bf16_f32 v96, v96, v97
	v_cvt_pk_bf16_f32 v97, v98, v99
	v_cvt_pk_bf16_f32 v98, v88, v89
	v_or_b32_e32 v88, 32, v156
	v_addc_co_u32_e32 v45, vcc, 0, v139, vcc
	v_lshlrev_b64 v[104:105], 11, v[104:105]
	v_ashrrev_i32_e32 v89, 31, v88
	v_cvt_pk_bf16_f32 v80, v80, v81
	v_cvt_pk_bf16_f32 v81, v82, v83
	v_cvt_pk_bf16_f32 v82, v72, v73
	v_or_b32_e32 v72, 48, v156
	s_mov_b64 s[0:1], 0x40000
	v_cvt_pk_bf16_f32 v32, v32, v33
	v_cvt_pk_bf16_f32 v33, v34, v35
	v_cvt_pk_bf16_f32 v35, v26, v27
	v_cvt_pk_bf16_f32 v26, v28, v29
	v_add_co_u32_e32 v28, vcc, s31, v138
	v_lshl_add_u64 v[104:105], s[24:25], 0, v[104:105]
	v_lshlrev_b64 v[88:89], 11, v[88:89]
	v_ashrrev_i32_e32 v73, 31, v72
	v_cvt_pk_bf16_f32 v68, v68, v69
	v_cvt_pk_bf16_f32 v69, v70, v71
	v_cvt_pk_bf16_f32 v70, v64, v65
	v_lshl_add_u64 v[64:65], v[138:139], 0, s[0:1]
	s_mov_b64 s[0:1], 0x48000
	v_addc_co_u32_e32 v29, vcc, 0, v139, vcc
	v_cvt_pk_bf16_f32 v115, v106, v107
	flat_store_dwordx4 v[138:139], v[112:115] offset:256
	v_lshl_add_u64 v[88:89], s[24:25], 0, v[88:89]
	v_lshlrev_b64 v[72:73], 11, v[72:73]
	v_lshl_add_u64 v[112:113], v[104:105], 0, v[160:161]
	v_cvt_pk_bf16_f32 v50, v40, v41
	flat_store_dwordx4 v[64:65], v[48:51] offset:256
	v_cvt_pk_bf16_f32 v16, v16, v17
	v_cvt_pk_bf16_f32 v17, v18, v19
	v_cvt_pk_bf16_f32 v19, v10, v11
	v_cvt_pk_bf16_f32 v10, v12, v13
	v_add_co_u32_e32 v12, vcc, s42, v138
	s_nop 0
	v_lshl_add_u64 v[48:49], v[138:139], 0, s[0:1]
	s_mov_b64 s[0:1], 0x50000
	v_cvt_pk_bf16_f32 v99, v90, v91
	flat_store_dwordx4 v[112:113], v[96:99] offset:256
	v_lshl_add_u64 v[72:73], s[24:25], 0, v[72:73]
	v_cvt_pk_bf16_f32 v34, v24, v25
	flat_store_dwordx4 v[48:49], v[32:35] offset:256
	v_lshl_add_u64 v[96:97], v[88:89], 0, v[160:161]
	v_addc_co_u32_e32 v13, vcc, 0, v139, vcc
	v_lshl_add_u64 v[32:33], v[138:139], 0, s[0:1]
	s_mov_b64 s[0:1], 0x58000
	v_cvt_pk_bf16_f32 v83, v74, v75
	flat_store_dwordx4 v[96:97], v[80:83] offset:256
	v_cvt_pk_bf16_f32 v18, v8, v9
	flat_store_dwordx4 v[32:33], v[16:19] offset:256
	s_and_b64 vcc, exec, s[6:7]
	v_lshl_add_u64 v[80:81], v[72:73], 0, v[160:161]
	v_lshl_add_u64 v[16:17], v[138:139], 0, s[0:1]
	s_mov_b32 s58, s52
	s_mov_b32 s57, s51
	s_mov_b64 s[0:1], s[8:9]
	s_mov_b64 s[12:13], s[4:5]
	v_cvt_pk_bf16_f32 v124, v124, v125
	v_cvt_pk_bf16_f32 v125, v126, v127
	v_cvt_pk_bf16_f32 v126, v120, v121
	v_cvt_pk_bf16_f32 v127, v122, v123
	flat_store_dwordx4 v[138:139], v[124:127]
	v_cvt_pk_bf16_f32 v104, v116, v117
	v_cvt_pk_bf16_f32 v105, v118, v119
	v_cvt_pk_bf16_f32 v106, v108, v109
	v_cvt_pk_bf16_f32 v107, v110, v111
	flat_store_dwordx4 v[112:113], v[104:107]
	v_cvt_pk_bf16_f32 v88, v100, v101
	v_cvt_pk_bf16_f32 v89, v102, v103
	v_cvt_pk_bf16_f32 v90, v92, v93
	v_cvt_pk_bf16_f32 v91, v94, v95
	flat_store_dwordx4 v[96:97], v[88:91]
	v_cvt_pk_bf16_f32 v72, v84, v85
	v_cvt_pk_bf16_f32 v73, v86, v87
	v_cvt_pk_bf16_f32 v74, v76, v77
	v_cvt_pk_bf16_f32 v75, v78, v79
	flat_store_dwordx4 v[80:81], v[72:75]
	v_cvt_pk_bf16_f32 v71, v66, v67
	flat_store_dwordx4 v[80:81], v[68:71] offset:256
	v_cvt_pk_bf16_f32 v63, v58, v59
	flat_store_dwordx4 v[56:57], v[60:63]
	v_cvt_pk_bf16_f32 v40, v52, v53
	v_cvt_pk_bf16_f32 v41, v54, v55
	v_cvt_pk_bf16_f32 v43, v46, v47
	flat_store_dwordx4 v[44:45], v[40:43]
	v_cvt_pk_bf16_f32 v24, v36, v37
	v_cvt_pk_bf16_f32 v25, v38, v39
	v_cvt_pk_bf16_f32 v27, v30, v31
	flat_store_dwordx4 v[28:29], v[24:27]
	v_cvt_pk_bf16_f32 v8, v20, v21
	v_cvt_pk_bf16_f32 v9, v22, v23
	v_cvt_pk_bf16_f32 v11, v14, v15
	flat_store_dwordx4 v[12:13], v[8:11]
	v_cvt_pk_bf16_f32 v4, v4, v5
	v_cvt_pk_bf16_f32 v5, v6, v7
	v_cvt_pk_bf16_f32 v6, v0, v1
	v_cvt_pk_bf16_f32 v7, v2, v3
	flat_store_dwordx4 v[16:17], v[4:7] offset:256
	s_cbranch_vccz .LBB0_264
	s_waitcnt vmcnt(0)
	s_cmpk_gt_u32 s17, 0xff
	s_cbranch_scc1 .LBB0_279
	s_barrier

.LBB0_289:
	s_add_u32 s0, s16, 0xfffc0080
	s_addc_u32 s1, s17, -1
	s_add_i32 s2, 0, 0x10000
	ds_read_b128 v[156:159], v236
	ds_read_b128 v[160:163], v236 offset:1024
	ds_read_b128 v[164:167], v236 offset:2048
	ds_read_b128 v[168:171], v236 offset:3072
	s_cmp_eq_u32 s21, 12
	s_cselect_b32 s37, s11, s1
	s_cselect_b32 s36, s10, s0
	s_cselect_b32 s1, s13, s9
	s_cselect_b32 s0, s12, s5
	s_add_i32 m0, s15, 0xc000
	ds_read_b128 v[172:175], v155
	ds_read_b128 v[176:179], v155 offset:1024
	ds_read_b128 v[180:183], v155 offset:2048
	ds_read_b128 v[184:187], v155 offset:3072
	ds_read_b128 v[188:191], v155 offset:4096
	ds_read_b128 v[192:195], v155 offset:5120
	ds_read_b128 v[196:199], v155 offset:6144
	global_load_lds_dwordx4 v136, s[16:17]
	s_add_i32 m0, s15, 0xe000
	ds_read_b128 v[200:203], v155 offset:7168
	global_load_lds_dwordx4 v134, s[16:17]
	s_waitcnt lgkmcnt(8)
	s_barrier
	s_waitcnt lgkmcnt(0)
	v_mfma_f32_16x16x32_bf16 v[124:127], v[156:159], v[172:175], v[124:127]
	v_mfma_f32_16x16x32_bf16 v[120:123], v[164:167], v[172:175], v[120:123]
	v_mfma_f32_16x16x32_bf16 v[108:111], v[156:159], v[180:183], v[108:111]
	v_mfma_f32_16x16x32_bf16 v[104:107], v[164:167], v[180:183], v[104:107]
	v_mfma_f32_16x16x32_bf16 v[92:95], v[156:159], v[188:191], v[92:95]
	v_mfma_f32_16x16x32_bf16 v[88:91], v[164:167], v[188:191], v[88:91]
	v_mfma_f32_16x16x32_bf16 v[76:79], v[156:159], v[196:199], v[76:79]
	v_mfma_f32_16x16x32_bf16 v[72:75], v[164:167], v[196:199], v[72:75]
	v_mfma_f32_16x16x32_bf16 v[124:127], v[160:163], v[176:179], v[124:127]
	v_mfma_f32_16x16x32_bf16 v[120:123], v[168:171], v[176:179], v[120:123]
	v_mfma_f32_16x16x32_bf16 v[108:111], v[160:163], v[184:187], v[108:111]
	v_mfma_f32_16x16x32_bf16 v[104:107], v[168:171], v[184:187], v[104:107]
	v_mfma_f32_16x16x32_bf16 v[92:95], v[160:163], v[192:195], v[92:95]
	v_mfma_f32_16x16x32_bf16 v[88:91], v[168:171], v[192:195], v[88:91]
	v_mfma_f32_16x16x32_bf16 v[76:79], v[160:163], v[200:203], v[76:79]
	v_mfma_f32_16x16x32_bf16 v[72:75], v[168:171], v[200:203], v[72:75]
	s_barrier
	s_add_i32 s30, 0, 0x14000
	s_add_i32 s2, s2, s44
	ds_read_b128 v[204:207], v237
	ds_read_b128 v[208:211], v237 offset:1024
	s_mov_b32 m0, s2
	ds_read_b128 v[228:231], v237 offset:2048
	global_load_lds_dwordx4 v140, s[0:1]
	s_add_i32 m0, s2, 0x2000
	ds_read_b128 v[232:235], v237 offset:3072
	global_load_lds_dwordx4 v128, s[0:1]
	s_barrier
	s_waitcnt lgkmcnt(0)
	v_mfma_f32_16x16x32_bf16 v[116:119], v[204:207], v[172:175], v[116:119]
	v_mfma_f32_16x16x32_bf16 v[112:115], v[228:231], v[172:175], v[112:115]
	v_mfma_f32_16x16x32_bf16 v[100:103], v[204:207], v[180:183], v[100:103]
	v_mfma_f32_16x16x32_bf16 v[96:99], v[228:231], v[180:183], v[96:99]
	v_mfma_f32_16x16x32_bf16 v[84:87], v[204:207], v[188:191], v[84:87]
	v_mfma_f32_16x16x32_bf16 v[80:83], v[228:231], v[188:191], v[80:83]
	v_mfma_f32_16x16x32_bf16 v[68:71], v[204:207], v[196:199], v[68:71]
	v_mfma_f32_16x16x32_bf16 v[64:67], v[228:231], v[196:199], v[64:67]
	v_mfma_f32_16x16x32_bf16 v[116:119], v[208:211], v[176:179], v[116:119]
	v_mfma_f32_16x16x32_bf16 v[112:115], v[232:235], v[176:179], v[112:115]
	v_mfma_f32_16x16x32_bf16 v[100:103], v[208:211], v[184:187], v[100:103]
	v_mfma_f32_16x16x32_bf16 v[96:99], v[232:235], v[184:187], v[96:99]
	v_mfma_f32_16x16x32_bf16 v[84:87], v[208:211], v[192:195], v[84:87]
	v_mfma_f32_16x16x32_bf16 v[80:83], v[232:235], v[192:195], v[80:83]
	v_mfma_f32_16x16x32_bf16 v[68:71], v[208:211], v[200:203], v[68:71]
	v_mfma_f32_16x16x32_bf16 v[64:67], v[232:235], v[200:203], v[64:67]
	s_mov_b32 m0, s15
	s_barrier
	ds_read_b128 v[172:175], v155 offset:16384
	ds_read_b128 v[176:179], v155 offset:17408
	ds_read_b128 v[180:183], v155 offset:18432
	ds_read_b128 v[184:187], v155 offset:19456
	ds_read_b128 v[188:191], v155 offset:20480
	ds_read_b128 v[192:195], v155 offset:21504
	ds_read_b128 v[196:199], v155 offset:22528
	global_load_lds_dwordx4 v132, s[36:37]
	s_mov_b32 m0, s45
	ds_read_b128 v[200:203], v155 offset:23552
	global_load_lds_dwordx4 v130, s[36:37]
	s_barrier
	s_waitcnt lgkmcnt(0)
	v_mfma_f32_16x16x32_bf16 v[60:63], v[156:159], v[172:175], v[60:63]
	v_mfma_f32_16x16x32_bf16 v[56:59], v[164:167], v[172:175], v[56:59]
	v_mfma_f32_16x16x32_bf16 v[44:47], v[156:159], v[180:183], v[44:47]
	v_mfma_f32_16x16x32_bf16 v[40:43], v[164:167], v[180:183], v[40:43]
	v_mfma_f32_16x16x32_bf16 v[28:31], v[156:159], v[188:191], v[28:31]
	v_mfma_f32_16x16x32_bf16 v[24:27], v[164:167], v[188:191], v[24:27]
	v_mfma_f32_16x16x32_bf16 v[12:15], v[156:159], v[196:199], v[12:15]
	v_mfma_f32_16x16x32_bf16 v[8:11], v[164:167], v[196:199], v[8:11]
	v_mfma_f32_16x16x32_bf16 v[60:63], v[160:163], v[176:179], v[60:63]
	v_mfma_f32_16x16x32_bf16 v[56:59], v[168:171], v[176:179], v[56:59]
	v_mfma_f32_16x16x32_bf16 v[44:47], v[160:163], v[184:187], v[44:47]
	v_mfma_f32_16x16x32_bf16 v[40:43], v[168:171], v[184:187], v[40:43]
	v_mfma_f32_16x16x32_bf16 v[28:31], v[160:163], v[192:195], v[28:31]
	v_mfma_f32_16x16x32_bf16 v[24:27], v[168:171], v[192:195], v[24:27]
	v_mfma_f32_16x16x32_bf16 v[12:15], v[160:163], v[200:203], v[12:15]
	v_mfma_f32_16x16x32_bf16 v[8:11], v[168:171], v[200:203], v[8:11]
	s_barrier
	s_add_i32 s2, s30, s44
	s_mov_b32 m0, s2
	s_add_u32 s18, s0, 0x40000
	s_addc_u32 s19, s1, 0
	global_load_lds_dwordx4 v140, s[18:19]
	s_add_i32 m0, s2, 0x2000
	s_nop 0
	global_load_lds_dwordx4 v128, s[18:19]
	s_waitcnt vmcnt(6)
	s_barrier
	v_mfma_f32_16x16x32_bf16 v[52:55], v[204:207], v[172:175], v[52:55]
	v_mfma_f32_16x16x32_bf16 v[48:51], v[228:231], v[172:175], v[48:51]
	v_mfma_f32_16x16x32_bf16 v[36:39], v[204:207], v[180:183], v[36:39]
	v_mfma_f32_16x16x32_bf16 v[32:35], v[228:231], v[180:183], v[32:35]
	v_mfma_f32_16x16x32_bf16 v[20:23], v[204:207], v[188:191], v[20:23]
	v_mfma_f32_16x16x32_bf16 v[16:19], v[228:231], v[188:191], v[16:19]
	v_mfma_f32_16x16x32_bf16 v[4:7], v[204:207], v[196:199], v[4:7]
	v_mfma_f32_16x16x32_bf16 v[0:3], v[228:231], v[196:199], v[0:3]
	v_mfma_f32_16x16x32_bf16 v[52:55], v[208:211], v[176:179], v[52:55]
	v_mfma_f32_16x16x32_bf16 v[48:51], v[232:235], v[176:179], v[48:51]
	v_mfma_f32_16x16x32_bf16 v[36:39], v[208:211], v[184:187], v[36:39]
	v_mfma_f32_16x16x32_bf16 v[32:35], v[232:235], v[184:187], v[32:35]
	v_mfma_f32_16x16x32_bf16 v[20:23], v[208:211], v[192:195], v[20:23]
	v_mfma_f32_16x16x32_bf16 v[16:19], v[232:235], v[192:195], v[16:19]
	v_mfma_f32_16x16x32_bf16 v[4:7], v[208:211], v[200:203], v[4:7]
	v_mfma_f32_16x16x32_bf16 v[0:3], v[232:235], v[200:203], v[0:3]
	s_add_i32 s2, 0, 0x18000
	s_barrier
	ds_read_b128 v[156:159], v238
	ds_read_b128 v[160:163], v238 offset:1024
	ds_read_b128 v[164:167], v238 offset:2048
	ds_read_b128 v[168:171], v238 offset:3072
	s_add_u32 s18, s36, 0x40000
	s_addc_u32 s19, s37, 0
	s_mov_b32 m0, s46
	ds_read_b128 v[172:175], v155 offset:32768
	ds_read_b128 v[176:179], v155 offset:33792
	ds_read_b128 v[180:183], v155 offset:34816
	ds_read_b128 v[184:187], v155 offset:35840
	ds_read_b128 v[188:191], v155 offset:36864
	ds_read_b128 v[192:195], v155 offset:37888
	ds_read_b128 v[196:199], v155 offset:38912
	global_load_lds_dwordx4 v132, s[18:19]
	s_mov_b32 m0, s48
	ds_read_b128 v[200:203], v155 offset:39936
	global_load_lds_dwordx4 v130, s[18:19]
	s_waitcnt lgkmcnt(8)
	s_barrier
	s_waitcnt lgkmcnt(0)
	v_mfma_f32_16x16x32_bf16 v[124:127], v[156:159], v[172:175], v[124:127]
	v_mfma_f32_16x16x32_bf16 v[120:123], v[164:167], v[172:175], v[120:123]
	v_mfma_f32_16x16x32_bf16 v[108:111], v[156:159], v[180:183], v[108:111]
	v_mfma_f32_16x16x32_bf16 v[104:107], v[164:167], v[180:183], v[104:107]
	v_mfma_f32_16x16x32_bf16 v[92:95], v[156:159], v[188:191], v[92:95]
	v_mfma_f32_16x16x32_bf16 v[88:91], v[164:167], v[188:191], v[88:91]
	v_mfma_f32_16x16x32_bf16 v[76:79], v[156:159], v[196:199], v[76:79]
	v_mfma_f32_16x16x32_bf16 v[72:75], v[164:167], v[196:199], v[72:75]
	v_mfma_f32_16x16x32_bf16 v[124:127], v[160:163], v[176:179], v[124:127]
	v_mfma_f32_16x16x32_bf16 v[120:123], v[168:171], v[176:179], v[120:123]
	v_mfma_f32_16x16x32_bf16 v[108:111], v[160:163], v[184:187], v[108:111]
	v_mfma_f32_16x16x32_bf16 v[104:107], v[168:171], v[184:187], v[104:107]
	v_mfma_f32_16x16x32_bf16 v[92:95], v[160:163], v[192:195], v[92:95]
	v_mfma_f32_16x16x32_bf16 v[88:91], v[168:171], v[192:195], v[88:91]
	v_mfma_f32_16x16x32_bf16 v[76:79], v[160:163], v[200:203], v[76:79]
	v_mfma_f32_16x16x32_bf16 v[72:75], v[168:171], v[200:203], v[72:75]
	s_barrier
	s_add_i32 s18, 0, 0x1c000
	s_add_i32 s2, s2, s44
	s_mov_b32 m0, s2
	ds_read_b128 v[204:207], v239
	ds_read_b128 v[208:211], v239 offset:1024
	ds_read_b128 v[228:231], v239 offset:2048
	ds_read_b128 v[232:235], v239 offset:3072
	s_add_u32 s100, s0, 0x80
	s_addc_u32 s101, s1, 0
	global_load_lds_dwordx4 v140, s[100:101]
	s_add_i32 m0, s2, 0x2000
	s_nop 0
	global_load_lds_dwordx4 v128, s[100:101]
	s_barrier
	s_waitcnt lgkmcnt(0)
	v_mfma_f32_16x16x32_bf16 v[116:119], v[204:207], v[172:175], v[116:119]
	v_mfma_f32_16x16x32_bf16 v[112:115], v[228:231], v[172:175], v[112:115]
	v_mfma_f32_16x16x32_bf16 v[100:103], v[204:207], v[180:183], v[100:103]
	v_mfma_f32_16x16x32_bf16 v[96:99], v[228:231], v[180:183], v[96:99]
	v_mfma_f32_16x16x32_bf16 v[84:87], v[204:207], v[188:191], v[84:87]
	v_mfma_f32_16x16x32_bf16 v[80:83], v[228:231], v[188:191], v[80:83]
	v_mfma_f32_16x16x32_bf16 v[68:71], v[204:207], v[196:199], v[68:71]
	v_mfma_f32_16x16x32_bf16 v[64:67], v[228:231], v[196:199], v[64:67]
	v_mfma_f32_16x16x32_bf16 v[116:119], v[208:211], v[176:179], v[116:119]
	v_mfma_f32_16x16x32_bf16 v[112:115], v[232:235], v[176:179], v[112:115]
	v_mfma_f32_16x16x32_bf16 v[100:103], v[208:211], v[184:187], v[100:103]
	v_mfma_f32_16x16x32_bf16 v[96:99], v[232:235], v[184:187], v[96:99]
	v_mfma_f32_16x16x32_bf16 v[84:87], v[208:211], v[192:195], v[84:87]
	v_mfma_f32_16x16x32_bf16 v[80:83], v[232:235], v[192:195], v[80:83]
	v_mfma_f32_16x16x32_bf16 v[68:71], v[208:211], v[200:203], v[68:71]
	v_mfma_f32_16x16x32_bf16 v[64:67], v[232:235], v[200:203], v[64:67]
	s_mov_b32 m0, s57
	s_barrier
	ds_read_b128 v[172:175], v155 offset:49152
	ds_read_b128 v[176:179], v155 offset:50176
	ds_read_b128 v[180:183], v155 offset:51200
	ds_read_b128 v[184:187], v155 offset:52224
	ds_read_b128 v[188:191], v155 offset:53248
	ds_read_b128 v[192:195], v155 offset:54272
	ds_read_b128 v[196:199], v155 offset:55296
	ds_read_b128 v[200:203], v155 offset:56320
	s_add_u32 s100, s36, 0x80
	s_addc_u32 s101, s37, 0
	global_load_lds_dwordx4 v132, s[100:101]
	s_mov_b32 m0, s58
	s_nop 0
	global_load_lds_dwordx4 v130, s[100:101]
	s_barrier
	s_waitcnt lgkmcnt(0)
	v_mfma_f32_16x16x32_bf16 v[60:63], v[156:159], v[172:175], v[60:63]
	v_mfma_f32_16x16x32_bf16 v[56:59], v[164:167], v[172:175], v[56:59]
	v_mfma_f32_16x16x32_bf16 v[44:47], v[156:159], v[180:183], v[44:47]
	v_mfma_f32_16x16x32_bf16 v[40:43], v[164:167], v[180:183], v[40:43]
	v_mfma_f32_16x16x32_bf16 v[28:31], v[156:159], v[188:191], v[28:31]
	v_mfma_f32_16x16x32_bf16 v[24:27], v[164:167], v[188:191], v[24:27]
	v_mfma_f32_16x16x32_bf16 v[12:15], v[156:159], v[196:199], v[12:15]
	v_mfma_f32_16x16x32_bf16 v[8:11], v[164:167], v[196:199], v[8:11]
	v_mfma_f32_16x16x32_bf16 v[60:63], v[160:163], v[176:179], v[60:63]
	v_mfma_f32_16x16x32_bf16 v[56:59], v[168:171], v[176:179], v[56:59]
	v_mfma_f32_16x16x32_bf16 v[44:47], v[160:163], v[184:187], v[44:47]
	v_mfma_f32_16x16x32_bf16 v[40:43], v[168:171], v[184:187], v[40:43]
	v_mfma_f32_16x16x32_bf16 v[28:31], v[160:163], v[192:195], v[28:31]
	v_mfma_f32_16x16x32_bf16 v[24:27], v[168:171], v[192:195], v[24:27]
	v_mfma_f32_16x16x32_bf16 v[12:15], v[160:163], v[200:203], v[12:15]
	v_mfma_f32_16x16x32_bf16 v[8:11], v[168:171], v[200:203], v[8:11]
	s_barrier
	s_add_i32 s2, s18, s44
	s_mov_b32 m0, s2
	s_add_u32 s0, s0, 0x40080
	s_addc_u32 s1, s1, 0
	global_load_lds_dwordx4 v140, s[0:1]
	s_add_i32 m0, s2, 0x2000
	s_nop 0
	global_load_lds_dwordx4 v128, s[0:1]
	s_waitcnt vmcnt(6)
	s_barrier
	v_mfma_f32_16x16x32_bf16 v[52:55], v[204:207], v[172:175], v[52:55]
	v_mfma_f32_16x16x32_bf16 v[48:51], v[228:231], v[172:175], v[48:51]
	v_mfma_f32_16x16x32_bf16 v[36:39], v[204:207], v[180:183], v[36:39]
	v_mfma_f32_16x16x32_bf16 v[32:35], v[228:231], v[180:183], v[32:35]
	v_mfma_f32_16x16x32_bf16 v[20:23], v[204:207], v[188:191], v[20:23]
	v_mfma_f32_16x16x32_bf16 v[16:19], v[228:231], v[188:191], v[16:19]
	v_mfma_f32_16x16x32_bf16 v[4:7], v[204:207], v[196:199], v[4:7]
	v_mfma_f32_16x16x32_bf16 v[0:3], v[228:231], v[196:199], v[0:3]
	v_mfma_f32_16x16x32_bf16 v[52:55], v[208:211], v[176:179], v[52:55]
	v_mfma_f32_16x16x32_bf16 v[48:51], v[232:235], v[176:179], v[48:51]
	v_mfma_f32_16x16x32_bf16 v[36:39], v[208:211], v[184:187], v[36:39]
	v_mfma_f32_16x16x32_bf16 v[32:35], v[232:235], v[184:187], v[32:35]
	v_mfma_f32_16x16x32_bf16 v[20:23], v[208:211], v[192:195], v[20:23]
	v_mfma_f32_16x16x32_bf16 v[16:19], v[232:235], v[192:195], v[16:19]
	v_mfma_f32_16x16x32_bf16 v[4:7], v[208:211], v[200:203], v[4:7]
	v_mfma_f32_16x16x32_bf16 v[0:3], v[232:235], v[200:203], v[0:3]
	s_add_i32 s21, s21, 2
	s_add_u32 s5, s5, 0x100
	s_addc_u32 s9, s9, 0
	s_add_u32 s16, s16, 0x100
	s_addc_u32 s17, s17, 0
	s_cmp_gt_u32 s21, 13
	s_barrier
	s_cbranch_scc0 .LBB0_289
	v_mul_f32_e32 v161, 0xbfb8aa3b, v124
	v_exp_f32_e32 v161, v161
	v_mul_f32_e32 v162, 0xbfb8aa3b, v125
	v_exp_f32_e32 v162, v162
	v_mul_f32_e32 v163, 0xbfb8aa3b, v126
	v_exp_f32_e32 v163, v163
	v_mul_f32_e32 v164, 0xbfb8aa3b, v127
	v_exp_f32_e32 v164, v164
	v_mul_f32_e32 v165, 0xbfb8aa3b, v120
	v_exp_f32_e32 v165, v165
	v_mul_f32_e32 v166, 0xbfb8aa3b, v121
	v_add_f32_e32 v161, 1.0, v161
	v_exp_f32_e32 v166, v166
	v_mul_f32_e32 v167, 0xbfb8aa3b, v122
	v_rcp_f32_e32 v161, v161
	v_add_f32_e32 v162, 1.0, v162
	v_exp_f32_e32 v167, v167
	v_mul_f32_e32 v168, 0xbfb8aa3b, v123
	v_rcp_f32_e32 v162, v162
	v_add_f32_e32 v163, 1.0, v163
	v_exp_f32_e32 v168, v168
	v_rcp_f32_e32 v163, v163
	v_add_f32_e32 v164, 1.0, v164
	v_rcp_f32_e32 v164, v164
	v_add_f32_e32 v165, 1.0, v165
	v_rcp_f32_e32 v165, v165
	v_add_f32_e32 v166, 1.0, v166
	v_mul_f32_e32 v124, v124, v161
	v_rcp_f32_e32 v166, v166
	v_add_f32_e32 v167, 1.0, v167
	v_mul_f32_e32 v116, v124, v116
	v_mul_f32_e32 v124, v125, v162
	s_lshl_b32 s0, s14, 8
	v_rcp_f32_e32 v167, v167
	v_add_f32_e32 v168, 1.0, v168
	v_mul_f32_e32 v117, v124, v117
	v_mul_f32_e32 v124, v126, v163
	v_mbcnt_lo_u32_b32 v138, -1, 0
	v_mbcnt_hi_u32_b32 v138, -1, v138
	s_add_i32 s0, s0, s51
	v_rcp_f32_e32 v168, v168
	v_mul_f32_e32 v124, v124, v118
	v_mul_f32_e32 v118, v127, v164
	v_and_or_b32 v160, v138, 15, s0
	s_lshl_b32 s0, s20, 7
	v_ashrrev_i32_e32 v138, 1, v138
	v_mul_f32_e32 v125, v118, v119
	v_mul_f32_e32 v118, v120, v165
	s_or_b32 s0, s0, s52
	v_and_b32_e32 v138, -8, v138
	v_mul_f32_e32 v120, v118, v112
	v_mul_f32_e32 v112, v121, v166
	v_add_u32_e32 v156, s0, v138
	v_mul_f32_e32 v121, v112, v113
	v_mul_f32_e32 v112, v122, v167
	v_ashrrev_i32_e32 v157, 31, v156
	v_mov_b64_e32 v[138:139], s[34:35]
	v_mul_f32_e32 v122, v112, v114
	v_mul_f32_e32 v112, v123, v168
	v_mad_i64_i32 v[158:159], s[0:1], v160, s33, v[138:139]
	v_mul_f32_e32 v123, v112, v115
	v_lshlrev_b64 v[112:113], 1, v[156:157]
	v_lshl_add_u64 v[118:119], v[158:159], 0, v[112:113]
	v_cvt_pk_bf16_f32 v114, v116, v117
	v_cvt_pk_bf16_f32 v116, v120, v121
	v_cvt_pk_bf16_f32 v115, v124, v125
	v_cvt_pk_bf16_f32 v117, v122, v123
	flat_store_dwordx4 v[118:119], v[114:117]
	v_mul_f32_e32 v118, 0xbfb8aa3b, v110
	v_exp_f32_e32 v118, v118
	v_mul_f32_e32 v116, 0xbfb8aa3b, v108
	v_exp_f32_e32 v116, v116
	v_mul_f32_e32 v117, 0xbfb8aa3b, v109
	v_exp_f32_e32 v117, v117
	v_mul_f32_e32 v119, 0xbfb8aa3b, v111
	v_exp_f32_e32 v119, v119
	v_mul_f32_e32 v120, 0xbfb8aa3b, v104
	v_exp_f32_e32 v120, v120
	v_mul_f32_e32 v121, 0xbfb8aa3b, v105
	v_add_f32_e32 v116, 1.0, v116
	v_exp_f32_e32 v121, v121
	v_mul_f32_e32 v122, 0xbfb8aa3b, v106
	v_rcp_f32_e32 v116, v116
	v_add_f32_e32 v117, 1.0, v117
	v_exp_f32_e32 v122, v122
	v_mul_f32_e32 v123, 0xbfb8aa3b, v107
	v_rcp_f32_e32 v117, v117
	v_add_f32_e32 v118, 1.0, v118
	v_exp_f32_e32 v123, v123
	v_rcp_f32_e32 v118, v118
	v_add_f32_e32 v119, 1.0, v119
	v_rcp_f32_e32 v119, v119
	v_add_f32_e32 v120, 1.0, v120
	v_rcp_f32_e32 v120, v120
	v_add_f32_e32 v121, 1.0, v121
	v_mul_f32_e32 v108, v108, v116
	v_rcp_f32_e32 v121, v121
	v_add_f32_e32 v122, 1.0, v122
	v_mul_f32_e32 v108, v108, v100
	v_mul_f32_e32 v100, v109, v117
	v_rcp_f32_e32 v122, v122
	v_add_f32_e32 v123, 1.0, v123
	v_mul_f32_e32 v109, v100, v101
	v_mul_f32_e32 v100, v110, v118
	v_rcp_f32_e32 v123, v123
	v_mul_f32_e32 v102, v100, v102
	v_mul_f32_e32 v100, v111, v119
	v_mul_f32_e32 v103, v100, v103
	v_mul_f32_e32 v100, v104, v120
	v_mul_f32_e32 v104, v100, v96
	v_mul_f32_e32 v96, v105, v121
	v_or_b32_e32 v114, 16, v160
	v_mul_f32_e32 v105, v96, v97
	v_mul_f32_e32 v96, v106, v122
	v_mad_i64_i32 v[114:115], s[0:1], v114, s33, v[138:139]
	v_mul_f32_e32 v106, v96, v98
	v_mul_f32_e32 v96, v107, v123
	v_mul_f32_e32 v99, v96, v99
	v_lshl_add_u64 v[100:101], v[114:115], 0, v[112:113]
	v_cvt_pk_bf16_f32 v98, v104, v105
	v_cvt_pk_bf16_f32 v96, v108, v109
	v_cvt_pk_bf16_f32 v97, v102, v103
	v_cvt_pk_bf16_f32 v99, v106, v99
	flat_store_dwordx4 v[100:101], v[96:99]
	v_mul_f32_e32 v100, 0xbfb8aa3b, v94
	v_exp_f32_e32 v100, v100
	v_mul_f32_e32 v98, 0xbfb8aa3b, v92
	v_exp_f32_e32 v98, v98
	v_mul_f32_e32 v99, 0xbfb8aa3b, v93
	v_exp_f32_e32 v99, v99
	v_mul_f32_e32 v101, 0xbfb8aa3b, v95
	v_exp_f32_e32 v101, v101
	v_mul_f32_e32 v102, 0xbfb8aa3b, v88
	v_exp_f32_e32 v102, v102
	v_mul_f32_e32 v103, 0xbfb8aa3b, v89
	v_add_f32_e32 v98, 1.0, v98
	v_exp_f32_e32 v103, v103
	v_mul_f32_e32 v104, 0xbfb8aa3b, v90
	v_rcp_f32_e32 v98, v98
	v_add_f32_e32 v99, 1.0, v99
	v_exp_f32_e32 v104, v104
	v_mul_f32_e32 v105, 0xbfb8aa3b, v91
	v_rcp_f32_e32 v99, v99
	v_add_f32_e32 v100, 1.0, v100
	v_exp_f32_e32 v105, v105
	v_rcp_f32_e32 v100, v100
	v_add_f32_e32 v101, 1.0, v101
	v_rcp_f32_e32 v101, v101
	v_add_f32_e32 v102, 1.0, v102
	v_rcp_f32_e32 v102, v102
	v_add_f32_e32 v103, 1.0, v103
	v_mul_f32_e32 v92, v92, v98
	v_rcp_f32_e32 v103, v103
	v_add_f32_e32 v104, 1.0, v104
	v_mul_f32_e32 v92, v92, v84
	v_mul_f32_e32 v84, v93, v99
	v_rcp_f32_e32 v104, v104
	v_add_f32_e32 v105, 1.0, v105
	v_mul_f32_e32 v93, v84, v85
	v_mul_f32_e32 v84, v94, v100
	v_rcp_f32_e32 v105, v105
	v_mul_f32_e32 v86, v84, v86
	v_mul_f32_e32 v84, v95, v101
	v_mul_f32_e32 v87, v84, v87
	v_mul_f32_e32 v84, v88, v102
	v_mul_f32_e32 v88, v84, v80
	v_mul_f32_e32 v80, v89, v103
	v_or_b32_e32 v96, 32, v160
	v_mul_f32_e32 v89, v80, v81
	v_mul_f32_e32 v80, v90, v104
	v_mad_i64_i32 v[96:97], s[0:1], v96, s33, v[138:139]
	v_mul_f32_e32 v90, v80, v82
	v_mul_f32_e32 v80, v91, v105
	v_mul_f32_e32 v83, v80, v83
	v_lshl_add_u64 v[84:85], v[96:97], 0, v[112:113]
	v_cvt_pk_bf16_f32 v82, v88, v89
	v_cvt_pk_bf16_f32 v80, v92, v93
	v_cvt_pk_bf16_f32 v81, v86, v87
	v_cvt_pk_bf16_f32 v83, v90, v83
	flat_store_dwordx4 v[84:85], v[80:83]
	v_mul_f32_e32 v84, 0xbfb8aa3b, v78
	v_exp_f32_e32 v84, v84
	v_mul_f32_e32 v82, 0xbfb8aa3b, v76
	v_exp_f32_e32 v82, v82
	v_mul_f32_e32 v83, 0xbfb8aa3b, v77
	v_exp_f32_e32 v83, v83
	v_mul_f32_e32 v85, 0xbfb8aa3b, v79
	v_exp_f32_e32 v85, v85
	v_mul_f32_e32 v86, 0xbfb8aa3b, v72
	v_exp_f32_e32 v86, v86
	v_mul_f32_e32 v87, 0xbfb8aa3b, v73
	v_add_f32_e32 v82, 1.0, v82
	v_exp_f32_e32 v87, v87
	v_mul_f32_e32 v88, 0xbfb8aa3b, v74
	v_rcp_f32_e32 v82, v82
	v_add_f32_e32 v83, 1.0, v83
	v_exp_f32_e32 v88, v88
	v_mul_f32_e32 v89, 0xbfb8aa3b, v75
	v_rcp_f32_e32 v83, v83
	v_add_f32_e32 v84, 1.0, v84
	v_exp_f32_e32 v89, v89
	v_rcp_f32_e32 v84, v84
	v_add_f32_e32 v85, 1.0, v85
	v_rcp_f32_e32 v85, v85
	v_add_f32_e32 v86, 1.0, v86
	v_rcp_f32_e32 v86, v86
	v_add_f32_e32 v87, 1.0, v87
	v_mul_f32_e32 v76, v76, v82
	v_rcp_f32_e32 v87, v87
	v_add_f32_e32 v88, 1.0, v88
	v_mul_f32_e32 v76, v76, v68
	v_mul_f32_e32 v68, v77, v83
	v_rcp_f32_e32 v88, v88
	v_add_f32_e32 v89, 1.0, v89
	v_mul_f32_e32 v77, v68, v69
	v_mul_f32_e32 v68, v78, v84
	v_rcp_f32_e32 v89, v89
	v_mul_f32_e32 v70, v68, v70
	v_mul_f32_e32 v68, v79, v85
	v_mul_f32_e32 v71, v68, v71
	v_mul_f32_e32 v68, v72, v86
	v_mul_f32_e32 v72, v68, v64
	v_mul_f32_e32 v64, v73, v87
	v_or_b32_e32 v80, 48, v160
	v_mul_f32_e32 v73, v64, v65
	v_mul_f32_e32 v64, v74, v88
	v_mad_i64_i32 v[80:81], s[0:1], v80, s33, v[138:139]
	v_mul_f32_e32 v74, v64, v66
	v_mul_f32_e32 v64, v75, v89
	v_mul_f32_e32 v67, v64, v67
	v_lshl_add_u64 v[68:69], v[80:81], 0, v[112:113]
	v_cvt_pk_bf16_f32 v66, v72, v73
	v_cvt_pk_bf16_f32 v64, v76, v77
	v_cvt_pk_bf16_f32 v65, v70, v71
	v_cvt_pk_bf16_f32 v67, v74, v67
	flat_store_dwordx4 v[68:69], v[64:67]
	v_mul_f32_e32 v68, 0xbfb8aa3b, v62
	v_exp_f32_e32 v68, v68
	v_mul_f32_e32 v66, 0xbfb8aa3b, v60
	v_exp_f32_e32 v66, v66
	v_mul_f32_e32 v67, 0xbfb8aa3b, v61
	v_exp_f32_e32 v67, v67
	v_mul_f32_e32 v69, 0xbfb8aa3b, v63
	v_exp_f32_e32 v69, v69
	v_mul_f32_e32 v70, 0xbfb8aa3b, v56
	v_exp_f32_e32 v70, v70
	v_mul_f32_e32 v71, 0xbfb8aa3b, v57
	v_add_f32_e32 v66, 1.0, v66
	v_exp_f32_e32 v71, v71
	v_mul_f32_e32 v72, 0xbfb8aa3b, v58
	v_rcp_f32_e32 v66, v66
	v_add_f32_e32 v67, 1.0, v67
	v_exp_f32_e32 v72, v72
	v_mul_f32_e32 v73, 0xbfb8aa3b, v59
	v_rcp_f32_e32 v67, v67
	v_add_f32_e32 v68, 1.0, v68
	v_exp_f32_e32 v73, v73
	v_rcp_f32_e32 v68, v68
	v_add_f32_e32 v69, 1.0, v69
	v_rcp_f32_e32 v69, v69
	v_add_f32_e32 v70, 1.0, v70
	v_rcp_f32_e32 v70, v70
	v_add_f32_e32 v71, 1.0, v71
	v_mul_f32_e32 v60, v60, v66
	v_rcp_f32_e32 v71, v71
	v_add_f32_e32 v72, 1.0, v72
	v_mul_f32_e32 v60, v60, v52
	v_mul_f32_e32 v52, v61, v67
	v_rcp_f32_e32 v72, v72
	v_add_f32_e32 v73, 1.0, v73
	v_mul_f32_e32 v61, v52, v53
	v_mul_f32_e32 v52, v62, v68
	v_rcp_f32_e32 v73, v73
	v_mul_f32_e32 v54, v52, v54
	v_mul_f32_e32 v52, v63, v69
	v_mul_f32_e32 v55, v52, v55
	v_mul_f32_e32 v52, v56, v70
	v_mul_f32_e32 v56, v52, v48
	v_mul_f32_e32 v48, v57, v71
	v_add_u32_e32 v64, 0x80, v160
	v_mul_f32_e32 v57, v48, v49
	v_mul_f32_e32 v48, v58, v72
	v_mad_i64_i32 v[64:65], s[0:1], v64, s33, v[138:139]
	v_mul_f32_e32 v58, v48, v50
	v_mul_f32_e32 v48, v59, v73
	v_mul_f32_e32 v51, v48, v51
	v_lshl_add_u64 v[52:53], v[64:65], 0, v[112:113]
	v_cvt_pk_bf16_f32 v50, v56, v57
	v_cvt_pk_bf16_f32 v48, v60, v61
	v_cvt_pk_bf16_f32 v49, v54, v55
	v_cvt_pk_bf16_f32 v51, v58, v51
	flat_store_dwordx4 v[52:53], v[48:51]
	v_mul_f32_e32 v52, 0xbfb8aa3b, v46
	v_exp_f32_e32 v52, v52
	v_mul_f32_e32 v50, 0xbfb8aa3b, v44
	v_exp_f32_e32 v50, v50
	v_mul_f32_e32 v51, 0xbfb8aa3b, v45
	v_exp_f32_e32 v51, v51
	v_mul_f32_e32 v53, 0xbfb8aa3b, v47
	v_exp_f32_e32 v53, v53
	v_mul_f32_e32 v54, 0xbfb8aa3b, v40
	v_exp_f32_e32 v54, v54
	v_mul_f32_e32 v55, 0xbfb8aa3b, v41
	v_add_f32_e32 v50, 1.0, v50
	v_exp_f32_e32 v55, v55
	v_mul_f32_e32 v56, 0xbfb8aa3b, v42
	v_rcp_f32_e32 v50, v50
	v_add_f32_e32 v51, 1.0, v51
	v_exp_f32_e32 v56, v56
	v_mul_f32_e32 v57, 0xbfb8aa3b, v43
	v_rcp_f32_e32 v51, v51
	v_add_f32_e32 v52, 1.0, v52
	v_exp_f32_e32 v57, v57
	v_rcp_f32_e32 v52, v52
	v_add_f32_e32 v53, 1.0, v53
	v_rcp_f32_e32 v53, v53
	v_add_f32_e32 v54, 1.0, v54
	v_rcp_f32_e32 v54, v54
	v_add_f32_e32 v55, 1.0, v55
	v_mul_f32_e32 v44, v44, v50
	v_rcp_f32_e32 v55, v55
	v_add_f32_e32 v56, 1.0, v56
	v_mul_f32_e32 v44, v44, v36
	v_mul_f32_e32 v36, v45, v51
	v_rcp_f32_e32 v56, v56
	v_add_f32_e32 v57, 1.0, v57
	v_mul_f32_e32 v45, v36, v37
	v_mul_f32_e32 v36, v46, v52
	v_rcp_f32_e32 v57, v57
	v_mul_f32_e32 v38, v36, v38
	v_mul_f32_e32 v36, v47, v53
	v_mul_f32_e32 v39, v36, v39
	v_mul_f32_e32 v36, v40, v54
	v_mul_f32_e32 v40, v36, v32
	v_mul_f32_e32 v32, v41, v55
	v_add_u32_e32 v48, 0x90, v160
	v_mul_f32_e32 v41, v32, v33
	v_mul_f32_e32 v32, v42, v56
	v_mad_i64_i32 v[48:49], s[0:1], v48, s33, v[138:139]
	v_mul_f32_e32 v42, v32, v34
	v_mul_f32_e32 v32, v43, v57
	v_mul_f32_e32 v35, v32, v35
	v_lshl_add_u64 v[36:37], v[48:49], 0, v[112:113]
	v_cvt_pk_bf16_f32 v34, v40, v41
	v_cvt_pk_bf16_f32 v32, v44, v45
	v_cvt_pk_bf16_f32 v33, v38, v39
	v_cvt_pk_bf16_f32 v35, v42, v35
	flat_store_dwordx4 v[36:37], v[32:35]
	v_mul_f32_e32 v36, 0xbfb8aa3b, v30
	v_exp_f32_e32 v36, v36
	v_mul_f32_e32 v34, 0xbfb8aa3b, v28
	v_exp_f32_e32 v34, v34
	v_mul_f32_e32 v35, 0xbfb8aa3b, v29
	v_exp_f32_e32 v35, v35
	v_mul_f32_e32 v37, 0xbfb8aa3b, v31
	v_exp_f32_e32 v37, v37
	v_mul_f32_e32 v38, 0xbfb8aa3b, v24
	v_exp_f32_e32 v38, v38
	v_mul_f32_e32 v39, 0xbfb8aa3b, v25
	v_add_f32_e32 v34, 1.0, v34
	v_exp_f32_e32 v39, v39
	v_mul_f32_e32 v40, 0xbfb8aa3b, v26
	v_rcp_f32_e32 v34, v34
	v_add_f32_e32 v35, 1.0, v35
	v_exp_f32_e32 v40, v40
	v_mul_f32_e32 v41, 0xbfb8aa3b, v27
	v_rcp_f32_e32 v35, v35
	v_add_f32_e32 v36, 1.0, v36
	v_exp_f32_e32 v41, v41
	v_rcp_f32_e32 v36, v36
	v_add_f32_e32 v37, 1.0, v37
	v_rcp_f32_e32 v37, v37
	v_add_f32_e32 v38, 1.0, v38
	v_rcp_f32_e32 v38, v38
	v_add_f32_e32 v39, 1.0, v39
	v_mul_f32_e32 v28, v28, v34
	v_rcp_f32_e32 v39, v39
	v_add_f32_e32 v40, 1.0, v40
	v_mul_f32_e32 v28, v28, v20
	v_mul_f32_e32 v20, v29, v35
	v_rcp_f32_e32 v40, v40
	v_add_f32_e32 v41, 1.0, v41
	v_mul_f32_e32 v29, v20, v21
	v_mul_f32_e32 v20, v30, v36
	v_rcp_f32_e32 v41, v41
	v_mul_f32_e32 v22, v20, v22
	v_mul_f32_e32 v20, v31, v37
	v_mul_f32_e32 v23, v20, v23
	v_mul_f32_e32 v20, v24, v38
	v_mul_f32_e32 v24, v20, v16
	v_mul_f32_e32 v16, v25, v39
	v_add_u32_e32 v32, 0xa0, v160
	v_mul_f32_e32 v25, v16, v17
	v_mul_f32_e32 v16, v26, v40
	v_mad_i64_i32 v[32:33], s[0:1], v32, s33, v[138:139]
	v_mul_f32_e32 v26, v16, v18
	v_mul_f32_e32 v16, v27, v41
	v_mul_f32_e32 v19, v16, v19
	v_lshl_add_u64 v[20:21], v[32:33], 0, v[112:113]
	v_cvt_pk_bf16_f32 v18, v24, v25
	v_cvt_pk_bf16_f32 v16, v28, v29
	v_cvt_pk_bf16_f32 v17, v22, v23
	v_cvt_pk_bf16_f32 v19, v26, v19
	flat_store_dwordx4 v[20:21], v[16:19]
	v_mul_f32_e32 v20, 0xbfb8aa3b, v14
	v_exp_f32_e32 v20, v20
	v_mul_f32_e32 v18, 0xbfb8aa3b, v12
	v_exp_f32_e32 v18, v18
	v_mul_f32_e32 v19, 0xbfb8aa3b, v13
	v_exp_f32_e32 v19, v19
	v_mul_f32_e32 v21, 0xbfb8aa3b, v15
	v_exp_f32_e32 v21, v21
	v_mul_f32_e32 v22, 0xbfb8aa3b, v8
	v_exp_f32_e32 v22, v22
	v_mul_f32_e32 v23, 0xbfb8aa3b, v9
	v_add_f32_e32 v18, 1.0, v18
	v_exp_f32_e32 v23, v23
	v_mul_f32_e32 v24, 0xbfb8aa3b, v10
	v_rcp_f32_e32 v18, v18
	v_add_f32_e32 v19, 1.0, v19
	v_exp_f32_e32 v24, v24
	v_mul_f32_e32 v25, 0xbfb8aa3b, v11
	v_rcp_f32_e32 v19, v19
	v_add_f32_e32 v20, 1.0, v20
	v_exp_f32_e32 v25, v25
	v_rcp_f32_e32 v20, v20
	v_add_f32_e32 v21, 1.0, v21
	v_rcp_f32_e32 v21, v21
	v_add_f32_e32 v22, 1.0, v22
	v_rcp_f32_e32 v22, v22
	v_add_f32_e32 v23, 1.0, v23
	v_mul_f32_e32 v12, v12, v18
	v_rcp_f32_e32 v23, v23
	v_add_f32_e32 v24, 1.0, v24
	v_mul_f32_e32 v12, v12, v4
	v_mul_f32_e32 v4, v13, v19
	v_rcp_f32_e32 v24, v24
	v_add_f32_e32 v25, 1.0, v25
	v_mul_f32_e32 v13, v4, v5
	v_mul_f32_e32 v4, v14, v20
	v_rcp_f32_e32 v25, v25
	v_mul_f32_e32 v6, v4, v6
	v_mul_f32_e32 v4, v15, v21
	v_mul_f32_e32 v7, v4, v7
	v_mul_f32_e32 v4, v8, v22
	v_mul_f32_e32 v8, v4, v0
	v_mul_f32_e32 v0, v9, v23
	v_add_u32_e32 v16, 0xb0, v160
	v_mul_f32_e32 v9, v0, v1
	v_mul_f32_e32 v0, v10, v24
	v_mad_i64_i32 v[16:17], s[0:1], v16, s33, v[138:139]
	v_mul_f32_e32 v10, v0, v2
	v_mul_f32_e32 v0, v11, v25
	v_mul_f32_e32 v3, v0, v3
	v_lshl_add_u64 v[4:5], v[16:17], 0, v[112:113]
	s_and_b64 vcc, exec, s[6:7]
	s_mov_b32 s20, s8
	s_mov_b32 s14, s4
	s_mov_b64 s[16:17], s[12:13]
	s_mov_b64 s[0:1], s[10:11]
	v_cvt_pk_bf16_f32 v0, v12, v13
	v_cvt_pk_bf16_f32 v1, v6, v7
	v_cvt_pk_bf16_f32 v2, v8, v9
	v_cvt_pk_bf16_f32 v3, v10, v3
	flat_store_dwordx4 v[4:5], v[0:3]
	s_cbranch_vccz .LBB0_286
	s_waitcnt vmcnt(0)
	s_cmpk_gt_u32 s39, 0xff
	v_readlane_b32 s51, v252, 10
	s_cbranch_scc1 .LBB0_293
	s_barrier

.LBB0_321:
	s_add_u32 s0, s16, 0xfffc0080
	s_addc_u32 s1, s17, -1
	s_add_i32 s2, 0, 0x10000
	ds_read_b128 v[156:159], v236
	ds_read_b128 v[160:163], v236 offset:1024
	ds_read_b128 v[164:167], v236 offset:2048
	ds_read_b128 v[168:171], v236 offset:3072
	s_cmp_eq_u32 s59, 12
	s_cselect_b32 s41, s11, s1
	s_cselect_b32 s40, s10, s0
	s_cselect_b32 s1, s13, s9
	s_cselect_b32 s0, s12, s5
	s_add_i32 m0, s15, 0xc000
	ds_read_b128 v[172:175], v155
	ds_read_b128 v[176:179], v155 offset:1024
	ds_read_b128 v[180:183], v155 offset:2048
	ds_read_b128 v[184:187], v155 offset:3072
	ds_read_b128 v[188:191], v155 offset:4096
	ds_read_b128 v[192:195], v155 offset:5120
	ds_read_b128 v[196:199], v155 offset:6144
	global_load_lds_dwordx4 v136, s[16:17]
	s_add_i32 m0, s15, 0xe000
	ds_read_b128 v[200:203], v155 offset:7168
	global_load_lds_dwordx4 v134, s[16:17]
	s_waitcnt lgkmcnt(8)
	s_barrier
	s_waitcnt lgkmcnt(0)
	v_mfma_f32_16x16x32_bf16 v[124:127], v[156:159], v[172:175], v[124:127]
	v_mfma_f32_16x16x32_bf16 v[120:123], v[164:167], v[172:175], v[120:123]
	v_mfma_f32_16x16x32_bf16 v[116:119], v[156:159], v[180:183], v[116:119]
	v_mfma_f32_16x16x32_bf16 v[108:111], v[164:167], v[180:183], v[108:111]
	v_mfma_f32_16x16x32_bf16 v[100:103], v[156:159], v[188:191], v[100:103]
	v_mfma_f32_16x16x32_bf16 v[92:95], v[164:167], v[188:191], v[92:95]
	v_mfma_f32_16x16x32_bf16 v[84:87], v[156:159], v[196:199], v[84:87]
	v_mfma_f32_16x16x32_bf16 v[76:79], v[164:167], v[196:199], v[76:79]
	v_mfma_f32_16x16x32_bf16 v[124:127], v[160:163], v[176:179], v[124:127]
	v_mfma_f32_16x16x32_bf16 v[120:123], v[168:171], v[176:179], v[120:123]
	v_mfma_f32_16x16x32_bf16 v[116:119], v[160:163], v[184:187], v[116:119]
	v_mfma_f32_16x16x32_bf16 v[108:111], v[168:171], v[184:187], v[108:111]
	v_mfma_f32_16x16x32_bf16 v[100:103], v[160:163], v[192:195], v[100:103]
	v_mfma_f32_16x16x32_bf16 v[92:95], v[168:171], v[192:195], v[92:95]
	v_mfma_f32_16x16x32_bf16 v[84:87], v[160:163], v[200:203], v[84:87]
	v_mfma_f32_16x16x32_bf16 v[76:79], v[168:171], v[200:203], v[76:79]
	s_barrier
	s_add_i32 s30, 0, 0x14000
	s_add_i32 s2, s2, s45
	ds_read_b128 v[204:207], v237
	ds_read_b128 v[208:211], v237 offset:1024
	s_mov_b32 m0, s2
	ds_read_b128 v[228:231], v237 offset:2048
	global_load_lds_dwordx4 v140, s[0:1]
	s_add_i32 m0, s2, 0x2000
	ds_read_b128 v[232:235], v237 offset:3072
	global_load_lds_dwordx4 v132, s[0:1]
	s_barrier
	s_waitcnt lgkmcnt(0)
	v_mfma_f32_16x16x32_bf16 v[112:115], v[204:207], v[172:175], v[112:115]
	v_mfma_f32_16x16x32_bf16 v[104:107], v[228:231], v[172:175], v[104:107]
	v_mfma_f32_16x16x32_bf16 v[96:99], v[204:207], v[180:183], v[96:99]
	v_mfma_f32_16x16x32_bf16 v[88:91], v[228:231], v[180:183], v[88:91]
	v_mfma_f32_16x16x32_bf16 v[80:83], v[204:207], v[188:191], v[80:83]
	v_mfma_f32_16x16x32_bf16 v[72:75], v[228:231], v[188:191], v[72:75]
	v_mfma_f32_16x16x32_bf16 v[68:71], v[204:207], v[196:199], v[68:71]
	v_mfma_f32_16x16x32_bf16 v[64:67], v[228:231], v[196:199], v[64:67]
	v_mfma_f32_16x16x32_bf16 v[112:115], v[208:211], v[176:179], v[112:115]
	v_mfma_f32_16x16x32_bf16 v[104:107], v[232:235], v[176:179], v[104:107]
	v_mfma_f32_16x16x32_bf16 v[96:99], v[208:211], v[184:187], v[96:99]
	v_mfma_f32_16x16x32_bf16 v[88:91], v[232:235], v[184:187], v[88:91]
	v_mfma_f32_16x16x32_bf16 v[80:83], v[208:211], v[192:195], v[80:83]
	v_mfma_f32_16x16x32_bf16 v[72:75], v[232:235], v[192:195], v[72:75]
	v_mfma_f32_16x16x32_bf16 v[68:71], v[208:211], v[200:203], v[68:71]
	v_mfma_f32_16x16x32_bf16 v[64:67], v[232:235], v[200:203], v[64:67]
	s_mov_b32 m0, s15
	s_barrier
	ds_read_b128 v[172:175], v155 offset:16384
	ds_read_b128 v[176:179], v155 offset:17408
	ds_read_b128 v[180:183], v155 offset:18432
	ds_read_b128 v[184:187], v155 offset:19456
	ds_read_b128 v[188:191], v155 offset:20480
	ds_read_b128 v[192:195], v155 offset:21504
	ds_read_b128 v[196:199], v155 offset:22528
	global_load_lds_dwordx4 v128, s[40:41]
	s_mov_b32 m0, s46
	ds_read_b128 v[200:203], v155 offset:23552
	global_load_lds_dwordx4 v130, s[40:41]
	s_barrier
	s_waitcnt lgkmcnt(0)
	v_mfma_f32_16x16x32_bf16 v[60:63], v[156:159], v[172:175], v[60:63]
	v_mfma_f32_16x16x32_bf16 v[56:59], v[164:167], v[172:175], v[56:59]
	v_mfma_f32_16x16x32_bf16 v[52:55], v[156:159], v[180:183], v[52:55]
	v_mfma_f32_16x16x32_bf16 v[44:47], v[164:167], v[180:183], v[44:47]
	v_mfma_f32_16x16x32_bf16 v[36:39], v[156:159], v[188:191], v[36:39]
	v_mfma_f32_16x16x32_bf16 v[28:31], v[164:167], v[188:191], v[28:31]
	v_mfma_f32_16x16x32_bf16 v[20:23], v[156:159], v[196:199], v[20:23]
	v_mfma_f32_16x16x32_bf16 v[12:15], v[164:167], v[196:199], v[12:15]
	v_mfma_f32_16x16x32_bf16 v[60:63], v[160:163], v[176:179], v[60:63]
	v_mfma_f32_16x16x32_bf16 v[56:59], v[168:171], v[176:179], v[56:59]
	v_mfma_f32_16x16x32_bf16 v[52:55], v[160:163], v[184:187], v[52:55]
	v_mfma_f32_16x16x32_bf16 v[44:47], v[168:171], v[184:187], v[44:47]
	v_mfma_f32_16x16x32_bf16 v[36:39], v[160:163], v[192:195], v[36:39]
	v_mfma_f32_16x16x32_bf16 v[28:31], v[168:171], v[192:195], v[28:31]
	v_mfma_f32_16x16x32_bf16 v[20:23], v[160:163], v[200:203], v[20:23]
	v_mfma_f32_16x16x32_bf16 v[12:15], v[168:171], v[200:203], v[12:15]
	s_barrier
	s_add_i32 s2, s30, s45
	s_mov_b32 m0, s2
	s_add_u32 s18, s0, 0x40000
	s_addc_u32 s19, s1, 0
	global_load_lds_dwordx4 v140, s[18:19]
	s_add_i32 m0, s2, 0x2000
	s_nop 0
	global_load_lds_dwordx4 v132, s[18:19]
	s_waitcnt vmcnt(6)
	s_barrier
	v_mfma_f32_16x16x32_bf16 v[48:51], v[204:207], v[172:175], v[48:51]
	v_mfma_f32_16x16x32_bf16 v[40:43], v[228:231], v[172:175], v[40:43]
	v_mfma_f32_16x16x32_bf16 v[32:35], v[204:207], v[180:183], v[32:35]
	v_mfma_f32_16x16x32_bf16 v[24:27], v[228:231], v[180:183], v[24:27]
	v_mfma_f32_16x16x32_bf16 v[16:19], v[204:207], v[188:191], v[16:19]
	v_mfma_f32_16x16x32_bf16 v[8:11], v[228:231], v[188:191], v[8:11]
	v_mfma_f32_16x16x32_bf16 v[4:7], v[204:207], v[196:199], v[4:7]
	v_mfma_f32_16x16x32_bf16 v[0:3], v[228:231], v[196:199], v[0:3]
	v_mfma_f32_16x16x32_bf16 v[48:51], v[208:211], v[176:179], v[48:51]
	v_mfma_f32_16x16x32_bf16 v[40:43], v[232:235], v[176:179], v[40:43]
	v_mfma_f32_16x16x32_bf16 v[32:35], v[208:211], v[184:187], v[32:35]
	v_mfma_f32_16x16x32_bf16 v[24:27], v[232:235], v[184:187], v[24:27]
	v_mfma_f32_16x16x32_bf16 v[16:19], v[208:211], v[192:195], v[16:19]
	v_mfma_f32_16x16x32_bf16 v[8:11], v[232:235], v[192:195], v[8:11]
	v_mfma_f32_16x16x32_bf16 v[4:7], v[208:211], v[200:203], v[4:7]
	v_mfma_f32_16x16x32_bf16 v[0:3], v[232:235], v[200:203], v[0:3]
	s_add_i32 s2, 0, 0x18000
	s_barrier
	ds_read_b128 v[156:159], v238
	ds_read_b128 v[160:163], v238 offset:1024
	ds_read_b128 v[164:167], v238 offset:2048
	ds_read_b128 v[168:171], v238 offset:3072
	s_add_u32 s18, s40, 0x40000
	s_addc_u32 s19, s41, 0
	s_mov_b32 m0, s48
	ds_read_b128 v[172:175], v155 offset:32768
	ds_read_b128 v[176:179], v155 offset:33792
	ds_read_b128 v[180:183], v155 offset:34816
	ds_read_b128 v[184:187], v155 offset:35840
	ds_read_b128 v[188:191], v155 offset:36864
	ds_read_b128 v[192:195], v155 offset:37888
	ds_read_b128 v[196:199], v155 offset:38912
	global_load_lds_dwordx4 v128, s[18:19]
	s_mov_b32 m0, s49
	ds_read_b128 v[200:203], v155 offset:39936
	global_load_lds_dwordx4 v130, s[18:19]
	s_waitcnt lgkmcnt(8)
	s_barrier
	s_waitcnt lgkmcnt(0)
	v_mfma_f32_16x16x32_bf16 v[124:127], v[156:159], v[172:175], v[124:127]
	v_mfma_f32_16x16x32_bf16 v[120:123], v[164:167], v[172:175], v[120:123]
	v_mfma_f32_16x16x32_bf16 v[116:119], v[156:159], v[180:183], v[116:119]
	v_mfma_f32_16x16x32_bf16 v[108:111], v[164:167], v[180:183], v[108:111]
	v_mfma_f32_16x16x32_bf16 v[100:103], v[156:159], v[188:191], v[100:103]
	v_mfma_f32_16x16x32_bf16 v[92:95], v[164:167], v[188:191], v[92:95]
	v_mfma_f32_16x16x32_bf16 v[84:87], v[156:159], v[196:199], v[84:87]
	v_mfma_f32_16x16x32_bf16 v[76:79], v[164:167], v[196:199], v[76:79]
	v_mfma_f32_16x16x32_bf16 v[124:127], v[160:163], v[176:179], v[124:127]
	v_mfma_f32_16x16x32_bf16 v[120:123], v[168:171], v[176:179], v[120:123]
	v_mfma_f32_16x16x32_bf16 v[116:119], v[160:163], v[184:187], v[116:119]
	v_mfma_f32_16x16x32_bf16 v[108:111], v[168:171], v[184:187], v[108:111]
	v_mfma_f32_16x16x32_bf16 v[100:103], v[160:163], v[192:195], v[100:103]
	v_mfma_f32_16x16x32_bf16 v[92:95], v[168:171], v[192:195], v[92:95]
	v_mfma_f32_16x16x32_bf16 v[84:87], v[160:163], v[200:203], v[84:87]
	v_mfma_f32_16x16x32_bf16 v[76:79], v[168:171], v[200:203], v[76:79]
	s_barrier
	s_add_i32 s18, 0, 0x1c000
	s_add_i32 s2, s2, s45
	s_mov_b32 m0, s2
	ds_read_b128 v[204:207], v239
	ds_read_b128 v[208:211], v239 offset:1024
	ds_read_b128 v[228:231], v239 offset:2048
	ds_read_b128 v[232:235], v239 offset:3072
	s_add_u32 s100, s0, 0x80
	s_addc_u32 s101, s1, 0
	global_load_lds_dwordx4 v140, s[100:101]
	s_add_i32 m0, s2, 0x2000
	s_nop 0
	global_load_lds_dwordx4 v132, s[100:101]
	s_barrier
	s_waitcnt lgkmcnt(0)
	v_mfma_f32_16x16x32_bf16 v[112:115], v[204:207], v[172:175], v[112:115]
	v_mfma_f32_16x16x32_bf16 v[104:107], v[228:231], v[172:175], v[104:107]
	v_mfma_f32_16x16x32_bf16 v[96:99], v[204:207], v[180:183], v[96:99]
	v_mfma_f32_16x16x32_bf16 v[88:91], v[228:231], v[180:183], v[88:91]
	v_mfma_f32_16x16x32_bf16 v[80:83], v[204:207], v[188:191], v[80:83]
	v_mfma_f32_16x16x32_bf16 v[72:75], v[228:231], v[188:191], v[72:75]
	v_mfma_f32_16x16x32_bf16 v[68:71], v[204:207], v[196:199], v[68:71]
	v_mfma_f32_16x16x32_bf16 v[64:67], v[228:231], v[196:199], v[64:67]
	v_mfma_f32_16x16x32_bf16 v[112:115], v[208:211], v[176:179], v[112:115]
	v_mfma_f32_16x16x32_bf16 v[104:107], v[232:235], v[176:179], v[104:107]
	v_mfma_f32_16x16x32_bf16 v[96:99], v[208:211], v[184:187], v[96:99]
	v_mfma_f32_16x16x32_bf16 v[88:91], v[232:235], v[184:187], v[88:91]
	v_mfma_f32_16x16x32_bf16 v[80:83], v[208:211], v[192:195], v[80:83]
	v_mfma_f32_16x16x32_bf16 v[72:75], v[232:235], v[192:195], v[72:75]
	v_mfma_f32_16x16x32_bf16 v[68:71], v[208:211], v[200:203], v[68:71]
	v_mfma_f32_16x16x32_bf16 v[64:67], v[232:235], v[200:203], v[64:67]
	s_mov_b32 m0, s57
	s_barrier
	ds_read_b128 v[172:175], v155 offset:49152
	ds_read_b128 v[176:179], v155 offset:50176
	ds_read_b128 v[180:183], v155 offset:51200
	ds_read_b128 v[184:187], v155 offset:52224
	ds_read_b128 v[188:191], v155 offset:53248
	ds_read_b128 v[192:195], v155 offset:54272
	ds_read_b128 v[196:199], v155 offset:55296
	ds_read_b128 v[200:203], v155 offset:56320
	s_add_u32 s100, s40, 0x80
	s_addc_u32 s101, s41, 0
	global_load_lds_dwordx4 v128, s[100:101]
	s_mov_b32 m0, s58
	s_nop 0
	global_load_lds_dwordx4 v130, s[100:101]
	s_barrier
	s_waitcnt lgkmcnt(0)
	v_mfma_f32_16x16x32_bf16 v[60:63], v[156:159], v[172:175], v[60:63]
	v_mfma_f32_16x16x32_bf16 v[56:59], v[164:167], v[172:175], v[56:59]
	v_mfma_f32_16x16x32_bf16 v[52:55], v[156:159], v[180:183], v[52:55]
	v_mfma_f32_16x16x32_bf16 v[44:47], v[164:167], v[180:183], v[44:47]
	v_mfma_f32_16x16x32_bf16 v[36:39], v[156:159], v[188:191], v[36:39]
	v_mfma_f32_16x16x32_bf16 v[28:31], v[164:167], v[188:191], v[28:31]
	v_mfma_f32_16x16x32_bf16 v[20:23], v[156:159], v[196:199], v[20:23]
	v_mfma_f32_16x16x32_bf16 v[12:15], v[164:167], v[196:199], v[12:15]
	v_mfma_f32_16x16x32_bf16 v[60:63], v[160:163], v[176:179], v[60:63]
	v_mfma_f32_16x16x32_bf16 v[56:59], v[168:171], v[176:179], v[56:59]
	v_mfma_f32_16x16x32_bf16 v[52:55], v[160:163], v[184:187], v[52:55]
	v_mfma_f32_16x16x32_bf16 v[44:47], v[168:171], v[184:187], v[44:47]
	v_mfma_f32_16x16x32_bf16 v[36:39], v[160:163], v[192:195], v[36:39]
	v_mfma_f32_16x16x32_bf16 v[28:31], v[168:171], v[192:195], v[28:31]
	v_mfma_f32_16x16x32_bf16 v[20:23], v[160:163], v[200:203], v[20:23]
	v_mfma_f32_16x16x32_bf16 v[12:15], v[168:171], v[200:203], v[12:15]
	s_barrier
	s_add_i32 s2, s18, s45
	s_mov_b32 m0, s2
	s_add_u32 s0, s0, 0x40080
	s_addc_u32 s1, s1, 0
	global_load_lds_dwordx4 v140, s[0:1]
	s_add_i32 m0, s2, 0x2000
	s_nop 0
	global_load_lds_dwordx4 v132, s[0:1]
	s_waitcnt vmcnt(6)
	s_barrier
	v_mfma_f32_16x16x32_bf16 v[48:51], v[204:207], v[172:175], v[48:51]
	v_mfma_f32_16x16x32_bf16 v[40:43], v[228:231], v[172:175], v[40:43]
	v_mfma_f32_16x16x32_bf16 v[32:35], v[204:207], v[180:183], v[32:35]
	v_mfma_f32_16x16x32_bf16 v[24:27], v[228:231], v[180:183], v[24:27]
	v_mfma_f32_16x16x32_bf16 v[16:19], v[204:207], v[188:191], v[16:19]
	v_mfma_f32_16x16x32_bf16 v[8:11], v[228:231], v[188:191], v[8:11]
	v_mfma_f32_16x16x32_bf16 v[4:7], v[204:207], v[196:199], v[4:7]
	v_mfma_f32_16x16x32_bf16 v[0:3], v[228:231], v[196:199], v[0:3]
	v_mfma_f32_16x16x32_bf16 v[48:51], v[208:211], v[176:179], v[48:51]
	v_mfma_f32_16x16x32_bf16 v[40:43], v[232:235], v[176:179], v[40:43]
	v_mfma_f32_16x16x32_bf16 v[32:35], v[208:211], v[184:187], v[32:35]
	v_mfma_f32_16x16x32_bf16 v[24:27], v[232:235], v[184:187], v[24:27]
	v_mfma_f32_16x16x32_bf16 v[16:19], v[208:211], v[192:195], v[16:19]
	v_mfma_f32_16x16x32_bf16 v[8:11], v[232:235], v[192:195], v[8:11]
	v_mfma_f32_16x16x32_bf16 v[4:7], v[208:211], v[200:203], v[4:7]
	v_mfma_f32_16x16x32_bf16 v[0:3], v[232:235], v[200:203], v[0:3]
	s_add_i32 s59, s59, 2
	s_add_u32 s5, s5, 0x100
	s_addc_u32 s9, s9, 0
	s_add_u32 s16, s16, 0x100
	s_addc_u32 s17, s17, 0
	s_cmp_gt_u32 s59, 13
	s_barrier
	s_cbranch_scc0 .LBB0_321
	s_lshl_b32 s0, s14, 8
	v_mbcnt_lo_u32_b32 v139, -1, 0
	v_mbcnt_hi_u32_b32 v139, -1, v139
	s_lshl_b32 s1, s21, 8
	v_ashrrev_i32_e32 v138, 1, v139
	s_add_i32 s0, s0, s51
	v_and_b32_e32 v138, -8, v138
	s_or_b32 s1, s1, s52
	v_and_or_b32 v156, v139, 15, s0
	v_add_u32_e32 v138, s1, v138
	v_ashrrev_i32_e32 v157, 31, v156
	v_ashrrev_i32_e32 v139, 31, v138
	v_lshlrev_b64 v[158:159], 11, v[156:157]
	v_lshl_add_u64 v[158:159], s[26:27], 0, v[158:159]
	v_lshlrev_b64 v[160:161], 1, v[138:139]
	v_lshl_add_u64 v[138:139], v[158:159], 0, v[160:161]
	v_cvt_pk_bf16_f32 v60, v60, v61
	v_cvt_pk_bf16_f32 v61, v62, v63
	v_cvt_pk_bf16_f32 v62, v56, v57
	v_add_co_u32_e32 v56, vcc, s31, v138
	v_cvt_pk_bf16_f32 v112, v112, v113
	v_cvt_pk_bf16_f32 v113, v114, v115
	v_cvt_pk_bf16_f32 v114, v104, v105
	v_or_b32_e32 v104, 16, v156
	s_nop 0
	v_addc_co_u32_e32 v57, vcc, 0, v139, vcc
	v_cvt_pk_bf16_f32 v48, v48, v49
	v_cvt_pk_bf16_f32 v49, v50, v51
	v_cvt_pk_bf16_f32 v51, v42, v43
	v_cvt_pk_bf16_f32 v42, v44, v45
	v_add_co_u32_e32 v44, vcc, s42, v138
	v_ashrrev_i32_e32 v105, 31, v104
	v_cvt_pk_bf16_f32 v96, v96, v97
	v_cvt_pk_bf16_f32 v97, v98, v99
	v_cvt_pk_bf16_f32 v98, v88, v89
	v_or_b32_e32 v88, 32, v156
	v_addc_co_u32_e32 v45, vcc, 0, v139, vcc
	v_lshlrev_b64 v[104:105], 11, v[104:105]
	v_ashrrev_i32_e32 v89, 31, v88
	v_cvt_pk_bf16_f32 v80, v80, v81
	v_cvt_pk_bf16_f32 v81, v82, v83
	v_cvt_pk_bf16_f32 v82, v72, v73
	v_or_b32_e32 v72, 48, v156
	s_mov_b64 s[0:1], 0x40000
	v_cvt_pk_bf16_f32 v32, v32, v33
	v_cvt_pk_bf16_f32 v33, v34, v35
	v_cvt_pk_bf16_f32 v35, v26, v27
	v_cvt_pk_bf16_f32 v26, v28, v29
	v_add_co_u32_e32 v28, vcc, s43, v138
	v_lshl_add_u64 v[104:105], s[26:27], 0, v[104:105]
	v_lshlrev_b64 v[88:89], 11, v[88:89]
	v_ashrrev_i32_e32 v73, 31, v72
	v_cvt_pk_bf16_f32 v68, v68, v69
	v_cvt_pk_bf16_f32 v69, v70, v71
	v_cvt_pk_bf16_f32 v70, v64, v65
	v_lshl_add_u64 v[64:65], v[138:139], 0, s[0:1]
	s_mov_b64 s[0:1], 0x48000
	v_addc_co_u32_e32 v29, vcc, 0, v139, vcc
	v_cvt_pk_bf16_f32 v115, v106, v107
	flat_store_dwordx4 v[138:139], v[112:115] offset:256
	v_lshl_add_u64 v[88:89], s[26:27], 0, v[88:89]
	v_lshlrev_b64 v[72:73], 11, v[72:73]
	v_lshl_add_u64 v[112:113], v[104:105], 0, v[160:161]
	v_cvt_pk_bf16_f32 v50, v40, v41
	flat_store_dwordx4 v[64:65], v[48:51] offset:256
	v_cvt_pk_bf16_f32 v16, v16, v17
	v_cvt_pk_bf16_f32 v17, v18, v19
	v_cvt_pk_bf16_f32 v19, v10, v11
	v_cvt_pk_bf16_f32 v10, v12, v13
	v_add_co_u32_e32 v12, vcc, s47, v138
	s_nop 0
	v_lshl_add_u64 v[48:49], v[138:139], 0, s[0:1]
	s_mov_b64 s[0:1], 0x50000
	v_cvt_pk_bf16_f32 v99, v90, v91
	flat_store_dwordx4 v[112:113], v[96:99] offset:256
	v_lshl_add_u64 v[72:73], s[26:27], 0, v[72:73]
	v_cvt_pk_bf16_f32 v34, v24, v25
	flat_store_dwordx4 v[48:49], v[32:35] offset:256
	v_lshl_add_u64 v[96:97], v[88:89], 0, v[160:161]
	v_addc_co_u32_e32 v13, vcc, 0, v139, vcc
	v_lshl_add_u64 v[32:33], v[138:139], 0, s[0:1]
	s_mov_b64 s[0:1], 0x58000
	v_cvt_pk_bf16_f32 v83, v74, v75
	flat_store_dwordx4 v[96:97], v[80:83] offset:256
	v_cvt_pk_bf16_f32 v18, v8, v9
	flat_store_dwordx4 v[32:33], v[16:19] offset:256
	s_and_b64 vcc, exec, s[6:7]
	v_lshl_add_u64 v[80:81], v[72:73], 0, v[160:161]
	v_lshl_add_u64 v[16:17], v[138:139], 0, s[0:1]
	s_mov_b32 s21, s8
	s_mov_b32 s14, s4
	s_mov_b64 s[16:17], s[12:13]
	s_mov_b64 s[0:1], s[10:11]
	v_cvt_pk_bf16_f32 v124, v124, v125
	v_cvt_pk_bf16_f32 v125, v126, v127
	v_cvt_pk_bf16_f32 v126, v120, v121
	v_cvt_pk_bf16_f32 v127, v122, v123
	flat_store_dwordx4 v[138:139], v[124:127]
	v_cvt_pk_bf16_f32 v104, v116, v117
	v_cvt_pk_bf16_f32 v105, v118, v119
	v_cvt_pk_bf16_f32 v106, v108, v109
	v_cvt_pk_bf16_f32 v107, v110, v111
	flat_store_dwordx4 v[112:113], v[104:107]
	v_cvt_pk_bf16_f32 v88, v100, v101
	v_cvt_pk_bf16_f32 v89, v102, v103
	v_cvt_pk_bf16_f32 v90, v92, v93
	v_cvt_pk_bf16_f32 v91, v94, v95
	flat_store_dwordx4 v[96:97], v[88:91]
	v_cvt_pk_bf16_f32 v72, v84, v85
	v_cvt_pk_bf16_f32 v73, v86, v87
	v_cvt_pk_bf16_f32 v74, v76, v77
	v_cvt_pk_bf16_f32 v75, v78, v79
	flat_store_dwordx4 v[80:81], v[72:75]
	v_cvt_pk_bf16_f32 v71, v66, v67
	flat_store_dwordx4 v[80:81], v[68:71] offset:256
	v_cvt_pk_bf16_f32 v63, v58, v59
	flat_store_dwordx4 v[56:57], v[60:63]
	v_cvt_pk_bf16_f32 v40, v52, v53
	v_cvt_pk_bf16_f32 v41, v54, v55
	v_cvt_pk_bf16_f32 v43, v46, v47
	flat_store_dwordx4 v[44:45], v[40:43]
	v_cvt_pk_bf16_f32 v24, v36, v37
	v_cvt_pk_bf16_f32 v25, v38, v39
	v_cvt_pk_bf16_f32 v27, v30, v31
	flat_store_dwordx4 v[28:29], v[24:27]
	v_cvt_pk_bf16_f32 v8, v20, v21
	v_cvt_pk_bf16_f32 v9, v22, v23
	v_cvt_pk_bf16_f32 v11, v14, v15
	flat_store_dwordx4 v[12:13], v[8:11]
	v_cvt_pk_bf16_f32 v4, v4, v5
	v_cvt_pk_bf16_f32 v5, v6, v7
	v_cvt_pk_bf16_f32 v6, v0, v1
	v_cvt_pk_bf16_f32 v7, v2, v3
	flat_store_dwordx4 v[16:17], v[4:7] offset:256
	s_cbranch_vccz .LBB0_314
	s_waitcnt vmcnt(0)
	s_cmpk_gt_u32 s37, 0xff
	s_cbranch_scc1 .LBB0_325
	s_barrier

.LBB0_405:
	s_add_i32 s21, s0, 2
	s_add_u32 s1, vcc_lo, 0xfffe0080
	s_addc_u32 s2, vcc_hi, -1
	s_add_i32 s18, 0, 0x10000
	v_add_u32_e32 v164, s18, v178
	ds_read_b128 v[128:131], v164
	ds_read_b128 v[132:135], v164 offset:1024
	ds_read_b128 v[136:139], v164 offset:2048
	ds_read_b128 v[164:167], v164 offset:3072
	s_cmp_eq_u32 s5, s0
	s_cselect_b32 s0, s10, s17
	s_cselect_b32 s89, s9, s2
	s_cselect_b32 s88, s8, s1
	s_cselect_b32 s1, s11, s20
	v_lshl_add_u64 v[176:177], vcc, 0, v[162:163]
	s_add_i32 m0, s97, 0xc000
	ds_read_b128 v[168:171], v179
	ds_read_b128 v[172:175], v179 offset:1024
	ds_read_b128 v[180:183], v179 offset:2048
	ds_read_b128 v[184:187], v179 offset:3072
	ds_read_b128 v[188:191], v179 offset:4096
	ds_read_b128 v[192:195], v179 offset:5120
	ds_read_b128 v[196:199], v179 offset:6144
	ds_read_b128 v[200:203], v179 offset:7168
	global_load_lds_dwordx4 v[176:177], off
	v_lshl_add_u64 v[176:177], vcc, 0, v[160:161]
	s_add_i32 m0, s97, 0xe000
	s_nop 0
	global_load_lds_dwordx4 v[176:177], off
	s_waitcnt lgkmcnt(8)
	s_barrier
	s_waitcnt lgkmcnt(0)
	v_mfma_f32_16x16x32_bf16 v[120:123], v[128:131], v[168:171], v[120:123]
	v_mfma_f32_16x16x32_bf16 v[68:71], v[136:139], v[168:171], v[68:71]
	v_mfma_f32_16x16x32_bf16 v[116:119], v[128:131], v[180:183], v[116:119]
	v_mfma_f32_16x16x32_bf16 v[60:63], v[136:139], v[180:183], v[60:63]
	v_mfma_f32_16x16x32_bf16 v[108:111], v[128:131], v[188:191], v[108:111]
	v_mfma_f32_16x16x32_bf16 v[44:47], v[136:139], v[188:191], v[44:47]
	v_mfma_f32_16x16x32_bf16 v[100:103], v[128:131], v[196:199], v[100:103]
	v_mfma_f32_16x16x32_bf16 v[36:39], v[136:139], v[196:199], v[36:39]
	v_mfma_f32_16x16x32_bf16 v[120:123], v[132:135], v[172:175], v[120:123]
	v_mfma_f32_16x16x32_bf16 v[68:71], v[164:167], v[172:175], v[68:71]
	v_mfma_f32_16x16x32_bf16 v[116:119], v[132:135], v[184:187], v[116:119]
	v_mfma_f32_16x16x32_bf16 v[60:63], v[164:167], v[184:187], v[60:63]
	v_mfma_f32_16x16x32_bf16 v[108:111], v[132:135], v[192:195], v[108:111]
	v_mfma_f32_16x16x32_bf16 v[44:47], v[164:167], v[192:195], v[44:47]
	v_mfma_f32_16x16x32_bf16 v[100:103], v[132:135], v[200:203], v[100:103]
	v_mfma_f32_16x16x32_bf16 v[36:39], v[164:167], v[200:203], v[36:39]
	s_barrier
	s_add_i32 s2, 0, 0x14000
	v_add_u32_e32 v176, s2, v178
	s_add_i32 s18, s18, s59
	ds_read_b128 v[204:207], v176
	ds_read_b128 v[208:211], v176 offset:1024
	s_mov_b32 m0, s18
	ds_read_b128 v[228:231], v176 offset:2048
	global_load_lds_dwordx4 v140, s[0:1]
	s_add_i32 m0, s18, 0x2000
	ds_read_b128 v[232:235], v176 offset:3072
	global_load_lds_dwordx4 v158, s[0:1]
	s_barrier
	s_waitcnt lgkmcnt(0)
	v_mfma_f32_16x16x32_bf16 v[124:127], v[204:207], v[168:171], v[124:127]
	v_mfma_f32_16x16x32_bf16 v[64:67], v[228:231], v[168:171], v[64:67]
	v_mfma_f32_16x16x32_bf16 v[112:115], v[204:207], v[180:183], v[112:115]
	v_mfma_f32_16x16x32_bf16 v[56:59], v[228:231], v[180:183], v[56:59]
	v_mfma_f32_16x16x32_bf16 v[104:107], v[204:207], v[188:191], v[104:107]
	v_mfma_f32_16x16x32_bf16 v[40:43], v[228:231], v[188:191], v[40:43]
	v_mfma_f32_16x16x32_bf16 v[96:99], v[204:207], v[196:199], v[96:99]
	v_mfma_f32_16x16x32_bf16 v[32:35], v[228:231], v[196:199], v[32:35]
	v_mfma_f32_16x16x32_bf16 v[124:127], v[208:211], v[172:175], v[124:127]
	v_mfma_f32_16x16x32_bf16 v[64:67], v[232:235], v[172:175], v[64:67]
	v_mfma_f32_16x16x32_bf16 v[112:115], v[208:211], v[184:187], v[112:115]
	v_mfma_f32_16x16x32_bf16 v[56:59], v[232:235], v[184:187], v[56:59]
	v_mfma_f32_16x16x32_bf16 v[104:107], v[208:211], v[192:195], v[104:107]
	v_mfma_f32_16x16x32_bf16 v[40:43], v[232:235], v[192:195], v[40:43]
	v_mfma_f32_16x16x32_bf16 v[96:99], v[208:211], v[200:203], v[96:99]
	v_mfma_f32_16x16x32_bf16 v[32:35], v[232:235], v[200:203], v[32:35]
	s_mov_b32 m0, s97
	s_barrier
	ds_read_b128 v[168:171], v179 offset:16384
	ds_read_b128 v[172:175], v179 offset:17408
	ds_read_b128 v[180:183], v179 offset:18432
	ds_read_b128 v[184:187], v179 offset:19456
	ds_read_b128 v[188:191], v179 offset:20480
	ds_read_b128 v[192:195], v179 offset:21504
	ds_read_b128 v[196:199], v179 offset:22528
	global_load_lds_dwordx4 v154, s[88:89]
	s_mov_b32 m0, s74
	ds_read_b128 v[200:203], v179 offset:23552
	global_load_lds_dwordx4 v156, s[88:89]
	s_barrier
	s_waitcnt lgkmcnt(0)
	v_mfma_f32_16x16x32_bf16 v[92:95], v[128:131], v[168:171], v[92:95]
	v_mfma_f32_16x16x32_bf16 v[28:31], v[136:139], v[168:171], v[28:31]
	v_mfma_f32_16x16x32_bf16 v[84:87], v[128:131], v[180:183], v[84:87]
	v_mfma_f32_16x16x32_bf16 v[20:23], v[136:139], v[180:183], v[20:23]
	v_mfma_f32_16x16x32_bf16 v[76:79], v[128:131], v[188:191], v[76:79]
	v_mfma_f32_16x16x32_bf16 v[12:15], v[136:139], v[188:191], v[12:15]
	v_mfma_f32_16x16x32_bf16 v[52:55], v[128:131], v[196:199], v[52:55]
	v_mfma_f32_16x16x32_bf16 v[4:7], v[136:139], v[196:199], v[4:7]
	v_mfma_f32_16x16x32_bf16 v[92:95], v[132:135], v[172:175], v[92:95]
	v_mfma_f32_16x16x32_bf16 v[28:31], v[164:167], v[172:175], v[28:31]
	v_mfma_f32_16x16x32_bf16 v[84:87], v[132:135], v[184:187], v[84:87]
	v_mfma_f32_16x16x32_bf16 v[20:23], v[164:167], v[184:187], v[20:23]
	v_mfma_f32_16x16x32_bf16 v[76:79], v[132:135], v[192:195], v[76:79]
	v_mfma_f32_16x16x32_bf16 v[12:15], v[164:167], v[192:195], v[12:15]
	v_mfma_f32_16x16x32_bf16 v[52:55], v[132:135], v[200:203], v[52:55]
	v_mfma_f32_16x16x32_bf16 v[4:7], v[164:167], v[200:203], v[4:7]
	s_barrier
	s_add_i32 s2, s2, s59
	s_mov_b32 m0, s2
	s_add_u32 s18, s0, 0x10000
	s_addc_u32 s19, s1, 0
	global_load_lds_dwordx4 v140, s[18:19]
	s_add_i32 m0, s2, 0x2000
	s_nop 0
	global_load_lds_dwordx4 v158, s[18:19]
	s_waitcnt vmcnt(6)
	s_barrier
	v_mfma_f32_16x16x32_bf16 v[88:91], v[204:207], v[168:171], v[88:91]
	v_mfma_f32_16x16x32_bf16 v[24:27], v[228:231], v[168:171], v[24:27]
	v_mfma_f32_16x16x32_bf16 v[80:83], v[204:207], v[180:183], v[80:83]
	v_mfma_f32_16x16x32_bf16 v[16:19], v[228:231], v[180:183], v[16:19]
	v_mfma_f32_16x16x32_bf16 v[72:75], v[204:207], v[188:191], v[72:75]
	v_mfma_f32_16x16x32_bf16 v[8:11], v[228:231], v[188:191], v[8:11]
	v_mfma_f32_16x16x32_bf16 v[48:51], v[204:207], v[196:199], v[48:51]
	v_mfma_f32_16x16x32_bf16 v[0:3], v[228:231], v[196:199], v[0:3]
	v_mfma_f32_16x16x32_bf16 v[88:91], v[208:211], v[172:175], v[88:91]
	v_mfma_f32_16x16x32_bf16 v[24:27], v[232:235], v[172:175], v[24:27]
	v_mfma_f32_16x16x32_bf16 v[80:83], v[208:211], v[184:187], v[80:83]
	v_mfma_f32_16x16x32_bf16 v[16:19], v[232:235], v[184:187], v[16:19]
	v_mfma_f32_16x16x32_bf16 v[72:75], v[208:211], v[192:195], v[72:75]
	v_mfma_f32_16x16x32_bf16 v[8:11], v[232:235], v[192:195], v[8:11]
	v_mfma_f32_16x16x32_bf16 v[48:51], v[208:211], v[200:203], v[48:51]
	v_mfma_f32_16x16x32_bf16 v[0:3], v[232:235], v[200:203], v[0:3]
	s_add_i32 s2, 0, 0x18000
	v_add_u32_e32 v164, s2, v178
	s_barrier
	ds_read_b128 v[128:131], v164
	ds_read_b128 v[132:135], v164 offset:1024
	ds_read_b128 v[136:139], v164 offset:2048
	ds_read_b128 v[164:167], v164 offset:3072
	s_add_u32 s18, s88, 0x20000
	s_addc_u32 s19, s89, 0
	s_mov_b32 m0, s75
	ds_read_b128 v[168:171], v179 offset:32768
	ds_read_b128 v[172:175], v179 offset:33792
	ds_read_b128 v[180:183], v179 offset:34816
	ds_read_b128 v[184:187], v179 offset:35840
	ds_read_b128 v[188:191], v179 offset:36864
	ds_read_b128 v[192:195], v179 offset:37888
	ds_read_b128 v[196:199], v179 offset:38912
	global_load_lds_dwordx4 v154, s[18:19]
	s_mov_b32 m0, s72
	ds_read_b128 v[200:203], v179 offset:39936
	global_load_lds_dwordx4 v156, s[18:19]
	s_waitcnt lgkmcnt(8)
	s_barrier
	s_waitcnt lgkmcnt(0)
	v_mfma_f32_16x16x32_bf16 v[120:123], v[128:131], v[168:171], v[120:123]
	v_mfma_f32_16x16x32_bf16 v[68:71], v[136:139], v[168:171], v[68:71]
	v_mfma_f32_16x16x32_bf16 v[116:119], v[128:131], v[180:183], v[116:119]
	v_mfma_f32_16x16x32_bf16 v[60:63], v[136:139], v[180:183], v[60:63]
	v_mfma_f32_16x16x32_bf16 v[108:111], v[128:131], v[188:191], v[108:111]
	v_mfma_f32_16x16x32_bf16 v[44:47], v[136:139], v[188:191], v[44:47]
	v_mfma_f32_16x16x32_bf16 v[100:103], v[128:131], v[196:199], v[100:103]
	v_mfma_f32_16x16x32_bf16 v[36:39], v[136:139], v[196:199], v[36:39]
	v_mfma_f32_16x16x32_bf16 v[120:123], v[132:135], v[172:175], v[120:123]
	v_mfma_f32_16x16x32_bf16 v[68:71], v[164:167], v[172:175], v[68:71]
	v_mfma_f32_16x16x32_bf16 v[116:119], v[132:135], v[184:187], v[116:119]
	v_mfma_f32_16x16x32_bf16 v[60:63], v[164:167], v[184:187], v[60:63]
	v_mfma_f32_16x16x32_bf16 v[108:111], v[132:135], v[192:195], v[108:111]
	v_mfma_f32_16x16x32_bf16 v[44:47], v[164:167], v[192:195], v[44:47]
	v_mfma_f32_16x16x32_bf16 v[100:103], v[132:135], v[200:203], v[100:103]
	v_mfma_f32_16x16x32_bf16 v[36:39], v[164:167], v[200:203], v[36:39]
	s_barrier
	s_add_i32 s18, 0, 0x1c000
	s_add_i32 s2, s2, s59
	v_add_u32_e32 v232, s18, v178
	s_mov_b32 m0, s2
	ds_read_b128 v[204:207], v232
	ds_read_b128 v[208:211], v232 offset:1024
	ds_read_b128 v[228:231], v232 offset:2048
	ds_read_b128 v[232:235], v232 offset:3072
	s_add_u32 s100, s0, 0x80
	s_addc_u32 s101, s1, 0
	global_load_lds_dwordx4 v140, s[100:101]
	s_add_i32 m0, s2, 0x2000
	s_nop 0
	global_load_lds_dwordx4 v158, s[100:101]
	s_barrier
	s_waitcnt lgkmcnt(0)
	v_mfma_f32_16x16x32_bf16 v[124:127], v[204:207], v[168:171], v[124:127]
	v_mfma_f32_16x16x32_bf16 v[64:67], v[228:231], v[168:171], v[64:67]
	v_mfma_f32_16x16x32_bf16 v[112:115], v[204:207], v[180:183], v[112:115]
	v_mfma_f32_16x16x32_bf16 v[56:59], v[228:231], v[180:183], v[56:59]
	v_mfma_f32_16x16x32_bf16 v[104:107], v[204:207], v[188:191], v[104:107]
	v_mfma_f32_16x16x32_bf16 v[40:43], v[228:231], v[188:191], v[40:43]
	v_mfma_f32_16x16x32_bf16 v[96:99], v[204:207], v[196:199], v[96:99]
	v_mfma_f32_16x16x32_bf16 v[32:35], v[228:231], v[196:199], v[32:35]
	v_mfma_f32_16x16x32_bf16 v[124:127], v[208:211], v[172:175], v[124:127]
	v_mfma_f32_16x16x32_bf16 v[64:67], v[232:235], v[172:175], v[64:67]
	v_mfma_f32_16x16x32_bf16 v[112:115], v[208:211], v[184:187], v[112:115]
	v_mfma_f32_16x16x32_bf16 v[56:59], v[232:235], v[184:187], v[56:59]
	v_mfma_f32_16x16x32_bf16 v[104:107], v[208:211], v[192:195], v[104:107]
	v_mfma_f32_16x16x32_bf16 v[40:43], v[232:235], v[192:195], v[40:43]
	v_mfma_f32_16x16x32_bf16 v[96:99], v[208:211], v[200:203], v[96:99]
	v_mfma_f32_16x16x32_bf16 v[32:35], v[232:235], v[200:203], v[32:35]
	s_mov_b32 m0, s38
	s_barrier
	ds_read_b128 v[168:171], v179 offset:49152
	ds_read_b128 v[172:175], v179 offset:50176
	ds_read_b128 v[180:183], v179 offset:51200
	ds_read_b128 v[184:187], v179 offset:52224
	ds_read_b128 v[188:191], v179 offset:53248
	ds_read_b128 v[192:195], v179 offset:54272
	ds_read_b128 v[196:199], v179 offset:55296
	ds_read_b128 v[200:203], v179 offset:56320
	s_add_u32 s100, s88, 0x80
	s_addc_u32 s101, s89, 0
	global_load_lds_dwordx4 v154, s[100:101]
	s_mov_b32 m0, s39
	s_nop 0
	global_load_lds_dwordx4 v156, s[100:101]
	s_barrier
	s_waitcnt lgkmcnt(0)
	v_mfma_f32_16x16x32_bf16 v[92:95], v[128:131], v[168:171], v[92:95]
	v_mfma_f32_16x16x32_bf16 v[28:31], v[136:139], v[168:171], v[28:31]
	v_mfma_f32_16x16x32_bf16 v[84:87], v[128:131], v[180:183], v[84:87]
	v_mfma_f32_16x16x32_bf16 v[20:23], v[136:139], v[180:183], v[20:23]
	v_mfma_f32_16x16x32_bf16 v[76:79], v[128:131], v[188:191], v[76:79]
	v_mfma_f32_16x16x32_bf16 v[12:15], v[136:139], v[188:191], v[12:15]
	v_mfma_f32_16x16x32_bf16 v[52:55], v[128:131], v[196:199], v[52:55]
	v_mfma_f32_16x16x32_bf16 v[4:7], v[136:139], v[196:199], v[4:7]
	v_mfma_f32_16x16x32_bf16 v[92:95], v[132:135], v[172:175], v[92:95]
	v_mfma_f32_16x16x32_bf16 v[28:31], v[164:167], v[172:175], v[28:31]
	v_mfma_f32_16x16x32_bf16 v[84:87], v[132:135], v[184:187], v[84:87]
	v_mfma_f32_16x16x32_bf16 v[20:23], v[164:167], v[184:187], v[20:23]
	v_mfma_f32_16x16x32_bf16 v[76:79], v[132:135], v[192:195], v[76:79]
	v_mfma_f32_16x16x32_bf16 v[12:15], v[164:167], v[192:195], v[12:15]
	v_mfma_f32_16x16x32_bf16 v[52:55], v[132:135], v[200:203], v[52:55]
	v_mfma_f32_16x16x32_bf16 v[4:7], v[164:167], v[200:203], v[4:7]
	s_barrier
	s_add_i32 s2, s18, s59
	s_mov_b32 m0, s2
	s_add_u32 s0, s0, 0x10080
	s_addc_u32 s1, s1, 0
	global_load_lds_dwordx4 v140, s[0:1]
	s_add_i32 m0, s2, 0x2000
	s_nop 0
	global_load_lds_dwordx4 v158, s[0:1]
	s_waitcnt vmcnt(6)
	s_barrier
	v_mfma_f32_16x16x32_bf16 v[88:91], v[204:207], v[168:171], v[88:91]
	v_mfma_f32_16x16x32_bf16 v[24:27], v[228:231], v[168:171], v[24:27]
	v_mfma_f32_16x16x32_bf16 v[80:83], v[204:207], v[180:183], v[80:83]
	v_mfma_f32_16x16x32_bf16 v[16:19], v[228:231], v[180:183], v[16:19]
	v_mfma_f32_16x16x32_bf16 v[72:75], v[204:207], v[188:191], v[72:75]
	v_mfma_f32_16x16x32_bf16 v[8:11], v[228:231], v[188:191], v[8:11]
	v_mfma_f32_16x16x32_bf16 v[48:51], v[204:207], v[196:199], v[48:51]
	v_mfma_f32_16x16x32_bf16 v[0:3], v[228:231], v[196:199], v[0:3]
	v_mfma_f32_16x16x32_bf16 v[88:91], v[208:211], v[172:175], v[88:91]
	v_mfma_f32_16x16x32_bf16 v[24:27], v[232:235], v[172:175], v[24:27]
	v_mfma_f32_16x16x32_bf16 v[80:83], v[208:211], v[184:187], v[80:83]
	v_mfma_f32_16x16x32_bf16 v[16:19], v[232:235], v[184:187], v[16:19]
	v_mfma_f32_16x16x32_bf16 v[72:75], v[208:211], v[192:195], v[72:75]
	v_mfma_f32_16x16x32_bf16 v[8:11], v[232:235], v[192:195], v[8:11]
	v_mfma_f32_16x16x32_bf16 v[48:51], v[208:211], v[200:203], v[48:51]
	v_mfma_f32_16x16x32_bf16 v[0:3], v[232:235], v[200:203], v[0:3]
	s_add_u32 s17, s17, 0x100
	s_addc_u32 s20, s20, 0
	s_add_u32 vcc_lo, vcc_lo, 0x100
	s_addc_u32 vcc_hi, vcc_hi, 0
	s_cmp_ge_i32 s21, s36
	s_mov_b32 s0, s21
	s_barrier
	s_cbranch_scc0 .LBB0_405
	s_branch .LBB0_392

.LBB0_507:
	s_add_u32 s0, s8, 0xfffc0080
	s_addc_u32 s1, s9, -1
	s_add_i32 s2, 0, 0x10000
	v_add_u32_e32 v140, s2, v168
	ds_read_b128 v[154:157], v140
	ds_read_b128 v[158:161], v140 offset:1024
	ds_read_b128 v[162:165], v140 offset:2048
	ds_read_b128 v[170:173], v140 offset:3072
	s_cmp_eq_u32 s21, 12
	s_cselect_b32 s31, s29, s1
	s_cselect_b32 s30, s28, s0
	s_cselect_b32 s1, s11, s19
	s_cselect_b32 s0, s10, s17
	s_add_i32 m0, s36, 0xc000
	ds_read_b128 v[174:177], v169
	ds_read_b128 v[178:181], v169 offset:1024
	ds_read_b128 v[182:185], v169 offset:2048
	ds_read_b128 v[186:189], v169 offset:3072
	ds_read_b128 v[190:193], v169 offset:4096
	ds_read_b128 v[194:197], v169 offset:5120
	ds_read_b128 v[198:201], v169 offset:6144
	global_load_lds_dwordx4 v138, s[8:9]
	s_add_i32 m0, s36, 0xe000
	ds_read_b128 v[202:205], v169 offset:7168
	global_load_lds_dwordx4 v136, s[8:9]
	s_waitcnt lgkmcnt(8)
	s_barrier
	s_waitcnt lgkmcnt(0)
	v_mfma_f32_16x16x32_bf16 v[124:127], v[154:157], v[174:177], v[124:127]
	v_mfma_f32_16x16x32_bf16 v[120:123], v[162:165], v[174:177], v[120:123]
	v_mfma_f32_16x16x32_bf16 v[112:115], v[154:157], v[182:185], v[112:115]
	v_mfma_f32_16x16x32_bf16 v[104:107], v[162:165], v[182:185], v[104:107]
	v_mfma_f32_16x16x32_bf16 v[96:99], v[154:157], v[190:193], v[96:99]
	v_mfma_f32_16x16x32_bf16 v[88:91], v[162:165], v[190:193], v[88:91]
	v_mfma_f32_16x16x32_bf16 v[80:83], v[154:157], v[198:201], v[80:83]
	v_mfma_f32_16x16x32_bf16 v[72:75], v[162:165], v[198:201], v[72:75]
	v_mfma_f32_16x16x32_bf16 v[124:127], v[158:161], v[178:181], v[124:127]
	v_mfma_f32_16x16x32_bf16 v[120:123], v[170:173], v[178:181], v[120:123]
	v_mfma_f32_16x16x32_bf16 v[112:115], v[158:161], v[186:189], v[112:115]
	v_mfma_f32_16x16x32_bf16 v[104:107], v[170:173], v[186:189], v[104:107]
	v_mfma_f32_16x16x32_bf16 v[96:99], v[158:161], v[194:197], v[96:99]
	v_mfma_f32_16x16x32_bf16 v[88:91], v[170:173], v[194:197], v[88:91]
	v_mfma_f32_16x16x32_bf16 v[80:83], v[158:161], v[202:205], v[80:83]
	v_mfma_f32_16x16x32_bf16 v[72:75], v[170:173], v[202:205], v[72:75]
	s_barrier
	s_add_i32 s49, 0, 0x14000
	s_add_i32 s2, s2, s35
	v_add_u32_e32 v140, s49, v168
	s_mov_b32 m0, s2
	ds_read_b128 v[206:209], v140
	ds_read_b128 v[228:231], v140 offset:1024
	ds_read_b128 v[232:235], v140 offset:2048
	global_load_lds_dwordx4 v130, s[0:1]
	s_add_i32 m0, s2, 0x2000
	ds_read_b128 v[236:239], v140 offset:3072
	global_load_lds_dwordx4 v134, s[0:1]
	s_barrier
	s_waitcnt lgkmcnt(0)
	v_mfma_f32_16x16x32_bf16 v[116:119], v[206:209], v[174:177], v[116:119]
	v_mfma_f32_16x16x32_bf16 v[108:111], v[232:235], v[174:177], v[108:111]
	v_mfma_f32_16x16x32_bf16 v[100:103], v[206:209], v[182:185], v[100:103]
	v_mfma_f32_16x16x32_bf16 v[92:95], v[232:235], v[182:185], v[92:95]
	v_mfma_f32_16x16x32_bf16 v[84:87], v[206:209], v[190:193], v[84:87]
	v_mfma_f32_16x16x32_bf16 v[76:79], v[232:235], v[190:193], v[76:79]
	v_mfma_f32_16x16x32_bf16 v[68:71], v[206:209], v[198:201], v[68:71]
	v_mfma_f32_16x16x32_bf16 v[64:67], v[232:235], v[198:201], v[64:67]
	v_mfma_f32_16x16x32_bf16 v[116:119], v[228:231], v[178:181], v[116:119]
	v_mfma_f32_16x16x32_bf16 v[108:111], v[236:239], v[178:181], v[108:111]
	v_mfma_f32_16x16x32_bf16 v[100:103], v[228:231], v[186:189], v[100:103]
	v_mfma_f32_16x16x32_bf16 v[92:95], v[236:239], v[186:189], v[92:95]
	v_mfma_f32_16x16x32_bf16 v[84:87], v[228:231], v[194:197], v[84:87]
	v_mfma_f32_16x16x32_bf16 v[76:79], v[236:239], v[194:197], v[76:79]
	v_mfma_f32_16x16x32_bf16 v[68:71], v[228:231], v[202:205], v[68:71]
	v_mfma_f32_16x16x32_bf16 v[64:67], v[236:239], v[202:205], v[64:67]
	s_mov_b32 m0, s36
	v_lshl_add_u64 v[240:241], s[30:31], 0, v[128:129]
	s_barrier
	ds_read_b128 v[174:177], v169 offset:16384
	ds_read_b128 v[178:181], v169 offset:17408
	ds_read_b128 v[182:185], v169 offset:18432
	ds_read_b128 v[186:189], v169 offset:19456
	ds_read_b128 v[190:193], v169 offset:20480
	ds_read_b128 v[194:197], v169 offset:21504
	ds_read_b128 v[198:201], v169 offset:22528
	ds_read_b128 v[202:205], v169 offset:23552
	global_load_lds_dwordx4 v128, s[30:31]
	v_lshl_add_u64 v[242:243], s[30:31], 0, v[132:133]
	s_mov_b32 m0, s37
	s_nop 0
	global_load_lds_dwordx4 v132, s[30:31]
	s_barrier
	s_waitcnt lgkmcnt(0)
	v_mfma_f32_16x16x32_bf16 v[60:63], v[154:157], v[174:177], v[60:63]
	v_mfma_f32_16x16x32_bf16 v[56:59], v[162:165], v[174:177], v[56:59]
	v_mfma_f32_16x16x32_bf16 v[48:51], v[154:157], v[182:185], v[48:51]
	v_mfma_f32_16x16x32_bf16 v[40:43], v[162:165], v[182:185], v[40:43]
	v_mfma_f32_16x16x32_bf16 v[32:35], v[154:157], v[190:193], v[32:35]
	v_mfma_f32_16x16x32_bf16 v[24:27], v[162:165], v[190:193], v[24:27]
	v_mfma_f32_16x16x32_bf16 v[16:19], v[154:157], v[198:201], v[16:19]
	v_mfma_f32_16x16x32_bf16 v[8:11], v[162:165], v[198:201], v[8:11]
	v_mfma_f32_16x16x32_bf16 v[60:63], v[158:161], v[178:181], v[60:63]
	v_mfma_f32_16x16x32_bf16 v[56:59], v[170:173], v[178:181], v[56:59]
	v_mfma_f32_16x16x32_bf16 v[48:51], v[158:161], v[186:189], v[48:51]
	v_mfma_f32_16x16x32_bf16 v[40:43], v[170:173], v[186:189], v[40:43]
	v_mfma_f32_16x16x32_bf16 v[32:35], v[158:161], v[194:197], v[32:35]
	v_mfma_f32_16x16x32_bf16 v[24:27], v[170:173], v[194:197], v[24:27]
	v_mfma_f32_16x16x32_bf16 v[16:19], v[158:161], v[202:205], v[16:19]
	v_mfma_f32_16x16x32_bf16 v[8:11], v[170:173], v[202:205], v[8:11]
	s_barrier
	s_add_i32 s2, s49, s35
	s_mov_b32 m0, s2
	s_add_u32 s42, s0, 0x40000
	s_addc_u32 s43, s1, 0
	global_load_lds_dwordx4 v130, s[42:43]
	s_add_i32 m0, s2, 0x2000
	s_nop 0
	global_load_lds_dwordx4 v134, s[42:43]
	s_waitcnt vmcnt(6)
	s_barrier
	v_mfma_f32_16x16x32_bf16 v[52:55], v[206:209], v[174:177], v[52:55]
	v_mfma_f32_16x16x32_bf16 v[44:47], v[232:235], v[174:177], v[44:47]
	v_mfma_f32_16x16x32_bf16 v[36:39], v[206:209], v[182:185], v[36:39]
	v_mfma_f32_16x16x32_bf16 v[28:31], v[232:235], v[182:185], v[28:31]
	v_mfma_f32_16x16x32_bf16 v[20:23], v[206:209], v[190:193], v[20:23]
	v_mfma_f32_16x16x32_bf16 v[12:15], v[232:235], v[190:193], v[12:15]
	v_mfma_f32_16x16x32_bf16 v[4:7], v[206:209], v[198:201], v[4:7]
	v_mfma_f32_16x16x32_bf16 v[0:3], v[232:235], v[198:201], v[0:3]
	v_mfma_f32_16x16x32_bf16 v[52:55], v[228:231], v[178:181], v[52:55]
	v_mfma_f32_16x16x32_bf16 v[44:47], v[236:239], v[178:181], v[44:47]
	v_mfma_f32_16x16x32_bf16 v[36:39], v[228:231], v[186:189], v[36:39]
	v_mfma_f32_16x16x32_bf16 v[28:31], v[236:239], v[186:189], v[28:31]
	v_mfma_f32_16x16x32_bf16 v[20:23], v[228:231], v[194:197], v[20:23]
	v_mfma_f32_16x16x32_bf16 v[12:15], v[236:239], v[194:197], v[12:15]
	v_mfma_f32_16x16x32_bf16 v[4:7], v[228:231], v[202:205], v[4:7]
	v_mfma_f32_16x16x32_bf16 v[0:3], v[236:239], v[202:205], v[0:3]
	s_add_i32 s2, 0, 0x18000
	v_add_u32_e32 v140, s2, v168
	s_barrier
	ds_read_b128 v[154:157], v140
	ds_read_b128 v[158:161], v140 offset:1024
	ds_read_b128 v[162:165], v140 offset:2048
	ds_read_b128 v[170:173], v140 offset:3072
	s_add_u32 s30, s30, 0x40000
	s_addc_u32 s31, s31, 0
	s_mov_b32 m0, s38
	ds_read_b128 v[174:177], v169 offset:32768
	ds_read_b128 v[178:181], v169 offset:33792
	ds_read_b128 v[182:185], v169 offset:34816
	ds_read_b128 v[186:189], v169 offset:35840
	ds_read_b128 v[190:193], v169 offset:36864
	ds_read_b128 v[194:197], v169 offset:37888
	ds_read_b128 v[198:201], v169 offset:38912
	global_load_lds_dwordx4 v128, s[30:31]
	s_mov_b32 m0, s39
	ds_read_b128 v[202:205], v169 offset:39936
	global_load_lds_dwordx4 v132, s[30:31]
	s_waitcnt lgkmcnt(8)
	s_barrier
	s_waitcnt lgkmcnt(0)
	v_mfma_f32_16x16x32_bf16 v[124:127], v[154:157], v[174:177], v[124:127]
	v_mfma_f32_16x16x32_bf16 v[120:123], v[162:165], v[174:177], v[120:123]
	v_mfma_f32_16x16x32_bf16 v[112:115], v[154:157], v[182:185], v[112:115]
	v_mfma_f32_16x16x32_bf16 v[104:107], v[162:165], v[182:185], v[104:107]
	v_mfma_f32_16x16x32_bf16 v[96:99], v[154:157], v[190:193], v[96:99]
	v_mfma_f32_16x16x32_bf16 v[88:91], v[162:165], v[190:193], v[88:91]
	v_mfma_f32_16x16x32_bf16 v[80:83], v[154:157], v[198:201], v[80:83]
	v_mfma_f32_16x16x32_bf16 v[72:75], v[162:165], v[198:201], v[72:75]
	v_mfma_f32_16x16x32_bf16 v[124:127], v[158:161], v[178:181], v[124:127]
	v_mfma_f32_16x16x32_bf16 v[120:123], v[170:173], v[178:181], v[120:123]
	v_mfma_f32_16x16x32_bf16 v[112:115], v[158:161], v[186:189], v[112:115]
	v_mfma_f32_16x16x32_bf16 v[104:107], v[170:173], v[186:189], v[104:107]
	v_mfma_f32_16x16x32_bf16 v[96:99], v[158:161], v[194:197], v[96:99]
	v_mfma_f32_16x16x32_bf16 v[88:91], v[170:173], v[194:197], v[88:91]
	v_mfma_f32_16x16x32_bf16 v[80:83], v[158:161], v[202:205], v[80:83]
	v_mfma_f32_16x16x32_bf16 v[72:75], v[170:173], v[202:205], v[72:75]
	s_barrier
	s_add_i32 s30, 0, 0x1c000
	s_add_i32 s2, s2, s35
	v_add_u32_e32 v140, s30, v168
	s_mov_b32 m0, s2
	ds_read_b128 v[206:209], v140
	ds_read_b128 v[228:231], v140 offset:1024
	ds_read_b128 v[232:235], v140 offset:2048
	ds_read_b128 v[236:239], v140 offset:3072
	s_add_u32 s100, s0, 0x80
	s_addc_u32 s101, s1, 0
	global_load_lds_dwordx4 v130, s[100:101]
	s_add_i32 m0, s2, 0x2000
	s_nop 0
	global_load_lds_dwordx4 v134, s[100:101]
	s_barrier
	s_waitcnt lgkmcnt(0)
	v_mfma_f32_16x16x32_bf16 v[116:119], v[206:209], v[174:177], v[116:119]
	v_mfma_f32_16x16x32_bf16 v[108:111], v[232:235], v[174:177], v[108:111]
	v_mfma_f32_16x16x32_bf16 v[100:103], v[206:209], v[182:185], v[100:103]
	v_mfma_f32_16x16x32_bf16 v[92:95], v[232:235], v[182:185], v[92:95]
	v_mfma_f32_16x16x32_bf16 v[84:87], v[206:209], v[190:193], v[84:87]
	v_mfma_f32_16x16x32_bf16 v[76:79], v[232:235], v[190:193], v[76:79]
	v_mfma_f32_16x16x32_bf16 v[68:71], v[206:209], v[198:201], v[68:71]
	v_mfma_f32_16x16x32_bf16 v[64:67], v[232:235], v[198:201], v[64:67]
	v_mfma_f32_16x16x32_bf16 v[116:119], v[228:231], v[178:181], v[116:119]
	v_mfma_f32_16x16x32_bf16 v[108:111], v[236:239], v[178:181], v[108:111]
	v_mfma_f32_16x16x32_bf16 v[100:103], v[228:231], v[186:189], v[100:103]
	v_mfma_f32_16x16x32_bf16 v[92:95], v[236:239], v[186:189], v[92:95]
	v_mfma_f32_16x16x32_bf16 v[84:87], v[228:231], v[194:197], v[84:87]
	v_mfma_f32_16x16x32_bf16 v[76:79], v[236:239], v[194:197], v[76:79]
	v_mfma_f32_16x16x32_bf16 v[68:71], v[228:231], v[202:205], v[68:71]
	v_mfma_f32_16x16x32_bf16 v[64:67], v[236:239], v[202:205], v[64:67]
	s_mov_b32 m0, s44
	v_lshl_add_u64 v[166:167], v[240:241], 0, s[82:83]
	s_barrier
	ds_read_b128 v[174:177], v169 offset:49152
	ds_read_b128 v[178:181], v169 offset:50176
	ds_read_b128 v[182:185], v169 offset:51200
	ds_read_b128 v[186:189], v169 offset:52224
	ds_read_b128 v[190:193], v169 offset:53248
	ds_read_b128 v[194:197], v169 offset:54272
	ds_read_b128 v[198:201], v169 offset:55296
	ds_read_b128 v[202:205], v169 offset:56320
	global_load_lds_dwordx4 v[166:167], off
	v_lshl_add_u64 v[166:167], v[242:243], 0, s[82:83]
	s_mov_b32 m0, s45
	s_nop 0
	global_load_lds_dwordx4 v[166:167], off
	s_barrier
	s_waitcnt lgkmcnt(0)
	v_mfma_f32_16x16x32_bf16 v[60:63], v[154:157], v[174:177], v[60:63]
	v_mfma_f32_16x16x32_bf16 v[56:59], v[162:165], v[174:177], v[56:59]
	v_mfma_f32_16x16x32_bf16 v[48:51], v[154:157], v[182:185], v[48:51]
	v_mfma_f32_16x16x32_bf16 v[40:43], v[162:165], v[182:185], v[40:43]
	v_mfma_f32_16x16x32_bf16 v[32:35], v[154:157], v[190:193], v[32:35]
	v_mfma_f32_16x16x32_bf16 v[24:27], v[162:165], v[190:193], v[24:27]
	v_mfma_f32_16x16x32_bf16 v[16:19], v[154:157], v[198:201], v[16:19]
	v_mfma_f32_16x16x32_bf16 v[8:11], v[162:165], v[198:201], v[8:11]
	v_mfma_f32_16x16x32_bf16 v[60:63], v[158:161], v[178:181], v[60:63]
	v_mfma_f32_16x16x32_bf16 v[56:59], v[170:173], v[178:181], v[56:59]
	v_mfma_f32_16x16x32_bf16 v[48:51], v[158:161], v[186:189], v[48:51]
	v_mfma_f32_16x16x32_bf16 v[40:43], v[170:173], v[186:189], v[40:43]
	v_mfma_f32_16x16x32_bf16 v[32:35], v[158:161], v[194:197], v[32:35]
	v_mfma_f32_16x16x32_bf16 v[24:27], v[170:173], v[194:197], v[24:27]
	v_mfma_f32_16x16x32_bf16 v[16:19], v[158:161], v[202:205], v[16:19]
	v_mfma_f32_16x16x32_bf16 v[8:11], v[170:173], v[202:205], v[8:11]
	s_barrier
	s_add_i32 s2, s30, s35
	s_mov_b32 m0, s2
	s_add_u32 s0, s0, 0x40080
	s_addc_u32 s1, s1, 0
	global_load_lds_dwordx4 v130, s[0:1]
	s_add_i32 m0, s2, 0x2000
	s_nop 0
	global_load_lds_dwordx4 v134, s[0:1]
	s_waitcnt vmcnt(6)
	s_barrier
	v_mfma_f32_16x16x32_bf16 v[52:55], v[206:209], v[174:177], v[52:55]
	v_mfma_f32_16x16x32_bf16 v[44:47], v[232:235], v[174:177], v[44:47]
	v_mfma_f32_16x16x32_bf16 v[36:39], v[206:209], v[182:185], v[36:39]
	v_mfma_f32_16x16x32_bf16 v[28:31], v[232:235], v[182:185], v[28:31]
	v_mfma_f32_16x16x32_bf16 v[20:23], v[206:209], v[190:193], v[20:23]
	v_mfma_f32_16x16x32_bf16 v[12:15], v[232:235], v[190:193], v[12:15]
	v_mfma_f32_16x16x32_bf16 v[4:7], v[206:209], v[198:201], v[4:7]
	v_mfma_f32_16x16x32_bf16 v[0:3], v[232:235], v[198:201], v[0:3]
	v_mfma_f32_16x16x32_bf16 v[52:55], v[228:231], v[178:181], v[52:55]
	v_mfma_f32_16x16x32_bf16 v[44:47], v[236:239], v[178:181], v[44:47]
	v_mfma_f32_16x16x32_bf16 v[36:39], v[228:231], v[186:189], v[36:39]
	v_mfma_f32_16x16x32_bf16 v[28:31], v[236:239], v[186:189], v[28:31]
	v_mfma_f32_16x16x32_bf16 v[20:23], v[228:231], v[194:197], v[20:23]
	v_mfma_f32_16x16x32_bf16 v[12:15], v[236:239], v[194:197], v[12:15]
	v_mfma_f32_16x16x32_bf16 v[4:7], v[228:231], v[202:205], v[4:7]
	v_mfma_f32_16x16x32_bf16 v[0:3], v[236:239], v[202:205], v[0:3]
	s_add_i32 s21, s21, 2
	s_add_u32 s17, s17, 0x100
	s_addc_u32 s19, s19, 0
	s_add_u32 s8, s8, 0x100
	s_addc_u32 s9, s9, 0
	s_cmp_gt_u32 s21, 13
	s_barrier
	s_cbranch_scc0 .LBB0_507
	v_mbcnt_lo_u32_b32 v154, -1, 0
	v_mbcnt_hi_u32_b32 v154, -1, v154
	s_lshl_b32 s19, s16, 8
	v_and_b32_e32 v140, 15, v154
	v_ashrrev_i32_e32 v154, 1, v154
	s_cmp_lt_i32 s48, 8
	v_and_b32_e32 v170, -8, v154
	s_mov_b64 s[0:1], -1
	s_cbranch_scc0 .LBB0_552
	s_ashr_i32 s2, s48, 1
	s_mov_b32 s30, 0x3e38aa3b
	s_cmp_lt_u32 s48, 2
	s_mov_b64 s[8:9], s[24:25]
	s_cbranch_scc1 .LBB0_519
	s_cmp_lt_i32 s2, 2
	s_cbranch_scc1 .LBB0_514
	s_cmp_eq_u32 s2, 2
	s_cbranch_scc0 .LBB0_513
	s_mov_b64 s[0:1], 0
